# P1 layer 1: the 32 context K/V tiles (a sixth round at 12% occupancy) done as 256 32-row sub-tiles
# speedup vs baseline: 1.0083x; 1.0029x over previous
.Lp1_skew1:
	s_nop 7
	s_nop 1
	s_mov_b32 s4, s6
	s_mov_b32 s5, s28
	s_cmp_eq_u32 s5, 0
	s_cbranch_scc1 .Lp1_e_gelu
	s_cmp_eq_u32 s5, 1
	s_cbranch_scc1 .Lp1_e_norm
	s_cmp_lt_u32 s5, 5
	s_cbranch_scc1 .Lp1_e_plain
	s_cmp_lt_u32 s5, 7
	s_cbranch_scc1 .Lp1_e_gt
	s_cmp_lt_u32 s5, 9
	s_cbranch_scc1 .Lp1_e_rope
	v_and_b32_e32 v194, 15, v222
	v_bfe_u32 v195, v222, 4, 2
	v_bfe_u32 v196, v222, 6, 2
	v_lshrrev_b32_e32 v197, 8, v222
	v_lshl_or_b32 v198, v197, 7, v194
	v_lshlrev_b32_e32 v199, 2, v195
	v_lshl_or_b32 v199, v196, 6, v199
	s_lshr_b32 s2, s4, 3
	s_and_b32 s3, s4, 7
	s_lshl_b32 s3, s3, 9
	s_add_i32 s7, s4, 0xffffff80
	s_mul_i32 s2, s2, 0x120000
	s_add_i32 s2, s2, s3
	s_addk_i32 s2, 0x200
	s_mul_i32 s7, s7, 0x120000
	s_cmp_lt_u32 s4, 0x80
	s_cselect_b32 s2, s2, s7
	s_add_i32 s2, s2, 0x13aae500
	s_movk_i32 s7, 0x1200
	v_readlane_b32 s22, v254, 14
	v_readlane_b32 s23, v254, 15
	s_nop 3
	s_add_u32 s22, s22, s2
	s_addc_u32 s23, s23, 0
	v_and_b32_e32 v190, 63, v222
	v_lshrrev_b32_e32 v191, 3, v190
	v_and_b32_e32 v192, 7, v190
	v_lshl_or_b32 v193, v196, 6, v191
	v_mul_lo_u32 v193, v193, s7
	v_lshlrev_b32_e32 v189, 4, v192
	v_lshl_add_u32 v189, v197, 8, v189
	v_add_u32_e32 v193, v193, v189
	v_lshrrev_b32_e32 v188, 6, v222
	v_mul_u32_u24_e32 v188, 0x2400, v188
	v_add_u32_e32 v188, 0x10000, v188
	v_mul_u32_u24_e32 v189, 0x90, v191
	v_lshl_add_u32 v189, v192, 4, v189
	v_add_u32_e32 v189, v189, v188
	v_mul_u32_u24_e32 v187, 0x240, v195
	v_lshl_add_u32 v187, v194, 1, v187
	v_add_u32_e32 v187, v187, v188
	s_add_i32 s2, s53, s95
	s_cmp_lt_i32 s2, s58
	s_cselect_b32 s21, 1, 0
	s_cselect_b32 s53, s2, s53
	s_lshr_b32 s2, s53, 5
	s_mul_hi_u32 s2, s2, 0xcccccccd
	s_lshr_b32 s2, s2, 2
	s_lshl_b32 s3, s2, 4
	s_mul_i32 s2, s2, 0xa0
	s_sub_i32 s2, s53, s2
	s_lshr_b32 s2, s2, 4
	s_and_b32 s6, s53, 15
	s_add_i32 s3, s3, s6
	s_sub_i32 s28, s53, s58
	s_lshr_b32 s28, s28, 4
	s_add_i32 s28, s28, 8
	s_or_b32 s6, s6, 0x80
	s_cmp_ge_i32 s53, s58
	s_cselect_b32 s6, s6, s3
	s_cselect_b32 s28, s28, s2
	s_lshl_b32 s2, s6, 19
	s_add_u32 s12, s64, s2
	s_addc_u32 s13, s65, 0
	s_lshl_b32 s2, s28, 19
	s_add_u32 s14, s34, s2
	s_addc_u32 s15, s35, 0
	s_mov_b32 m0, s18
	s_nop 0
	global_load_lds_dwordx4 v1, s[12:13]
	s_add_i32 m0, s18, 0x2000
	s_add_u32 s16, s12, 0x20000
	s_addc_u32 s17, s13, 0
	global_load_lds_dwordx4 v1, s[16:17]
	s_add_i32 m0, s18, 0x4000
	s_add_u32 s16, s12, 0x40000
	s_addc_u32 s17, s13, 0
	global_load_lds_dwordx4 v1, s[16:17]
	s_add_i32 m0, s18, 0x6000
	s_add_u32 s16, s12, 0x60000
	s_addc_u32 s17, s13, 0
	global_load_lds_dwordx4 v1, s[16:17]
	s_add_i32 m0, s18, 0x8000
	s_nop 0
	global_load_lds_dwordx4 v1, s[14:15]
	s_add_i32 m0, s18, 0xa000
	s_add_u32 s16, s14, 0x20000
	s_addc_u32 s17, s15, 0
	global_load_lds_dwordx4 v1, s[16:17]
	s_add_i32 m0, s18, 0xc000
	s_add_u32 s16, s14, 0x40000
	s_addc_u32 s17, s15, 0
	global_load_lds_dwordx4 v1, s[16:17]
	s_add_i32 m0, s18, 0xe000
	s_add_u32 s16, s14, 0x60000
	s_addc_u32 s17, s15, 0
	global_load_lds_dwordx4 v1, s[16:17]
	s_lshl_b32 s3, s7, 3
	v_cvt_pk_f16_f32 v130, v126, v127
	ds_write_b16 v187, v130 offset:0
	ds_write_b16_d16_hi v187, v130 offset:144
	v_cvt_pk_f16_f32 v131, v128, v129
	ds_write_b16 v187, v131 offset:288
	ds_write_b16_d16_hi v187, v131 offset:432
	v_cvt_pk_f16_f32 v132, v122, v123
	ds_write_b16 v187, v132 offset:2304
	ds_write_b16_d16_hi v187, v132 offset:2448
	v_cvt_pk_f16_f32 v133, v124, v125
	ds_write_b16 v187, v133 offset:2592
	ds_write_b16_d16_hi v187, v133 offset:2736
	v_cvt_pk_f16_f32 v134, v118, v119
	ds_write_b16 v187, v134 offset:4608
	ds_write_b16_d16_hi v187, v134 offset:4752
	v_cvt_pk_f16_f32 v135, v120, v121
	ds_write_b16 v187, v135 offset:4896
	ds_write_b16_d16_hi v187, v135 offset:5040
	v_cvt_pk_f16_f32 v136, v114, v115
	ds_write_b16 v187, v136 offset:6912
	ds_write_b16_d16_hi v187, v136 offset:7056
	v_cvt_pk_f16_f32 v137, v116, v117
	ds_write_b16 v187, v137 offset:7200
	ds_write_b16_d16_hi v187, v137 offset:7344
	v_cvt_pk_f16_f32 v130, v110, v111
	ds_write_b16 v187, v130 offset:32
	ds_write_b16_d16_hi v187, v130 offset:176
	v_cvt_pk_f16_f32 v131, v112, v113
	ds_write_b16 v187, v131 offset:320
	ds_write_b16_d16_hi v187, v131 offset:464
	v_cvt_pk_f16_f32 v132, v106, v107
	ds_write_b16 v187, v132 offset:2336
	ds_write_b16_d16_hi v187, v132 offset:2480
	v_cvt_pk_f16_f32 v133, v108, v109
	ds_write_b16 v187, v133 offset:2624
	ds_write_b16_d16_hi v187, v133 offset:2768
	v_cvt_pk_f16_f32 v134, v102, v103
	ds_write_b16 v187, v134 offset:4640
	ds_write_b16_d16_hi v187, v134 offset:4784
	v_cvt_pk_f16_f32 v135, v104, v105
	ds_write_b16 v187, v135 offset:4928
	ds_write_b16_d16_hi v187, v135 offset:5072
	v_cvt_pk_f16_f32 v136, v98, v99
	ds_write_b16 v187, v136 offset:6944
	ds_write_b16_d16_hi v187, v136 offset:7088
	v_cvt_pk_f16_f32 v137, v100, v101
	ds_write_b16 v187, v137 offset:7232
	ds_write_b16_d16_hi v187, v137 offset:7376
	v_cvt_pk_f16_f32 v130, v94, v95
	ds_write_b16 v187, v130 offset:64
	ds_write_b16_d16_hi v187, v130 offset:208
	v_cvt_pk_f16_f32 v131, v96, v97
	ds_write_b16 v187, v131 offset:352
	ds_write_b16_d16_hi v187, v131 offset:496
	v_cvt_pk_f16_f32 v132, v90, v91
	ds_write_b16 v187, v132 offset:2368
	ds_write_b16_d16_hi v187, v132 offset:2512
	v_cvt_pk_f16_f32 v133, v92, v93
	ds_write_b16 v187, v133 offset:2656
	ds_write_b16_d16_hi v187, v133 offset:2800
	v_cvt_pk_f16_f32 v134, v86, v87
	ds_write_b16 v187, v134 offset:4672
	ds_write_b16_d16_hi v187, v134 offset:4816
	v_cvt_pk_f16_f32 v135, v88, v89
	ds_write_b16 v187, v135 offset:4960
	ds_write_b16_d16_hi v187, v135 offset:5104
	v_cvt_pk_f16_f32 v136, v82, v83
	ds_write_b16 v187, v136 offset:6976
	ds_write_b16_d16_hi v187, v136 offset:7120
	v_cvt_pk_f16_f32 v137, v84, v85
	ds_write_b16 v187, v137 offset:7264
	ds_write_b16_d16_hi v187, v137 offset:7408
	v_cvt_pk_f16_f32 v130, v78, v79
	ds_write_b16 v187, v130 offset:96
	ds_write_b16_d16_hi v187, v130 offset:240
	v_cvt_pk_f16_f32 v131, v80, v81
	ds_write_b16 v187, v131 offset:384
	ds_write_b16_d16_hi v187, v131 offset:528
	v_cvt_pk_f16_f32 v132, v74, v75
	ds_write_b16 v187, v132 offset:2400
	ds_write_b16_d16_hi v187, v132 offset:2544
	v_cvt_pk_f16_f32 v133, v76, v77
	ds_write_b16 v187, v133 offset:2688
	ds_write_b16_d16_hi v187, v133 offset:2832
	v_cvt_pk_f16_f32 v134, v70, v71
	ds_write_b16 v187, v134 offset:4704
	ds_write_b16_d16_hi v187, v134 offset:4848
	v_cvt_pk_f16_f32 v135, v72, v73
	ds_write_b16 v187, v135 offset:4992
	ds_write_b16_d16_hi v187, v135 offset:5136
	v_cvt_pk_f16_f32 v136, v66, v67
	ds_write_b16 v187, v136 offset:7008
	ds_write_b16_d16_hi v187, v136 offset:7152
	v_cvt_pk_f16_f32 v137, v68, v69
	ds_write_b16 v187, v137 offset:7296
	ds_write_b16_d16_hi v187, v137 offset:7440
	s_waitcnt lgkmcnt(0)
	ds_read_b128 v[152:155], v189 offset:0
	ds_read_b128 v[156:159], v189 offset:1152
	ds_read_b128 v[160:163], v189 offset:2304
	ds_read_b128 v[164:167], v189 offset:3456
	ds_read_b128 v[168:171], v189 offset:4608
	ds_read_b128 v[172:175], v189 offset:5760
	ds_read_b128 v[176:179], v189 offset:6912
	ds_read_b128 v[180:183], v189 offset:8064
	s_waitcnt lgkmcnt(7)
	global_store_dwordx4 v193, v[152:155], s[22:23]
	v_add_u32_e32 v193, s3, v193
	s_waitcnt lgkmcnt(6)
	global_store_dwordx4 v193, v[156:159], s[22:23]
	v_add_u32_e32 v193, s3, v193
	s_waitcnt lgkmcnt(5)
	global_store_dwordx4 v193, v[160:163], s[22:23]
	v_add_u32_e32 v193, s3, v193
	s_waitcnt lgkmcnt(4)
	global_store_dwordx4 v193, v[164:167], s[22:23]
	v_add_u32_e32 v193, s3, v193
	s_waitcnt lgkmcnt(3)
	global_store_dwordx4 v193, v[168:171], s[22:23]
	v_add_u32_e32 v193, s3, v193
	s_waitcnt lgkmcnt(2)
	global_store_dwordx4 v193, v[172:175], s[22:23]
	v_add_u32_e32 v193, s3, v193
	s_waitcnt lgkmcnt(1)
	global_store_dwordx4 v193, v[176:179], s[22:23]
	v_add_u32_e32 v193, s3, v193
	s_waitcnt lgkmcnt(0)
	global_store_dwordx4 v193, v[180:183], s[22:23]
	s_lshl_b32 s2, s3, 3
	s_sub_i32 s2, 0x80, s2
	s_add_i32 s2, s2, s3
	v_add_u32_e32 v193, s2, v193
	v_cvt_pk_f16_f32 v130, v62, v63
	ds_write_b16 v187, v130 offset:0
	ds_write_b16_d16_hi v187, v130 offset:144
	v_cvt_pk_f16_f32 v131, v64, v65
	ds_write_b16 v187, v131 offset:288
	ds_write_b16_d16_hi v187, v131 offset:432
	v_cvt_pk_f16_f32 v132, v58, v59
	ds_write_b16 v187, v132 offset:2304
	ds_write_b16_d16_hi v187, v132 offset:2448
	v_cvt_pk_f16_f32 v133, v60, v61
	ds_write_b16 v187, v133 offset:2592
	ds_write_b16_d16_hi v187, v133 offset:2736
	v_cvt_pk_f16_f32 v134, v54, v55
	ds_write_b16 v187, v134 offset:4608
	ds_write_b16_d16_hi v187, v134 offset:4752
	v_cvt_pk_f16_f32 v135, v56, v57
	ds_write_b16 v187, v135 offset:4896
	ds_write_b16_d16_hi v187, v135 offset:5040
	v_cvt_pk_f16_f32 v136, v50, v51
	ds_write_b16 v187, v136 offset:6912
	ds_write_b16_d16_hi v187, v136 offset:7056
	v_cvt_pk_f16_f32 v137, v52, v53
	ds_write_b16 v187, v137 offset:7200
	ds_write_b16_d16_hi v187, v137 offset:7344
	v_cvt_pk_f16_f32 v130, v46, v47
	ds_write_b16 v187, v130 offset:32
	ds_write_b16_d16_hi v187, v130 offset:176
	v_cvt_pk_f16_f32 v131, v48, v49
	ds_write_b16 v187, v131 offset:320
	ds_write_b16_d16_hi v187, v131 offset:464
	v_cvt_pk_f16_f32 v132, v42, v43
	ds_write_b16 v187, v132 offset:2336
	ds_write_b16_d16_hi v187, v132 offset:2480
	v_cvt_pk_f16_f32 v133, v44, v45
	ds_write_b16 v187, v133 offset:2624
	ds_write_b16_d16_hi v187, v133 offset:2768
	v_cvt_pk_f16_f32 v134, v38, v39
	ds_write_b16 v187, v134 offset:4640
	ds_write_b16_d16_hi v187, v134 offset:4784
	v_cvt_pk_f16_f32 v135, v40, v41
	ds_write_b16 v187, v135 offset:4928
	ds_write_b16_d16_hi v187, v135 offset:5072
	v_cvt_pk_f16_f32 v136, v34, v35
	ds_write_b16 v187, v136 offset:6944
	ds_write_b16_d16_hi v187, v136 offset:7088
	v_cvt_pk_f16_f32 v137, v36, v37
	ds_write_b16 v187, v137 offset:7232
	ds_write_b16_d16_hi v187, v137 offset:7376
	v_cvt_pk_f16_f32 v130, v30, v31
	ds_write_b16 v187, v130 offset:64
	ds_write_b16_d16_hi v187, v130 offset:208
	v_cvt_pk_f16_f32 v131, v32, v33
	ds_write_b16 v187, v131 offset:352
	ds_write_b16_d16_hi v187, v131 offset:496
	v_cvt_pk_f16_f32 v132, v26, v27
	ds_write_b16 v187, v132 offset:2368
	ds_write_b16_d16_hi v187, v132 offset:2512
	v_cvt_pk_f16_f32 v133, v28, v29
	ds_write_b16 v187, v133 offset:2656
	ds_write_b16_d16_hi v187, v133 offset:2800
	v_cvt_pk_f16_f32 v134, v22, v23
	ds_write_b16 v187, v134 offset:4672
	ds_write_b16_d16_hi v187, v134 offset:4816
	v_cvt_pk_f16_f32 v135, v24, v25
	ds_write_b16 v187, v135 offset:4960
	ds_write_b16_d16_hi v187, v135 offset:5104
	v_cvt_pk_f16_f32 v136, v18, v19
	ds_write_b16 v187, v136 offset:6976
	ds_write_b16_d16_hi v187, v136 offset:7120
	v_cvt_pk_f16_f32 v137, v20, v21
	ds_write_b16 v187, v137 offset:7264
	ds_write_b16_d16_hi v187, v137 offset:7408
	v_cvt_pk_f16_f32 v130, v14, v15
	ds_write_b16 v187, v130 offset:96
	ds_write_b16_d16_hi v187, v130 offset:240
	v_cvt_pk_f16_f32 v131, v16, v17
	ds_write_b16 v187, v131 offset:384
	ds_write_b16_d16_hi v187, v131 offset:528
	v_cvt_pk_f16_f32 v132, v10, v11
	ds_write_b16 v187, v132 offset:2400
	ds_write_b16_d16_hi v187, v132 offset:2544
	v_cvt_pk_f16_f32 v133, v12, v13
	ds_write_b16 v187, v133 offset:2688
	ds_write_b16_d16_hi v187, v133 offset:2832
	v_cvt_pk_f16_f32 v134, v6, v7
	ds_write_b16 v187, v134 offset:4704
	ds_write_b16_d16_hi v187, v134 offset:4848
	v_cvt_pk_f16_f32 v135, v8, v9
	ds_write_b16 v187, v135 offset:4992
	ds_write_b16_d16_hi v187, v135 offset:5136
	v_cvt_pk_f16_f32 v136, v2, v3
	ds_write_b16 v187, v136 offset:7008
	ds_write_b16_d16_hi v187, v136 offset:7152
	v_cvt_pk_f16_f32 v137, v4, v5
	ds_write_b16 v187, v137 offset:7296
	ds_write_b16_d16_hi v187, v137 offset:7440
	s_waitcnt lgkmcnt(0)
	ds_read_b128 v[152:155], v189 offset:0
	ds_read_b128 v[156:159], v189 offset:1152
	ds_read_b128 v[160:163], v189 offset:2304
	ds_read_b128 v[164:167], v189 offset:3456
	ds_read_b128 v[168:171], v189 offset:4608
	ds_read_b128 v[172:175], v189 offset:5760
	ds_read_b128 v[176:179], v189 offset:6912
	ds_read_b128 v[180:183], v189 offset:8064
	s_waitcnt lgkmcnt(7)
	global_store_dwordx4 v193, v[152:155], s[22:23]
	v_add_u32_e32 v193, s3, v193
	s_waitcnt lgkmcnt(6)
	global_store_dwordx4 v193, v[156:159], s[22:23]
	v_add_u32_e32 v193, s3, v193
	s_waitcnt lgkmcnt(5)
	global_store_dwordx4 v193, v[160:163], s[22:23]
	v_add_u32_e32 v193, s3, v193
	s_waitcnt lgkmcnt(4)
	global_store_dwordx4 v193, v[164:167], s[22:23]
	v_add_u32_e32 v193, s3, v193
	s_waitcnt lgkmcnt(3)
	global_store_dwordx4 v193, v[168:171], s[22:23]
	v_add_u32_e32 v193, s3, v193
	s_waitcnt lgkmcnt(2)
	global_store_dwordx4 v193, v[172:175], s[22:23]
	v_add_u32_e32 v193, s3, v193
	s_waitcnt lgkmcnt(1)
	global_store_dwordx4 v193, v[176:179], s[22:23]
	v_add_u32_e32 v193, s3, v193
	s_waitcnt lgkmcnt(0)
	global_store_dwordx4 v193, v[180:183], s[22:23]
	s_waitcnt vmcnt(16)
	s_branch .Lp1_join
.Lp1_e_gt:
	v_and_b32_e32 v194, 15, v222
	v_bfe_u32 v195, v222, 4, 2
	v_bfe_u32 v196, v222, 6, 2
	v_lshrrev_b32_e32 v197, 8, v222
	v_lshl_or_b32 v198, v197, 7, v194
	v_lshlrev_b32_e32 v199, 2, v195
	v_lshl_or_b32 v199, v196, 6, v199
	s_lshr_b32 s2, s4, 3
	s_and_b32 s3, s4, 7
	s_lshl_b32 s3, s3, 9
	s_add_i32 s7, s4, 0xffffff80
	s_lshl_b32 s2, s2, 21
	s_add_i32 s2, s2, s3
	s_add_i32 s2, s2, 0xf2ae500
	s_lshl_b32 s7, s7, 18
	s_add_i32 s7, s7, 0x112ae500
	s_cmp_eq_u32 s5, 6
	s_cselect_b32 s3, 0x1000, 0
	s_add_i32 s2, s2, s3
	s_lshr_b32 s3, s3, 3
	s_add_i32 s7, s7, s3
	s_cmp_lt_u32 s4, 0x80
	s_cselect_b32 s2, s2, s7
	s_movk_i32 s7, 0x400
	s_cselect_b32 s7, 0x2000, s7
	v_readlane_b32 s22, v254, 14
	v_readlane_b32 s23, v254, 15
	s_nop 3
	s_add_u32 s22, s22, s2
	s_addc_u32 s23, s23, 0
	v_and_b32_e32 v190, 63, v222
	v_lshrrev_b32_e32 v191, 3, v190
	v_and_b32_e32 v192, 7, v190
	v_lshl_or_b32 v193, v196, 6, v191
	v_mul_lo_u32 v193, v193, s7
	v_lshlrev_b32_e32 v189, 4, v192
	v_lshl_add_u32 v189, v197, 8, v189
	v_add_u32_e32 v193, v193, v189
	v_lshrrev_b32_e32 v188, 6, v222
	v_mul_u32_u24_e32 v188, 0x2400, v188
	v_add_u32_e32 v188, 0x10000, v188
	v_mul_u32_u24_e32 v189, 0x90, v191
	v_lshl_add_u32 v189, v192, 4, v189
	v_add_u32_e32 v189, v189, v188
	v_mul_u32_u24_e32 v187, 0x240, v195
	v_lshl_add_u32 v187, v194, 1, v187
	v_add_u32_e32 v187, v187, v188
	s_add_i32 s2, s53, s95
	s_cmp_lt_i32 s2, s58
	s_cselect_b32 s21, 1, 0
	s_cselect_b32 s53, s2, s53
	s_lshr_b32 s2, s53, 5
	s_mul_hi_u32 s2, s2, 0xcccccccd
	s_lshr_b32 s2, s2, 2
	s_lshl_b32 s3, s2, 4
	s_mul_i32 s2, s2, 0xa0
	s_sub_i32 s2, s53, s2
	s_lshr_b32 s2, s2, 4
	s_and_b32 s6, s53, 15
	s_add_i32 s3, s3, s6
	s_sub_i32 s28, s53, s58
	s_lshr_b32 s28, s28, 4
	s_add_i32 s28, s28, 8
	s_or_b32 s6, s6, 0x80
	s_cmp_ge_i32 s53, s58
	s_cselect_b32 s6, s6, s3
	s_cselect_b32 s28, s28, s2
	s_lshl_b32 s2, s6, 19
	s_add_u32 s12, s64, s2
	s_addc_u32 s13, s65, 0
	s_lshl_b32 s2, s28, 19
	s_add_u32 s14, s34, s2
	s_addc_u32 s15, s35, 0
	s_mov_b32 m0, s18
	s_nop 0
	global_load_lds_dwordx4 v1, s[12:13]
	s_add_i32 m0, s18, 0x2000
	s_add_u32 s16, s12, 0x20000
	s_addc_u32 s17, s13, 0
	global_load_lds_dwordx4 v1, s[16:17]
	s_add_i32 m0, s18, 0x4000
	s_add_u32 s16, s12, 0x40000
	s_addc_u32 s17, s13, 0
	global_load_lds_dwordx4 v1, s[16:17]
	s_add_i32 m0, s18, 0x6000
	s_add_u32 s16, s12, 0x60000
	s_addc_u32 s17, s13, 0
	global_load_lds_dwordx4 v1, s[16:17]
	s_add_i32 m0, s18, 0x8000
	s_nop 0
	global_load_lds_dwordx4 v1, s[14:15]
	s_add_i32 m0, s18, 0xa000
	s_add_u32 s16, s14, 0x20000
	s_addc_u32 s17, s15, 0
	global_load_lds_dwordx4 v1, s[16:17]
	s_add_i32 m0, s18, 0xc000
	s_add_u32 s16, s14, 0x40000
	s_addc_u32 s17, s15, 0
	global_load_lds_dwordx4 v1, s[16:17]
	s_add_i32 m0, s18, 0xe000
	s_add_u32 s16, s14, 0x60000
	s_addc_u32 s17, s15, 0
	global_load_lds_dwordx4 v1, s[16:17]
	s_lshl_b32 s3, s7, 3
	v_cvt_pk_f16_f32 v130, v126, v127
	ds_write_b16 v187, v130 offset:0
	ds_write_b16_d16_hi v187, v130 offset:144
	v_cvt_pk_f16_f32 v131, v128, v129
	ds_write_b16 v187, v131 offset:288
	ds_write_b16_d16_hi v187, v131 offset:432
	v_cvt_pk_f16_f32 v132, v122, v123
	ds_write_b16 v187, v132 offset:2304
	ds_write_b16_d16_hi v187, v132 offset:2448
	v_cvt_pk_f16_f32 v133, v124, v125
	ds_write_b16 v187, v133 offset:2592
	ds_write_b16_d16_hi v187, v133 offset:2736
	v_cvt_pk_f16_f32 v134, v118, v119
	ds_write_b16 v187, v134 offset:4608
	ds_write_b16_d16_hi v187, v134 offset:4752
	v_cvt_pk_f16_f32 v135, v120, v121
	ds_write_b16 v187, v135 offset:4896
	ds_write_b16_d16_hi v187, v135 offset:5040
	v_cvt_pk_f16_f32 v136, v114, v115
	ds_write_b16 v187, v136 offset:6912
	ds_write_b16_d16_hi v187, v136 offset:7056
	v_cvt_pk_f16_f32 v137, v116, v117
	ds_write_b16 v187, v137 offset:7200
	ds_write_b16_d16_hi v187, v137 offset:7344
	v_cvt_pk_f16_f32 v130, v110, v111
	ds_write_b16 v187, v130 offset:32
	ds_write_b16_d16_hi v187, v130 offset:176
	v_cvt_pk_f16_f32 v131, v112, v113
	ds_write_b16 v187, v131 offset:320
	ds_write_b16_d16_hi v187, v131 offset:464
	v_cvt_pk_f16_f32 v132, v106, v107
	ds_write_b16 v187, v132 offset:2336
	ds_write_b16_d16_hi v187, v132 offset:2480
	v_cvt_pk_f16_f32 v133, v108, v109
	ds_write_b16 v187, v133 offset:2624
	ds_write_b16_d16_hi v187, v133 offset:2768
	v_cvt_pk_f16_f32 v134, v102, v103
	ds_write_b16 v187, v134 offset:4640
	ds_write_b16_d16_hi v187, v134 offset:4784
	v_cvt_pk_f16_f32 v135, v104, v105
	ds_write_b16 v187, v135 offset:4928
	ds_write_b16_d16_hi v187, v135 offset:5072
	v_cvt_pk_f16_f32 v136, v98, v99
	ds_write_b16 v187, v136 offset:6944
	ds_write_b16_d16_hi v187, v136 offset:7088
	v_cvt_pk_f16_f32 v137, v100, v101
	ds_write_b16 v187, v137 offset:7232
	ds_write_b16_d16_hi v187, v137 offset:7376
	v_cvt_pk_f16_f32 v130, v94, v95
	ds_write_b16 v187, v130 offset:64
	ds_write_b16_d16_hi v187, v130 offset:208
	v_cvt_pk_f16_f32 v131, v96, v97
	ds_write_b16 v187, v131 offset:352
	ds_write_b16_d16_hi v187, v131 offset:496
	v_cvt_pk_f16_f32 v132, v90, v91
	ds_write_b16 v187, v132 offset:2368
	ds_write_b16_d16_hi v187, v132 offset:2512
	v_cvt_pk_f16_f32 v133, v92, v93
	ds_write_b16 v187, v133 offset:2656
	ds_write_b16_d16_hi v187, v133 offset:2800
	v_cvt_pk_f16_f32 v134, v86, v87
	ds_write_b16 v187, v134 offset:4672
	ds_write_b16_d16_hi v187, v134 offset:4816
	v_cvt_pk_f16_f32 v135, v88, v89
	ds_write_b16 v187, v135 offset:4960
	ds_write_b16_d16_hi v187, v135 offset:5104
	v_cvt_pk_f16_f32 v136, v82, v83
	ds_write_b16 v187, v136 offset:6976
	ds_write_b16_d16_hi v187, v136 offset:7120
	v_cvt_pk_f16_f32 v137, v84, v85
	ds_write_b16 v187, v137 offset:7264
	ds_write_b16_d16_hi v187, v137 offset:7408
	v_cvt_pk_f16_f32 v130, v78, v79
	ds_write_b16 v187, v130 offset:96
	ds_write_b16_d16_hi v187, v130 offset:240
	v_cvt_pk_f16_f32 v131, v80, v81
	ds_write_b16 v187, v131 offset:384
	ds_write_b16_d16_hi v187, v131 offset:528
	v_cvt_pk_f16_f32 v132, v74, v75
	ds_write_b16 v187, v132 offset:2400
	ds_write_b16_d16_hi v187, v132 offset:2544
	v_cvt_pk_f16_f32 v133, v76, v77
	ds_write_b16 v187, v133 offset:2688
	ds_write_b16_d16_hi v187, v133 offset:2832
	v_cvt_pk_f16_f32 v134, v70, v71
	ds_write_b16 v187, v134 offset:4704
	ds_write_b16_d16_hi v187, v134 offset:4848
	v_cvt_pk_f16_f32 v135, v72, v73
	ds_write_b16 v187, v135 offset:4992
	ds_write_b16_d16_hi v187, v135 offset:5136
	v_cvt_pk_f16_f32 v136, v66, v67
	ds_write_b16 v187, v136 offset:7008
	ds_write_b16_d16_hi v187, v136 offset:7152
	v_cvt_pk_f16_f32 v137, v68, v69
	ds_write_b16 v187, v137 offset:7296
	ds_write_b16_d16_hi v187, v137 offset:7440
	s_waitcnt lgkmcnt(0)
	ds_read_b128 v[152:155], v189 offset:0
	ds_read_b128 v[156:159], v189 offset:1152
	ds_read_b128 v[160:163], v189 offset:2304
	ds_read_b128 v[164:167], v189 offset:3456
	ds_read_b128 v[168:171], v189 offset:4608
	ds_read_b128 v[172:175], v189 offset:5760
	ds_read_b128 v[176:179], v189 offset:6912
	ds_read_b128 v[180:183], v189 offset:8064
	s_waitcnt lgkmcnt(7)
	global_store_dwordx4 v193, v[152:155], s[22:23]
	v_add_u32_e32 v193, s3, v193
	s_waitcnt lgkmcnt(6)
	global_store_dwordx4 v193, v[156:159], s[22:23]
	v_add_u32_e32 v193, s3, v193
	s_waitcnt lgkmcnt(5)
	global_store_dwordx4 v193, v[160:163], s[22:23]
	v_add_u32_e32 v193, s3, v193
	s_waitcnt lgkmcnt(4)
	global_store_dwordx4 v193, v[164:167], s[22:23]
	v_add_u32_e32 v193, s3, v193
	s_waitcnt lgkmcnt(3)
	global_store_dwordx4 v193, v[168:171], s[22:23]
	v_add_u32_e32 v193, s3, v193
	s_waitcnt lgkmcnt(2)
	global_store_dwordx4 v193, v[172:175], s[22:23]
	v_add_u32_e32 v193, s3, v193
	s_waitcnt lgkmcnt(1)
	global_store_dwordx4 v193, v[176:179], s[22:23]
	v_add_u32_e32 v193, s3, v193
	s_waitcnt lgkmcnt(0)
	global_store_dwordx4 v193, v[180:183], s[22:23]
	s_lshl_b32 s2, s3, 3
	s_sub_i32 s2, 0x80, s2
	s_add_i32 s2, s2, s3
	v_add_u32_e32 v193, s2, v193
	v_cvt_pk_f16_f32 v130, v62, v63
	ds_write_b16 v187, v130 offset:0
	ds_write_b16_d16_hi v187, v130 offset:144
	v_cvt_pk_f16_f32 v131, v64, v65
	ds_write_b16 v187, v131 offset:288
	ds_write_b16_d16_hi v187, v131 offset:432
	v_cvt_pk_f16_f32 v132, v58, v59
	ds_write_b16 v187, v132 offset:2304
	ds_write_b16_d16_hi v187, v132 offset:2448
	v_cvt_pk_f16_f32 v133, v60, v61
	ds_write_b16 v187, v133 offset:2592
	ds_write_b16_d16_hi v187, v133 offset:2736
	v_cvt_pk_f16_f32 v134, v54, v55
	ds_write_b16 v187, v134 offset:4608
	ds_write_b16_d16_hi v187, v134 offset:4752
	v_cvt_pk_f16_f32 v135, v56, v57
	ds_write_b16 v187, v135 offset:4896
	ds_write_b16_d16_hi v187, v135 offset:5040
	v_cvt_pk_f16_f32 v136, v50, v51
	ds_write_b16 v187, v136 offset:6912
	ds_write_b16_d16_hi v187, v136 offset:7056
	v_cvt_pk_f16_f32 v137, v52, v53
	ds_write_b16 v187, v137 offset:7200
	ds_write_b16_d16_hi v187, v137 offset:7344
	v_cvt_pk_f16_f32 v130, v46, v47
	ds_write_b16 v187, v130 offset:32
	ds_write_b16_d16_hi v187, v130 offset:176
	v_cvt_pk_f16_f32 v131, v48, v49
	ds_write_b16 v187, v131 offset:320
	ds_write_b16_d16_hi v187, v131 offset:464
	v_cvt_pk_f16_f32 v132, v42, v43
	ds_write_b16 v187, v132 offset:2336
	ds_write_b16_d16_hi v187, v132 offset:2480
	v_cvt_pk_f16_f32 v133, v44, v45
	ds_write_b16 v187, v133 offset:2624
	ds_write_b16_d16_hi v187, v133 offset:2768
	v_cvt_pk_f16_f32 v134, v38, v39
	ds_write_b16 v187, v134 offset:4640
	ds_write_b16_d16_hi v187, v134 offset:4784
	v_cvt_pk_f16_f32 v135, v40, v41
	ds_write_b16 v187, v135 offset:4928
	ds_write_b16_d16_hi v187, v135 offset:5072
	v_cvt_pk_f16_f32 v136, v34, v35
	ds_write_b16 v187, v136 offset:6944
	ds_write_b16_d16_hi v187, v136 offset:7088
	v_cvt_pk_f16_f32 v137, v36, v37
	ds_write_b16 v187, v137 offset:7232
	ds_write_b16_d16_hi v187, v137 offset:7376
	v_cvt_pk_f16_f32 v130, v30, v31
	ds_write_b16 v187, v130 offset:64
	ds_write_b16_d16_hi v187, v130 offset:208
	v_cvt_pk_f16_f32 v131, v32, v33
	ds_write_b16 v187, v131 offset:352
	ds_write_b16_d16_hi v187, v131 offset:496
	v_cvt_pk_f16_f32 v132, v26, v27
	ds_write_b16 v187, v132 offset:2368
	ds_write_b16_d16_hi v187, v132 offset:2512
	v_cvt_pk_f16_f32 v133, v28, v29
	ds_write_b16 v187, v133 offset:2656
	ds_write_b16_d16_hi v187, v133 offset:2800
	v_cvt_pk_f16_f32 v134, v22, v23
	ds_write_b16 v187, v134 offset:4672
	ds_write_b16_d16_hi v187, v134 offset:4816
	v_cvt_pk_f16_f32 v135, v24, v25
	ds_write_b16 v187, v135 offset:4960
	ds_write_b16_d16_hi v187, v135 offset:5104
	v_cvt_pk_f16_f32 v136, v18, v19
	ds_write_b16 v187, v136 offset:6976
	ds_write_b16_d16_hi v187, v136 offset:7120
	v_cvt_pk_f16_f32 v137, v20, v21
	ds_write_b16 v187, v137 offset:7264
	ds_write_b16_d16_hi v187, v137 offset:7408
	v_cvt_pk_f16_f32 v130, v14, v15
	ds_write_b16 v187, v130 offset:96
	ds_write_b16_d16_hi v187, v130 offset:240
	v_cvt_pk_f16_f32 v131, v16, v17
	ds_write_b16 v187, v131 offset:384
	ds_write_b16_d16_hi v187, v131 offset:528
	v_cvt_pk_f16_f32 v132, v10, v11
	ds_write_b16 v187, v132 offset:2400
	ds_write_b16_d16_hi v187, v132 offset:2544
	v_cvt_pk_f16_f32 v133, v12, v13
	ds_write_b16 v187, v133 offset:2688
	ds_write_b16_d16_hi v187, v133 offset:2832
	v_cvt_pk_f16_f32 v134, v6, v7
	ds_write_b16 v187, v134 offset:4704
	ds_write_b16_d16_hi v187, v134 offset:4848
	v_cvt_pk_f16_f32 v135, v8, v9
	ds_write_b16 v187, v135 offset:4992
	ds_write_b16_d16_hi v187, v135 offset:5136
	v_cvt_pk_f16_f32 v136, v2, v3
	ds_write_b16 v187, v136 offset:7008
	ds_write_b16_d16_hi v187, v136 offset:7152
	v_cvt_pk_f16_f32 v137, v4, v5
	ds_write_b16 v187, v137 offset:7296
	ds_write_b16_d16_hi v187, v137 offset:7440
	s_waitcnt lgkmcnt(0)
	ds_read_b128 v[152:155], v189 offset:0
	ds_read_b128 v[156:159], v189 offset:1152
	ds_read_b128 v[160:163], v189 offset:2304
	ds_read_b128 v[164:167], v189 offset:3456
	ds_read_b128 v[168:171], v189 offset:4608
	ds_read_b128 v[172:175], v189 offset:5760
	ds_read_b128 v[176:179], v189 offset:6912
	ds_read_b128 v[180:183], v189 offset:8064
	s_waitcnt lgkmcnt(7)
	global_store_dwordx4 v193, v[152:155], s[22:23]
	v_add_u32_e32 v193, s3, v193
	s_waitcnt lgkmcnt(6)
	global_store_dwordx4 v193, v[156:159], s[22:23]
	v_add_u32_e32 v193, s3, v193
	s_waitcnt lgkmcnt(5)
	global_store_dwordx4 v193, v[160:163], s[22:23]
	v_add_u32_e32 v193, s3, v193
	s_waitcnt lgkmcnt(4)
	global_store_dwordx4 v193, v[164:167], s[22:23]
	v_add_u32_e32 v193, s3, v193
	s_waitcnt lgkmcnt(3)
	global_store_dwordx4 v193, v[168:171], s[22:23]
	v_add_u32_e32 v193, s3, v193
	s_waitcnt lgkmcnt(2)
	global_store_dwordx4 v193, v[172:175], s[22:23]
	v_add_u32_e32 v193, s3, v193
	s_waitcnt lgkmcnt(1)
	global_store_dwordx4 v193, v[176:179], s[22:23]
	v_add_u32_e32 v193, s3, v193
	s_waitcnt lgkmcnt(0)
	global_store_dwordx4 v193, v[180:183], s[22:23]
	s_waitcnt vmcnt(16)
	s_branch .Lp1_join
.Lp1_e_norm:
	v_and_b32_e32 v194, 15, v222
	v_bfe_u32 v195, v222, 4, 2
	v_bfe_u32 v196, v222, 6, 2
	v_lshrrev_b32_e32 v197, 8, v222
	v_lshl_or_b32 v198, v197, 7, v194
	v_lshlrev_b32_e32 v199, 2, v195
	v_lshl_or_b32 v199, v196, 6, v199
	s_lshr_b32 s2, s4, 3
	s_and_b32 s3, s4, 7
	s_lshl_b32 s3, s3, 9
	s_add_i32 s7, s4, 0xffffff80
	s_lshl_b32 s2, s2, 18
	s_add_i32 s2, s2, s3
	s_add_i32 s2, s2, 0xaaae500
	s_lshl_b32 s7, s7, 15
	s_add_i32 s7, s7, 0xbaae500
	s_cmp_lt_u32 s4, 0x80
	s_cselect_b32 s2, s2, s7
	s_movk_i32 s7, 0x200
	s_cselect_b32 s7, 0x1000, s7
	v_readlane_b32 s22, v254, 14
	v_readlane_b32 s23, v254, 15
	s_nop 3
	s_add_u32 s22, s22, s2
	s_addc_u32 s23, s23, 0
	v_and_b32_e32 v190, 63, v222
	v_lshrrev_b32_e32 v191, 3, v190
	v_and_b32_e32 v192, 7, v190
	v_lshl_or_b32 v193, v196, 10, v191
	v_mul_lo_u32 v193, v193, s7
	v_lshlrev_b32_e32 v189, 4, v192
	v_lshl_add_u32 v189, v197, 8, v189
	v_add_u32_e32 v193, v193, v189
	v_lshrrev_b32_e32 v188, 6, v222
	v_mul_u32_u24_e32 v188, 0x2400, v188
	v_add_u32_e32 v188, 0x10000, v188
	v_mul_u32_u24_e32 v189, 0x90, v191
	v_lshl_add_u32 v189, v192, 4, v189
	v_add_u32_e32 v189, v189, v188
	v_mul_u32_u24_e32 v187, 0x240, v195
	v_lshl_add_u32 v187, v194, 1, v187
	v_add_u32_e32 v187, v187, v188
	v_xor_b32_e32 v186, 16, v190
	v_lshlrev_b32_e32 v186, 2, v186
	v_xor_b32_e32 v185, 32, v190
	v_lshlrev_b32_e32 v185, 2, v185
	s_add_i32 s2, s53, s95
	s_cmp_lt_i32 s2, s58
	s_cselect_b32 s21, 1, 0
	s_cselect_b32 s53, s2, s53
	s_lshr_b32 s2, s53, 5
	s_mul_hi_u32 s2, s2, 0xcccccccd
	s_lshr_b32 s2, s2, 2
	s_lshl_b32 s3, s2, 4
	s_mul_i32 s2, s2, 0xa0
	s_sub_i32 s2, s53, s2
	s_lshr_b32 s2, s2, 4
	s_and_b32 s6, s53, 15
	s_add_i32 s3, s3, s6
	s_sub_i32 s28, s53, s58
	s_lshr_b32 s28, s28, 4
	s_add_i32 s28, s28, 8
	s_or_b32 s6, s6, 0x80
	s_cmp_ge_i32 s53, s58
	s_cselect_b32 s6, s6, s3
	s_cselect_b32 s28, s28, s2
	s_lshl_b32 s2, s6, 19
	s_add_u32 s12, s64, s2
	s_addc_u32 s13, s65, 0
	s_lshl_b32 s2, s28, 19
	s_add_u32 s14, s34, s2
	s_addc_u32 s15, s35, 0
	s_mov_b32 m0, s18
	s_nop 0
	global_load_lds_dwordx4 v1, s[12:13]
	s_add_i32 m0, s18, 0x2000
	s_add_u32 s16, s12, 0x20000
	s_addc_u32 s17, s13, 0
	global_load_lds_dwordx4 v1, s[16:17]
	s_add_i32 m0, s18, 0x4000
	s_add_u32 s16, s12, 0x40000
	s_addc_u32 s17, s13, 0
	global_load_lds_dwordx4 v1, s[16:17]
	s_add_i32 m0, s18, 0x6000
	s_add_u32 s16, s12, 0x60000
	s_addc_u32 s17, s13, 0
	global_load_lds_dwordx4 v1, s[16:17]
	s_add_i32 m0, s18, 0x8000
	s_nop 0
	global_load_lds_dwordx4 v1, s[14:15]
	s_add_i32 m0, s18, 0xa000
	s_add_u32 s16, s14, 0x20000
	s_addc_u32 s17, s15, 0
	global_load_lds_dwordx4 v1, s[16:17]
	s_add_i32 m0, s18, 0xc000
	s_add_u32 s16, s14, 0x40000
	s_addc_u32 s17, s15, 0
	global_load_lds_dwordx4 v1, s[16:17]
	s_add_i32 m0, s18, 0xe000
	s_add_u32 s16, s14, 0x60000
	s_addc_u32 s17, s15, 0
	global_load_lds_dwordx4 v1, s[16:17]
	s_lshl_b32 s3, s7, 3
	v_mul_f32_e32 v130, 0x3d372713, v126
	v_mul_f32_e32 v131, 0x3d372713, v127
	v_mul_f32_e32 v132, 0x3d372713, v128
	v_mul_f32_e32 v133, 0x3d372713, v129
	v_mul_f32_e32 v130, v126, v130
	v_mul_f32_e32 v131, v127, v131
	v_mul_f32_e32 v132, v128, v132
	v_mul_f32_e32 v133, v129, v133
	v_fma_f32 v130, v126, v130, v126
	v_fma_f32 v131, v127, v131, v127
	v_fma_f32 v132, v128, v132, v128
	v_fma_f32 v133, v129, v133, v129
	v_mul_f32_e32 v130, 0x3f4c422a, v130
	v_mul_f32_e32 v131, 0x3f4c422a, v131
	v_mul_f32_e32 v132, 0x3f4c422a, v132
	v_mul_f32_e32 v133, 0x3f4c422a, v133
	v_mul_f32_e32 v130, -2.0, v130
	v_mul_f32_e32 v131, -2.0, v131
	v_mul_f32_e32 v132, -2.0, v132
	v_mul_f32_e32 v133, -2.0, v133
	v_mul_f32_e32 v130, 0x3fb8aa3b, v130
	v_mul_f32_e32 v131, 0x3fb8aa3b, v131
	v_mul_f32_e32 v132, 0x3fb8aa3b, v132
	v_mul_f32_e32 v133, 0x3fb8aa3b, v133
	v_exp_f32_e32 v130, v130
	v_exp_f32_e32 v131, v131
	v_exp_f32_e32 v132, v132
	v_exp_f32_e32 v133, v133
	v_add_f32_e32 v130, 1.0, v130
	v_add_f32_e32 v131, 1.0, v131
	v_add_f32_e32 v132, 1.0, v132
	v_add_f32_e32 v133, 1.0, v133
	v_rcp_f32_e32 v130, v130
	v_rcp_f32_e32 v131, v131
	v_rcp_f32_e32 v132, v132
	v_rcp_f32_e32 v133, v133
	s_nop 0
	v_mul_f32_e32 v126, v126, v130
	v_mul_f32_e32 v127, v127, v131
	v_mul_f32_e32 v128, v128, v132
	v_mul_f32_e32 v129, v129, v133
	v_mul_f32_e32 v134, 0x3d372713, v122
	v_mul_f32_e32 v135, 0x3d372713, v123
	v_mul_f32_e32 v136, 0x3d372713, v124
	v_mul_f32_e32 v137, 0x3d372713, v125
	v_mul_f32_e32 v134, v122, v134
	v_mul_f32_e32 v135, v123, v135
	v_mul_f32_e32 v136, v124, v136
	v_mul_f32_e32 v137, v125, v137
	v_fma_f32 v134, v122, v134, v122
	v_fma_f32 v135, v123, v135, v123
	v_fma_f32 v136, v124, v136, v124
	v_fma_f32 v137, v125, v137, v125
	v_mul_f32_e32 v134, 0x3f4c422a, v134
	v_mul_f32_e32 v135, 0x3f4c422a, v135
	v_mul_f32_e32 v136, 0x3f4c422a, v136
	v_mul_f32_e32 v137, 0x3f4c422a, v137
	v_mul_f32_e32 v134, -2.0, v134
	v_mul_f32_e32 v135, -2.0, v135
	v_mul_f32_e32 v136, -2.0, v136
	v_mul_f32_e32 v137, -2.0, v137
	v_mul_f32_e32 v134, 0x3fb8aa3b, v134
	v_mul_f32_e32 v135, 0x3fb8aa3b, v135
	v_mul_f32_e32 v136, 0x3fb8aa3b, v136
	v_mul_f32_e32 v137, 0x3fb8aa3b, v137
	v_exp_f32_e32 v134, v134
	v_exp_f32_e32 v135, v135
	v_exp_f32_e32 v136, v136
	v_exp_f32_e32 v137, v137
	v_add_f32_e32 v134, 1.0, v134
	v_add_f32_e32 v135, 1.0, v135
	v_add_f32_e32 v136, 1.0, v136
	v_add_f32_e32 v137, 1.0, v137
	v_rcp_f32_e32 v134, v134
	v_rcp_f32_e32 v135, v135
	v_rcp_f32_e32 v136, v136
	v_rcp_f32_e32 v137, v137
	s_nop 0
	v_mul_f32_e32 v122, v122, v134
	v_mul_f32_e32 v123, v123, v135
	v_mul_f32_e32 v124, v124, v136
	v_mul_f32_e32 v125, v125, v137
	v_mul_f32_e32 v130, 0x3d372713, v118
	v_mul_f32_e32 v131, 0x3d372713, v119
	v_mul_f32_e32 v132, 0x3d372713, v120
	v_mul_f32_e32 v133, 0x3d372713, v121
	v_mul_f32_e32 v130, v118, v130
	v_mul_f32_e32 v131, v119, v131
	v_mul_f32_e32 v132, v120, v132
	v_mul_f32_e32 v133, v121, v133
	v_fma_f32 v130, v118, v130, v118
	v_fma_f32 v131, v119, v131, v119
	v_fma_f32 v132, v120, v132, v120
	v_fma_f32 v133, v121, v133, v121
	v_mul_f32_e32 v130, 0x3f4c422a, v130
	v_mul_f32_e32 v131, 0x3f4c422a, v131
	v_mul_f32_e32 v132, 0x3f4c422a, v132
	v_mul_f32_e32 v133, 0x3f4c422a, v133
	v_mul_f32_e32 v130, -2.0, v130
	v_mul_f32_e32 v131, -2.0, v131
	v_mul_f32_e32 v132, -2.0, v132
	v_mul_f32_e32 v133, -2.0, v133
	v_mul_f32_e32 v130, 0x3fb8aa3b, v130
	v_mul_f32_e32 v131, 0x3fb8aa3b, v131
	v_mul_f32_e32 v132, 0x3fb8aa3b, v132
	v_mul_f32_e32 v133, 0x3fb8aa3b, v133
	v_exp_f32_e32 v130, v130
	v_exp_f32_e32 v131, v131
	v_exp_f32_e32 v132, v132
	v_exp_f32_e32 v133, v133
	v_add_f32_e32 v130, 1.0, v130
	v_add_f32_e32 v131, 1.0, v131
	v_add_f32_e32 v132, 1.0, v132
	v_add_f32_e32 v133, 1.0, v133
	v_rcp_f32_e32 v130, v130
	v_rcp_f32_e32 v131, v131
	v_rcp_f32_e32 v132, v132
	v_rcp_f32_e32 v133, v133
	s_nop 0
	v_mul_f32_e32 v118, v118, v130
	v_mul_f32_e32 v119, v119, v131
	v_mul_f32_e32 v120, v120, v132
	v_mul_f32_e32 v121, v121, v133
	v_mul_f32_e32 v134, 0x3d372713, v114
	v_mul_f32_e32 v135, 0x3d372713, v115
	v_mul_f32_e32 v136, 0x3d372713, v116
	v_mul_f32_e32 v137, 0x3d372713, v117
	v_mul_f32_e32 v134, v114, v134
	v_mul_f32_e32 v135, v115, v135
	v_mul_f32_e32 v136, v116, v136
	v_mul_f32_e32 v137, v117, v137
	v_fma_f32 v134, v114, v134, v114
	v_fma_f32 v135, v115, v135, v115
	v_fma_f32 v136, v116, v136, v116
	v_fma_f32 v137, v117, v137, v117
	v_mul_f32_e32 v134, 0x3f4c422a, v134
	v_mul_f32_e32 v135, 0x3f4c422a, v135
	v_mul_f32_e32 v136, 0x3f4c422a, v136
	v_mul_f32_e32 v137, 0x3f4c422a, v137
	v_mul_f32_e32 v134, -2.0, v134
	v_mul_f32_e32 v135, -2.0, v135
	v_mul_f32_e32 v136, -2.0, v136
	v_mul_f32_e32 v137, -2.0, v137
	v_mul_f32_e32 v134, 0x3fb8aa3b, v134
	v_mul_f32_e32 v135, 0x3fb8aa3b, v135
	v_mul_f32_e32 v136, 0x3fb8aa3b, v136
	v_mul_f32_e32 v137, 0x3fb8aa3b, v137
	v_exp_f32_e32 v134, v134
	v_exp_f32_e32 v135, v135
	v_exp_f32_e32 v136, v136
	v_exp_f32_e32 v137, v137
	v_add_f32_e32 v134, 1.0, v134
	v_add_f32_e32 v135, 1.0, v135
	v_add_f32_e32 v136, 1.0, v136
	v_add_f32_e32 v137, 1.0, v137
	v_rcp_f32_e32 v134, v134
	v_rcp_f32_e32 v135, v135
	v_rcp_f32_e32 v136, v136
	v_rcp_f32_e32 v137, v137
	s_nop 0
	v_mul_f32_e32 v114, v114, v134
	v_mul_f32_e32 v115, v115, v135
	v_mul_f32_e32 v116, v116, v136
	v_mul_f32_e32 v117, v117, v137
	v_pk_mul_f32 v[136:137], v[126:127], v[126:127]
	v_pk_mul_f32 v[138:139], v[128:129], v[128:129]
	v_add_f32_e32 v140, 0, v136
	v_add_f32_e32 v140, v137, v140
	v_add_f32_e32 v140, v138, v140
	v_add_f32_e32 v140, v139, v140
	v_pk_mul_f32 v[136:137], v[122:123], v[122:123]
	v_pk_mul_f32 v[138:139], v[124:125], v[124:125]
	v_add_f32_e32 v140, v136, v140
	v_add_f32_e32 v140, v137, v140
	v_add_f32_e32 v140, v138, v140
	v_add_f32_e32 v140, v139, v140
	v_pk_mul_f32 v[136:137], v[118:119], v[118:119]
	v_pk_mul_f32 v[138:139], v[120:121], v[120:121]
	v_add_f32_e32 v140, v136, v140
	v_add_f32_e32 v140, v137, v140
	v_add_f32_e32 v140, v138, v140
	v_add_f32_e32 v140, v139, v140
	v_pk_mul_f32 v[136:137], v[114:115], v[114:115]
	v_pk_mul_f32 v[138:139], v[116:117], v[116:117]
	v_add_f32_e32 v140, v136, v140
	v_add_f32_e32 v140, v137, v140
	v_add_f32_e32 v140, v138, v140
	v_add_f32_e32 v140, v139, v140
	ds_bpermute_b32 v141, v186, v140
	s_waitcnt lgkmcnt(0)
	v_add_f32_e32 v140, v140, v141
	ds_bpermute_b32 v141, v185, v140
	s_waitcnt lgkmcnt(0)
	v_add_f32_e32 v140, v140, v141
	v_mov_b32_e32 v141, 0x358637bd
	v_fmamk_f32 v140, v140, 0x3c800000, v141
	v_mul_f32_e32 v141, 0x4b800000, v140
	v_cmp_gt_f32_e32 vcc, 0x800000, v140
	s_nop 1
	v_cndmask_b32_e32 v140, v140, v141, vcc
	v_rsq_f32_e32 v140, v140
	s_nop 0
	v_mul_f32_e32 v141, 0x45800000, v140
	v_cndmask_b32_e32 v144, v140, v141, vcc
	v_mul_f32_e32 v130, 0x3d372713, v110
	v_mul_f32_e32 v131, 0x3d372713, v111
	v_mul_f32_e32 v132, 0x3d372713, v112
	v_mul_f32_e32 v133, 0x3d372713, v113
	v_mul_f32_e32 v130, v110, v130
	v_mul_f32_e32 v131, v111, v131
	v_mul_f32_e32 v132, v112, v132
	v_mul_f32_e32 v133, v113, v133
	v_fma_f32 v130, v110, v130, v110
	v_fma_f32 v131, v111, v131, v111
	v_fma_f32 v132, v112, v132, v112
	v_fma_f32 v133, v113, v133, v113
	v_mul_f32_e32 v130, 0x3f4c422a, v130
	v_mul_f32_e32 v131, 0x3f4c422a, v131
	v_mul_f32_e32 v132, 0x3f4c422a, v132
	v_mul_f32_e32 v133, 0x3f4c422a, v133
	v_mul_f32_e32 v130, -2.0, v130
	v_mul_f32_e32 v131, -2.0, v131
	v_mul_f32_e32 v132, -2.0, v132
	v_mul_f32_e32 v133, -2.0, v133
	v_mul_f32_e32 v130, 0x3fb8aa3b, v130
	v_mul_f32_e32 v131, 0x3fb8aa3b, v131
	v_mul_f32_e32 v132, 0x3fb8aa3b, v132
	v_mul_f32_e32 v133, 0x3fb8aa3b, v133
	v_exp_f32_e32 v130, v130
	v_exp_f32_e32 v131, v131
	v_exp_f32_e32 v132, v132
	v_exp_f32_e32 v133, v133
	v_add_f32_e32 v130, 1.0, v130
	v_add_f32_e32 v131, 1.0, v131
	v_add_f32_e32 v132, 1.0, v132
	v_add_f32_e32 v133, 1.0, v133
	v_rcp_f32_e32 v130, v130
	v_rcp_f32_e32 v131, v131
	v_rcp_f32_e32 v132, v132
	v_rcp_f32_e32 v133, v133
	s_nop 0
	v_mul_f32_e32 v110, v110, v130
	v_mul_f32_e32 v111, v111, v131
	v_mul_f32_e32 v112, v112, v132
	v_mul_f32_e32 v113, v113, v133
	v_mul_f32_e32 v134, 0x3d372713, v106
	v_mul_f32_e32 v135, 0x3d372713, v107
	v_mul_f32_e32 v136, 0x3d372713, v108
	v_mul_f32_e32 v137, 0x3d372713, v109
	v_mul_f32_e32 v134, v106, v134
	v_mul_f32_e32 v135, v107, v135
	v_mul_f32_e32 v136, v108, v136
	v_mul_f32_e32 v137, v109, v137
	v_fma_f32 v134, v106, v134, v106
	v_fma_f32 v135, v107, v135, v107
	v_fma_f32 v136, v108, v136, v108
	v_fma_f32 v137, v109, v137, v109
	v_mul_f32_e32 v134, 0x3f4c422a, v134
	v_mul_f32_e32 v135, 0x3f4c422a, v135
	v_mul_f32_e32 v136, 0x3f4c422a, v136
	v_mul_f32_e32 v137, 0x3f4c422a, v137
	v_mul_f32_e32 v134, -2.0, v134
	v_mul_f32_e32 v135, -2.0, v135
	v_mul_f32_e32 v136, -2.0, v136
	v_mul_f32_e32 v137, -2.0, v137
	v_mul_f32_e32 v134, 0x3fb8aa3b, v134
	v_mul_f32_e32 v135, 0x3fb8aa3b, v135
	v_mul_f32_e32 v136, 0x3fb8aa3b, v136
	v_mul_f32_e32 v137, 0x3fb8aa3b, v137
	v_exp_f32_e32 v134, v134
	v_exp_f32_e32 v135, v135
	v_exp_f32_e32 v136, v136
	v_exp_f32_e32 v137, v137
	v_add_f32_e32 v134, 1.0, v134
	v_add_f32_e32 v135, 1.0, v135
	v_add_f32_e32 v136, 1.0, v136
	v_add_f32_e32 v137, 1.0, v137
	v_rcp_f32_e32 v134, v134
	v_rcp_f32_e32 v135, v135
	v_rcp_f32_e32 v136, v136
	v_rcp_f32_e32 v137, v137
	s_nop 0
	v_mul_f32_e32 v106, v106, v134
	v_mul_f32_e32 v107, v107, v135
	v_mul_f32_e32 v108, v108, v136
	v_mul_f32_e32 v109, v109, v137
	v_mul_f32_e32 v130, 0x3d372713, v102
	v_mul_f32_e32 v131, 0x3d372713, v103
	v_mul_f32_e32 v132, 0x3d372713, v104
	v_mul_f32_e32 v133, 0x3d372713, v105
	v_mul_f32_e32 v130, v102, v130
	v_mul_f32_e32 v131, v103, v131
	v_mul_f32_e32 v132, v104, v132
	v_mul_f32_e32 v133, v105, v133
	v_fma_f32 v130, v102, v130, v102
	v_fma_f32 v131, v103, v131, v103
	v_fma_f32 v132, v104, v132, v104
	v_fma_f32 v133, v105, v133, v105
	v_mul_f32_e32 v130, 0x3f4c422a, v130
	v_mul_f32_e32 v131, 0x3f4c422a, v131
	v_mul_f32_e32 v132, 0x3f4c422a, v132
	v_mul_f32_e32 v133, 0x3f4c422a, v133
	v_mul_f32_e32 v130, -2.0, v130
	v_mul_f32_e32 v131, -2.0, v131
	v_mul_f32_e32 v132, -2.0, v132
	v_mul_f32_e32 v133, -2.0, v133
	v_mul_f32_e32 v130, 0x3fb8aa3b, v130
	v_mul_f32_e32 v131, 0x3fb8aa3b, v131
	v_mul_f32_e32 v132, 0x3fb8aa3b, v132
	v_mul_f32_e32 v133, 0x3fb8aa3b, v133
	v_exp_f32_e32 v130, v130
	v_exp_f32_e32 v131, v131
	v_exp_f32_e32 v132, v132
	v_exp_f32_e32 v133, v133
	v_add_f32_e32 v130, 1.0, v130
	v_add_f32_e32 v131, 1.0, v131
	v_add_f32_e32 v132, 1.0, v132
	v_add_f32_e32 v133, 1.0, v133
	v_rcp_f32_e32 v130, v130
	v_rcp_f32_e32 v131, v131
	v_rcp_f32_e32 v132, v132
	v_rcp_f32_e32 v133, v133
	s_nop 0
	v_mul_f32_e32 v102, v102, v130
	v_mul_f32_e32 v103, v103, v131
	v_mul_f32_e32 v104, v104, v132
	v_mul_f32_e32 v105, v105, v133
	v_mul_f32_e32 v134, 0x3d372713, v98
	v_mul_f32_e32 v135, 0x3d372713, v99
	v_mul_f32_e32 v136, 0x3d372713, v100
	v_mul_f32_e32 v137, 0x3d372713, v101
	v_mul_f32_e32 v134, v98, v134
	v_mul_f32_e32 v135, v99, v135
	v_mul_f32_e32 v136, v100, v136
	v_mul_f32_e32 v137, v101, v137
	v_fma_f32 v134, v98, v134, v98
	v_fma_f32 v135, v99, v135, v99
	v_fma_f32 v136, v100, v136, v100
	v_fma_f32 v137, v101, v137, v101
	v_mul_f32_e32 v134, 0x3f4c422a, v134
	v_mul_f32_e32 v135, 0x3f4c422a, v135
	v_mul_f32_e32 v136, 0x3f4c422a, v136
	v_mul_f32_e32 v137, 0x3f4c422a, v137
	v_mul_f32_e32 v134, -2.0, v134
	v_mul_f32_e32 v135, -2.0, v135
	v_mul_f32_e32 v136, -2.0, v136
	v_mul_f32_e32 v137, -2.0, v137
	v_mul_f32_e32 v134, 0x3fb8aa3b, v134
	v_mul_f32_e32 v135, 0x3fb8aa3b, v135
	v_mul_f32_e32 v136, 0x3fb8aa3b, v136
	v_mul_f32_e32 v137, 0x3fb8aa3b, v137
	v_exp_f32_e32 v134, v134
	v_exp_f32_e32 v135, v135
	v_exp_f32_e32 v136, v136
	v_exp_f32_e32 v137, v137
	v_add_f32_e32 v134, 1.0, v134
	v_add_f32_e32 v135, 1.0, v135
	v_add_f32_e32 v136, 1.0, v136
	v_add_f32_e32 v137, 1.0, v137
	v_rcp_f32_e32 v134, v134
	v_rcp_f32_e32 v135, v135
	v_rcp_f32_e32 v136, v136
	v_rcp_f32_e32 v137, v137
	s_nop 0
	v_mul_f32_e32 v98, v98, v134
	v_mul_f32_e32 v99, v99, v135
	v_mul_f32_e32 v100, v100, v136
	v_mul_f32_e32 v101, v101, v137
	v_pk_mul_f32 v[136:137], v[110:111], v[110:111]
	v_pk_mul_f32 v[138:139], v[112:113], v[112:113]
	v_add_f32_e32 v140, 0, v136
	v_add_f32_e32 v140, v137, v140
	v_add_f32_e32 v140, v138, v140
	v_add_f32_e32 v140, v139, v140
	v_pk_mul_f32 v[136:137], v[106:107], v[106:107]
	v_pk_mul_f32 v[138:139], v[108:109], v[108:109]
	v_add_f32_e32 v140, v136, v140
	v_add_f32_e32 v140, v137, v140
	v_add_f32_e32 v140, v138, v140
	v_add_f32_e32 v140, v139, v140
	v_pk_mul_f32 v[136:137], v[102:103], v[102:103]
	v_pk_mul_f32 v[138:139], v[104:105], v[104:105]
	v_add_f32_e32 v140, v136, v140
	v_add_f32_e32 v140, v137, v140
	v_add_f32_e32 v140, v138, v140
	v_add_f32_e32 v140, v139, v140
	v_pk_mul_f32 v[136:137], v[98:99], v[98:99]
	v_pk_mul_f32 v[138:139], v[100:101], v[100:101]
	v_add_f32_e32 v140, v136, v140
	v_add_f32_e32 v140, v137, v140
	v_add_f32_e32 v140, v138, v140
	v_add_f32_e32 v140, v139, v140
	ds_bpermute_b32 v141, v186, v140
	s_waitcnt lgkmcnt(0)
	v_add_f32_e32 v140, v140, v141
	ds_bpermute_b32 v141, v185, v140
	s_waitcnt lgkmcnt(0)
	v_add_f32_e32 v140, v140, v141
	v_mov_b32_e32 v141, 0x358637bd
	v_fmamk_f32 v140, v140, 0x3c800000, v141
	v_mul_f32_e32 v141, 0x4b800000, v140
	v_cmp_gt_f32_e32 vcc, 0x800000, v140
	s_nop 1
	v_cndmask_b32_e32 v140, v140, v141, vcc
	v_rsq_f32_e32 v140, v140
	s_nop 0
	v_mul_f32_e32 v141, 0x45800000, v140
	v_cndmask_b32_e32 v145, v140, v141, vcc
	v_mul_f32_e32 v130, 0x3d372713, v94
	v_mul_f32_e32 v131, 0x3d372713, v95
	v_mul_f32_e32 v132, 0x3d372713, v96
	v_mul_f32_e32 v133, 0x3d372713, v97
	v_mul_f32_e32 v130, v94, v130
	v_mul_f32_e32 v131, v95, v131
	v_mul_f32_e32 v132, v96, v132
	v_mul_f32_e32 v133, v97, v133
	v_fma_f32 v130, v94, v130, v94
	v_fma_f32 v131, v95, v131, v95
	v_fma_f32 v132, v96, v132, v96
	v_fma_f32 v133, v97, v133, v97
	v_mul_f32_e32 v130, 0x3f4c422a, v130
	v_mul_f32_e32 v131, 0x3f4c422a, v131
	v_mul_f32_e32 v132, 0x3f4c422a, v132
	v_mul_f32_e32 v133, 0x3f4c422a, v133
	v_mul_f32_e32 v130, -2.0, v130
	v_mul_f32_e32 v131, -2.0, v131
	v_mul_f32_e32 v132, -2.0, v132
	v_mul_f32_e32 v133, -2.0, v133
	v_mul_f32_e32 v130, 0x3fb8aa3b, v130
	v_mul_f32_e32 v131, 0x3fb8aa3b, v131
	v_mul_f32_e32 v132, 0x3fb8aa3b, v132
	v_mul_f32_e32 v133, 0x3fb8aa3b, v133
	v_exp_f32_e32 v130, v130
	v_exp_f32_e32 v131, v131
	v_exp_f32_e32 v132, v132
	v_exp_f32_e32 v133, v133
	v_add_f32_e32 v130, 1.0, v130
	v_add_f32_e32 v131, 1.0, v131
	v_add_f32_e32 v132, 1.0, v132
	v_add_f32_e32 v133, 1.0, v133
	v_rcp_f32_e32 v130, v130
	v_rcp_f32_e32 v131, v131
	v_rcp_f32_e32 v132, v132
	v_rcp_f32_e32 v133, v133
	s_nop 0
	v_mul_f32_e32 v94, v94, v130
	v_mul_f32_e32 v95, v95, v131
	v_mul_f32_e32 v96, v96, v132
	v_mul_f32_e32 v97, v97, v133
	v_mul_f32_e32 v134, 0x3d372713, v90
	v_mul_f32_e32 v135, 0x3d372713, v91
	v_mul_f32_e32 v136, 0x3d372713, v92
	v_mul_f32_e32 v137, 0x3d372713, v93
	v_mul_f32_e32 v134, v90, v134
	v_mul_f32_e32 v135, v91, v135
	v_mul_f32_e32 v136, v92, v136
	v_mul_f32_e32 v137, v93, v137
	v_fma_f32 v134, v90, v134, v90
	v_fma_f32 v135, v91, v135, v91
	v_fma_f32 v136, v92, v136, v92
	v_fma_f32 v137, v93, v137, v93
	v_mul_f32_e32 v134, 0x3f4c422a, v134
	v_mul_f32_e32 v135, 0x3f4c422a, v135
	v_mul_f32_e32 v136, 0x3f4c422a, v136
	v_mul_f32_e32 v137, 0x3f4c422a, v137
	v_mul_f32_e32 v134, -2.0, v134
	v_mul_f32_e32 v135, -2.0, v135
	v_mul_f32_e32 v136, -2.0, v136
	v_mul_f32_e32 v137, -2.0, v137
	v_mul_f32_e32 v134, 0x3fb8aa3b, v134
	v_mul_f32_e32 v135, 0x3fb8aa3b, v135
	v_mul_f32_e32 v136, 0x3fb8aa3b, v136
	v_mul_f32_e32 v137, 0x3fb8aa3b, v137
	v_exp_f32_e32 v134, v134
	v_exp_f32_e32 v135, v135
	v_exp_f32_e32 v136, v136
	v_exp_f32_e32 v137, v137
	v_add_f32_e32 v134, 1.0, v134
	v_add_f32_e32 v135, 1.0, v135
	v_add_f32_e32 v136, 1.0, v136
	v_add_f32_e32 v137, 1.0, v137
	v_rcp_f32_e32 v134, v134
	v_rcp_f32_e32 v135, v135
	v_rcp_f32_e32 v136, v136
	v_rcp_f32_e32 v137, v137
	s_nop 0
	v_mul_f32_e32 v90, v90, v134
	v_mul_f32_e32 v91, v91, v135
	v_mul_f32_e32 v92, v92, v136
	v_mul_f32_e32 v93, v93, v137
	v_mul_f32_e32 v130, 0x3d372713, v86
	v_mul_f32_e32 v131, 0x3d372713, v87
	v_mul_f32_e32 v132, 0x3d372713, v88
	v_mul_f32_e32 v133, 0x3d372713, v89
	v_mul_f32_e32 v130, v86, v130
	v_mul_f32_e32 v131, v87, v131
	v_mul_f32_e32 v132, v88, v132
	v_mul_f32_e32 v133, v89, v133
	v_fma_f32 v130, v86, v130, v86
	v_fma_f32 v131, v87, v131, v87
	v_fma_f32 v132, v88, v132, v88
	v_fma_f32 v133, v89, v133, v89
	v_mul_f32_e32 v130, 0x3f4c422a, v130
	v_mul_f32_e32 v131, 0x3f4c422a, v131
	v_mul_f32_e32 v132, 0x3f4c422a, v132
	v_mul_f32_e32 v133, 0x3f4c422a, v133
	v_mul_f32_e32 v130, -2.0, v130
	v_mul_f32_e32 v131, -2.0, v131
	v_mul_f32_e32 v132, -2.0, v132
	v_mul_f32_e32 v133, -2.0, v133
	v_mul_f32_e32 v130, 0x3fb8aa3b, v130
	v_mul_f32_e32 v131, 0x3fb8aa3b, v131
	v_mul_f32_e32 v132, 0x3fb8aa3b, v132
	v_mul_f32_e32 v133, 0x3fb8aa3b, v133
	v_exp_f32_e32 v130, v130
	v_exp_f32_e32 v131, v131
	v_exp_f32_e32 v132, v132
	v_exp_f32_e32 v133, v133
	v_add_f32_e32 v130, 1.0, v130
	v_add_f32_e32 v131, 1.0, v131
	v_add_f32_e32 v132, 1.0, v132
	v_add_f32_e32 v133, 1.0, v133
	v_rcp_f32_e32 v130, v130
	v_rcp_f32_e32 v131, v131
	v_rcp_f32_e32 v132, v132
	v_rcp_f32_e32 v133, v133
	s_nop 0
	v_mul_f32_e32 v86, v86, v130
	v_mul_f32_e32 v87, v87, v131
	v_mul_f32_e32 v88, v88, v132
	v_mul_f32_e32 v89, v89, v133
	v_mul_f32_e32 v134, 0x3d372713, v82
	v_mul_f32_e32 v135, 0x3d372713, v83
	v_mul_f32_e32 v136, 0x3d372713, v84
	v_mul_f32_e32 v137, 0x3d372713, v85
	v_mul_f32_e32 v134, v82, v134
	v_mul_f32_e32 v135, v83, v135
	v_mul_f32_e32 v136, v84, v136
	v_mul_f32_e32 v137, v85, v137
	v_fma_f32 v134, v82, v134, v82
	v_fma_f32 v135, v83, v135, v83
	v_fma_f32 v136, v84, v136, v84
	v_fma_f32 v137, v85, v137, v85
	v_mul_f32_e32 v134, 0x3f4c422a, v134
	v_mul_f32_e32 v135, 0x3f4c422a, v135
	v_mul_f32_e32 v136, 0x3f4c422a, v136
	v_mul_f32_e32 v137, 0x3f4c422a, v137
	v_mul_f32_e32 v134, -2.0, v134
	v_mul_f32_e32 v135, -2.0, v135
	v_mul_f32_e32 v136, -2.0, v136
	v_mul_f32_e32 v137, -2.0, v137
	v_mul_f32_e32 v134, 0x3fb8aa3b, v134
	v_mul_f32_e32 v135, 0x3fb8aa3b, v135
	v_mul_f32_e32 v136, 0x3fb8aa3b, v136
	v_mul_f32_e32 v137, 0x3fb8aa3b, v137
	v_exp_f32_e32 v134, v134
	v_exp_f32_e32 v135, v135
	v_exp_f32_e32 v136, v136
	v_exp_f32_e32 v137, v137
	v_add_f32_e32 v134, 1.0, v134
	v_add_f32_e32 v135, 1.0, v135
	v_add_f32_e32 v136, 1.0, v136
	v_add_f32_e32 v137, 1.0, v137
	v_rcp_f32_e32 v134, v134
	v_rcp_f32_e32 v135, v135
	v_rcp_f32_e32 v136, v136
	v_rcp_f32_e32 v137, v137
	s_nop 0
	v_mul_f32_e32 v82, v82, v134
	v_mul_f32_e32 v83, v83, v135
	v_mul_f32_e32 v84, v84, v136
	v_mul_f32_e32 v85, v85, v137
	v_pk_mul_f32 v[136:137], v[94:95], v[94:95]
	v_pk_mul_f32 v[138:139], v[96:97], v[96:97]
	v_add_f32_e32 v140, 0, v136
	v_add_f32_e32 v140, v137, v140
	v_add_f32_e32 v140, v138, v140
	v_add_f32_e32 v140, v139, v140
	v_pk_mul_f32 v[136:137], v[90:91], v[90:91]
	v_pk_mul_f32 v[138:139], v[92:93], v[92:93]
	v_add_f32_e32 v140, v136, v140
	v_add_f32_e32 v140, v137, v140
	v_add_f32_e32 v140, v138, v140
	v_add_f32_e32 v140, v139, v140
	v_pk_mul_f32 v[136:137], v[86:87], v[86:87]
	v_pk_mul_f32 v[138:139], v[88:89], v[88:89]
	v_add_f32_e32 v140, v136, v140
	v_add_f32_e32 v140, v137, v140
	v_add_f32_e32 v140, v138, v140
	v_add_f32_e32 v140, v139, v140
	v_pk_mul_f32 v[136:137], v[82:83], v[82:83]
	v_pk_mul_f32 v[138:139], v[84:85], v[84:85]
	v_add_f32_e32 v140, v136, v140
	v_add_f32_e32 v140, v137, v140
	v_add_f32_e32 v140, v138, v140
	v_add_f32_e32 v140, v139, v140
	ds_bpermute_b32 v141, v186, v140
	s_waitcnt lgkmcnt(0)
	v_add_f32_e32 v140, v140, v141
	ds_bpermute_b32 v141, v185, v140
	s_waitcnt lgkmcnt(0)
	v_add_f32_e32 v140, v140, v141
	v_mov_b32_e32 v141, 0x358637bd
	v_fmamk_f32 v140, v140, 0x3c800000, v141
	v_mul_f32_e32 v141, 0x4b800000, v140
	v_cmp_gt_f32_e32 vcc, 0x800000, v140
	s_nop 1
	v_cndmask_b32_e32 v140, v140, v141, vcc
	v_rsq_f32_e32 v140, v140
	s_nop 0
	v_mul_f32_e32 v141, 0x45800000, v140
	v_cndmask_b32_e32 v146, v140, v141, vcc
	v_mul_f32_e32 v130, 0x3d372713, v78
	v_mul_f32_e32 v131, 0x3d372713, v79
	v_mul_f32_e32 v132, 0x3d372713, v80
	v_mul_f32_e32 v133, 0x3d372713, v81
	v_mul_f32_e32 v130, v78, v130
	v_mul_f32_e32 v131, v79, v131
	v_mul_f32_e32 v132, v80, v132
	v_mul_f32_e32 v133, v81, v133
	v_fma_f32 v130, v78, v130, v78
	v_fma_f32 v131, v79, v131, v79
	v_fma_f32 v132, v80, v132, v80
	v_fma_f32 v133, v81, v133, v81
	v_mul_f32_e32 v130, 0x3f4c422a, v130
	v_mul_f32_e32 v131, 0x3f4c422a, v131
	v_mul_f32_e32 v132, 0x3f4c422a, v132
	v_mul_f32_e32 v133, 0x3f4c422a, v133
	v_mul_f32_e32 v130, -2.0, v130
	v_mul_f32_e32 v131, -2.0, v131
	v_mul_f32_e32 v132, -2.0, v132
	v_mul_f32_e32 v133, -2.0, v133
	v_mul_f32_e32 v130, 0x3fb8aa3b, v130
	v_mul_f32_e32 v131, 0x3fb8aa3b, v131
	v_mul_f32_e32 v132, 0x3fb8aa3b, v132
	v_mul_f32_e32 v133, 0x3fb8aa3b, v133
	v_exp_f32_e32 v130, v130
	v_exp_f32_e32 v131, v131
	v_exp_f32_e32 v132, v132
	v_exp_f32_e32 v133, v133
	v_add_f32_e32 v130, 1.0, v130
	v_add_f32_e32 v131, 1.0, v131
	v_add_f32_e32 v132, 1.0, v132
	v_add_f32_e32 v133, 1.0, v133
	v_rcp_f32_e32 v130, v130
	v_rcp_f32_e32 v131, v131
	v_rcp_f32_e32 v132, v132
	v_rcp_f32_e32 v133, v133
	s_nop 0
	v_mul_f32_e32 v78, v78, v130
	v_mul_f32_e32 v79, v79, v131
	v_mul_f32_e32 v80, v80, v132
	v_mul_f32_e32 v81, v81, v133
	v_mul_f32_e32 v134, 0x3d372713, v74
	v_mul_f32_e32 v135, 0x3d372713, v75
	v_mul_f32_e32 v136, 0x3d372713, v76
	v_mul_f32_e32 v137, 0x3d372713, v77
	v_mul_f32_e32 v134, v74, v134
	v_mul_f32_e32 v135, v75, v135
	v_mul_f32_e32 v136, v76, v136
	v_mul_f32_e32 v137, v77, v137
	v_fma_f32 v134, v74, v134, v74
	v_fma_f32 v135, v75, v135, v75
	v_fma_f32 v136, v76, v136, v76
	v_fma_f32 v137, v77, v137, v77
	v_mul_f32_e32 v134, 0x3f4c422a, v134
	v_mul_f32_e32 v135, 0x3f4c422a, v135
	v_mul_f32_e32 v136, 0x3f4c422a, v136
	v_mul_f32_e32 v137, 0x3f4c422a, v137
	v_mul_f32_e32 v134, -2.0, v134
	v_mul_f32_e32 v135, -2.0, v135
	v_mul_f32_e32 v136, -2.0, v136
	v_mul_f32_e32 v137, -2.0, v137
	v_mul_f32_e32 v134, 0x3fb8aa3b, v134
	v_mul_f32_e32 v135, 0x3fb8aa3b, v135
	v_mul_f32_e32 v136, 0x3fb8aa3b, v136
	v_mul_f32_e32 v137, 0x3fb8aa3b, v137
	v_exp_f32_e32 v134, v134
	v_exp_f32_e32 v135, v135
	v_exp_f32_e32 v136, v136
	v_exp_f32_e32 v137, v137
	v_add_f32_e32 v134, 1.0, v134
	v_add_f32_e32 v135, 1.0, v135
	v_add_f32_e32 v136, 1.0, v136
	v_add_f32_e32 v137, 1.0, v137
	v_rcp_f32_e32 v134, v134
	v_rcp_f32_e32 v135, v135
	v_rcp_f32_e32 v136, v136
	v_rcp_f32_e32 v137, v137
	s_nop 0
	v_mul_f32_e32 v74, v74, v134
	v_mul_f32_e32 v75, v75, v135
	v_mul_f32_e32 v76, v76, v136
	v_mul_f32_e32 v77, v77, v137
	v_mul_f32_e32 v130, 0x3d372713, v70
	v_mul_f32_e32 v131, 0x3d372713, v71
	v_mul_f32_e32 v132, 0x3d372713, v72
	v_mul_f32_e32 v133, 0x3d372713, v73
	v_mul_f32_e32 v130, v70, v130
	v_mul_f32_e32 v131, v71, v131
	v_mul_f32_e32 v132, v72, v132
	v_mul_f32_e32 v133, v73, v133
	v_fma_f32 v130, v70, v130, v70
	v_fma_f32 v131, v71, v131, v71
	v_fma_f32 v132, v72, v132, v72
	v_fma_f32 v133, v73, v133, v73
	v_mul_f32_e32 v130, 0x3f4c422a, v130
	v_mul_f32_e32 v131, 0x3f4c422a, v131
	v_mul_f32_e32 v132, 0x3f4c422a, v132
	v_mul_f32_e32 v133, 0x3f4c422a, v133
	v_mul_f32_e32 v130, -2.0, v130
	v_mul_f32_e32 v131, -2.0, v131
	v_mul_f32_e32 v132, -2.0, v132
	v_mul_f32_e32 v133, -2.0, v133
	v_mul_f32_e32 v130, 0x3fb8aa3b, v130
	v_mul_f32_e32 v131, 0x3fb8aa3b, v131
	v_mul_f32_e32 v132, 0x3fb8aa3b, v132
	v_mul_f32_e32 v133, 0x3fb8aa3b, v133
	v_exp_f32_e32 v130, v130
	v_exp_f32_e32 v131, v131
	v_exp_f32_e32 v132, v132
	v_exp_f32_e32 v133, v133
	v_add_f32_e32 v130, 1.0, v130
	v_add_f32_e32 v131, 1.0, v131
	v_add_f32_e32 v132, 1.0, v132
	v_add_f32_e32 v133, 1.0, v133
	v_rcp_f32_e32 v130, v130
	v_rcp_f32_e32 v131, v131
	v_rcp_f32_e32 v132, v132
	v_rcp_f32_e32 v133, v133
	s_nop 0
	v_mul_f32_e32 v70, v70, v130
	v_mul_f32_e32 v71, v71, v131
	v_mul_f32_e32 v72, v72, v132
	v_mul_f32_e32 v73, v73, v133
	v_mul_f32_e32 v134, 0x3d372713, v66
	v_mul_f32_e32 v135, 0x3d372713, v67
	v_mul_f32_e32 v136, 0x3d372713, v68
	v_mul_f32_e32 v137, 0x3d372713, v69
	v_mul_f32_e32 v134, v66, v134
	v_mul_f32_e32 v135, v67, v135
	v_mul_f32_e32 v136, v68, v136
	v_mul_f32_e32 v137, v69, v137
	v_fma_f32 v134, v66, v134, v66
	v_fma_f32 v135, v67, v135, v67
	v_fma_f32 v136, v68, v136, v68
	v_fma_f32 v137, v69, v137, v69
	v_mul_f32_e32 v134, 0x3f4c422a, v134
	v_mul_f32_e32 v135, 0x3f4c422a, v135
	v_mul_f32_e32 v136, 0x3f4c422a, v136
	v_mul_f32_e32 v137, 0x3f4c422a, v137
	v_mul_f32_e32 v134, -2.0, v134
	v_mul_f32_e32 v135, -2.0, v135
	v_mul_f32_e32 v136, -2.0, v136
	v_mul_f32_e32 v137, -2.0, v137
	v_mul_f32_e32 v134, 0x3fb8aa3b, v134
	v_mul_f32_e32 v135, 0x3fb8aa3b, v135
	v_mul_f32_e32 v136, 0x3fb8aa3b, v136
	v_mul_f32_e32 v137, 0x3fb8aa3b, v137
	v_exp_f32_e32 v134, v134
	v_exp_f32_e32 v135, v135
	v_exp_f32_e32 v136, v136
	v_exp_f32_e32 v137, v137
	v_add_f32_e32 v134, 1.0, v134
	v_add_f32_e32 v135, 1.0, v135
	v_add_f32_e32 v136, 1.0, v136
	v_add_f32_e32 v137, 1.0, v137
	v_rcp_f32_e32 v134, v134
	v_rcp_f32_e32 v135, v135
	v_rcp_f32_e32 v136, v136
	v_rcp_f32_e32 v137, v137
	s_nop 0
	v_mul_f32_e32 v66, v66, v134
	v_mul_f32_e32 v67, v67, v135
	v_mul_f32_e32 v68, v68, v136
	v_mul_f32_e32 v69, v69, v137
	v_pk_mul_f32 v[136:137], v[78:79], v[78:79]
	v_pk_mul_f32 v[138:139], v[80:81], v[80:81]
	v_add_f32_e32 v140, 0, v136
	v_add_f32_e32 v140, v137, v140
	v_add_f32_e32 v140, v138, v140
	v_add_f32_e32 v140, v139, v140
	v_pk_mul_f32 v[136:137], v[74:75], v[74:75]
	v_pk_mul_f32 v[138:139], v[76:77], v[76:77]
	v_add_f32_e32 v140, v136, v140
	v_add_f32_e32 v140, v137, v140
	v_add_f32_e32 v140, v138, v140
	v_add_f32_e32 v140, v139, v140
	v_pk_mul_f32 v[136:137], v[70:71], v[70:71]
	v_pk_mul_f32 v[138:139], v[72:73], v[72:73]
	v_add_f32_e32 v140, v136, v140
	v_add_f32_e32 v140, v137, v140
	v_add_f32_e32 v140, v138, v140
	v_add_f32_e32 v140, v139, v140
	v_pk_mul_f32 v[136:137], v[66:67], v[66:67]
	v_pk_mul_f32 v[138:139], v[68:69], v[68:69]
	v_add_f32_e32 v140, v136, v140
	v_add_f32_e32 v140, v137, v140
	v_add_f32_e32 v140, v138, v140
	v_add_f32_e32 v140, v139, v140
	ds_bpermute_b32 v141, v186, v140
	s_waitcnt lgkmcnt(0)
	v_add_f32_e32 v140, v140, v141
	ds_bpermute_b32 v141, v185, v140
	s_waitcnt lgkmcnt(0)
	v_add_f32_e32 v140, v140, v141
	v_mov_b32_e32 v141, 0x358637bd
	v_fmamk_f32 v140, v140, 0x3c800000, v141
	v_mul_f32_e32 v141, 0x4b800000, v140
	v_cmp_gt_f32_e32 vcc, 0x800000, v140
	s_nop 1
	v_cndmask_b32_e32 v140, v140, v141, vcc
	v_rsq_f32_e32 v140, v140
	s_nop 0
	v_mul_f32_e32 v141, 0x45800000, v140
	v_cndmask_b32_e32 v147, v140, v141, vcc
	v_mul_f32_e32 v130, 0x3d372713, v62
	v_mul_f32_e32 v131, 0x3d372713, v63
	v_mul_f32_e32 v132, 0x3d372713, v64
	v_mul_f32_e32 v133, 0x3d372713, v65
	v_mul_f32_e32 v130, v62, v130
	v_mul_f32_e32 v131, v63, v131
	v_mul_f32_e32 v132, v64, v132
	v_mul_f32_e32 v133, v65, v133
	v_fma_f32 v130, v62, v130, v62
	v_fma_f32 v131, v63, v131, v63
	v_fma_f32 v132, v64, v132, v64
	v_fma_f32 v133, v65, v133, v65
	v_mul_f32_e32 v130, 0x3f4c422a, v130
	v_mul_f32_e32 v131, 0x3f4c422a, v131
	v_mul_f32_e32 v132, 0x3f4c422a, v132
	v_mul_f32_e32 v133, 0x3f4c422a, v133
	v_mul_f32_e32 v130, -2.0, v130
	v_mul_f32_e32 v131, -2.0, v131
	v_mul_f32_e32 v132, -2.0, v132
	v_mul_f32_e32 v133, -2.0, v133
	v_mul_f32_e32 v130, 0x3fb8aa3b, v130
	v_mul_f32_e32 v131, 0x3fb8aa3b, v131
	v_mul_f32_e32 v132, 0x3fb8aa3b, v132
	v_mul_f32_e32 v133, 0x3fb8aa3b, v133
	v_exp_f32_e32 v130, v130
	v_exp_f32_e32 v131, v131
	v_exp_f32_e32 v132, v132
	v_exp_f32_e32 v133, v133
	v_add_f32_e32 v130, 1.0, v130
	v_add_f32_e32 v131, 1.0, v131
	v_add_f32_e32 v132, 1.0, v132
	v_add_f32_e32 v133, 1.0, v133
	v_rcp_f32_e32 v130, v130
	v_rcp_f32_e32 v131, v131
	v_rcp_f32_e32 v132, v132
	v_rcp_f32_e32 v133, v133
	s_nop 0
	v_mul_f32_e32 v62, v62, v130
	v_mul_f32_e32 v63, v63, v131
	v_mul_f32_e32 v64, v64, v132
	v_mul_f32_e32 v65, v65, v133
	v_mul_f32_e32 v134, 0x3d372713, v58
	v_mul_f32_e32 v135, 0x3d372713, v59
	v_mul_f32_e32 v136, 0x3d372713, v60
	v_mul_f32_e32 v137, 0x3d372713, v61
	v_mul_f32_e32 v134, v58, v134
	v_mul_f32_e32 v135, v59, v135
	v_mul_f32_e32 v136, v60, v136
	v_mul_f32_e32 v137, v61, v137
	v_fma_f32 v134, v58, v134, v58
	v_fma_f32 v135, v59, v135, v59
	v_fma_f32 v136, v60, v136, v60
	v_fma_f32 v137, v61, v137, v61
	v_mul_f32_e32 v134, 0x3f4c422a, v134
	v_mul_f32_e32 v135, 0x3f4c422a, v135
	v_mul_f32_e32 v136, 0x3f4c422a, v136
	v_mul_f32_e32 v137, 0x3f4c422a, v137
	v_mul_f32_e32 v134, -2.0, v134
	v_mul_f32_e32 v135, -2.0, v135
	v_mul_f32_e32 v136, -2.0, v136
	v_mul_f32_e32 v137, -2.0, v137
	v_mul_f32_e32 v134, 0x3fb8aa3b, v134
	v_mul_f32_e32 v135, 0x3fb8aa3b, v135
	v_mul_f32_e32 v136, 0x3fb8aa3b, v136
	v_mul_f32_e32 v137, 0x3fb8aa3b, v137
	v_exp_f32_e32 v134, v134
	v_exp_f32_e32 v135, v135
	v_exp_f32_e32 v136, v136
	v_exp_f32_e32 v137, v137
	v_add_f32_e32 v134, 1.0, v134
	v_add_f32_e32 v135, 1.0, v135
	v_add_f32_e32 v136, 1.0, v136
	v_add_f32_e32 v137, 1.0, v137
	v_rcp_f32_e32 v134, v134
	v_rcp_f32_e32 v135, v135
	v_rcp_f32_e32 v136, v136
	v_rcp_f32_e32 v137, v137
	s_nop 0
	v_mul_f32_e32 v58, v58, v134
	v_mul_f32_e32 v59, v59, v135
	v_mul_f32_e32 v60, v60, v136
	v_mul_f32_e32 v61, v61, v137
	v_mul_f32_e32 v130, 0x3d372713, v54
	v_mul_f32_e32 v131, 0x3d372713, v55
	v_mul_f32_e32 v132, 0x3d372713, v56
	v_mul_f32_e32 v133, 0x3d372713, v57
	v_mul_f32_e32 v130, v54, v130
	v_mul_f32_e32 v131, v55, v131
	v_mul_f32_e32 v132, v56, v132
	v_mul_f32_e32 v133, v57, v133
	v_fma_f32 v130, v54, v130, v54
	v_fma_f32 v131, v55, v131, v55
	v_fma_f32 v132, v56, v132, v56
	v_fma_f32 v133, v57, v133, v57
	v_mul_f32_e32 v130, 0x3f4c422a, v130
	v_mul_f32_e32 v131, 0x3f4c422a, v131
	v_mul_f32_e32 v132, 0x3f4c422a, v132
	v_mul_f32_e32 v133, 0x3f4c422a, v133
	v_mul_f32_e32 v130, -2.0, v130
	v_mul_f32_e32 v131, -2.0, v131
	v_mul_f32_e32 v132, -2.0, v132
	v_mul_f32_e32 v133, -2.0, v133
	v_mul_f32_e32 v130, 0x3fb8aa3b, v130
	v_mul_f32_e32 v131, 0x3fb8aa3b, v131
	v_mul_f32_e32 v132, 0x3fb8aa3b, v132
	v_mul_f32_e32 v133, 0x3fb8aa3b, v133
	v_exp_f32_e32 v130, v130
	v_exp_f32_e32 v131, v131
	v_exp_f32_e32 v132, v132
	v_exp_f32_e32 v133, v133
	v_add_f32_e32 v130, 1.0, v130
	v_add_f32_e32 v131, 1.0, v131
	v_add_f32_e32 v132, 1.0, v132
	v_add_f32_e32 v133, 1.0, v133
	v_rcp_f32_e32 v130, v130
	v_rcp_f32_e32 v131, v131
	v_rcp_f32_e32 v132, v132
	v_rcp_f32_e32 v133, v133
	s_nop 0
	v_mul_f32_e32 v54, v54, v130
	v_mul_f32_e32 v55, v55, v131
	v_mul_f32_e32 v56, v56, v132
	v_mul_f32_e32 v57, v57, v133
	v_mul_f32_e32 v134, 0x3d372713, v50
	v_mul_f32_e32 v135, 0x3d372713, v51
	v_mul_f32_e32 v136, 0x3d372713, v52
	v_mul_f32_e32 v137, 0x3d372713, v53
	v_mul_f32_e32 v134, v50, v134
	v_mul_f32_e32 v135, v51, v135
	v_mul_f32_e32 v136, v52, v136
	v_mul_f32_e32 v137, v53, v137
	v_fma_f32 v134, v50, v134, v50
	v_fma_f32 v135, v51, v135, v51
	v_fma_f32 v136, v52, v136, v52
	v_fma_f32 v137, v53, v137, v53
	v_mul_f32_e32 v134, 0x3f4c422a, v134
	v_mul_f32_e32 v135, 0x3f4c422a, v135
	v_mul_f32_e32 v136, 0x3f4c422a, v136
	v_mul_f32_e32 v137, 0x3f4c422a, v137
	v_mul_f32_e32 v134, -2.0, v134
	v_mul_f32_e32 v135, -2.0, v135
	v_mul_f32_e32 v136, -2.0, v136
	v_mul_f32_e32 v137, -2.0, v137
	v_mul_f32_e32 v134, 0x3fb8aa3b, v134
	v_mul_f32_e32 v135, 0x3fb8aa3b, v135
	v_mul_f32_e32 v136, 0x3fb8aa3b, v136
	v_mul_f32_e32 v137, 0x3fb8aa3b, v137
	v_exp_f32_e32 v134, v134
	v_exp_f32_e32 v135, v135
	v_exp_f32_e32 v136, v136
	v_exp_f32_e32 v137, v137
	v_add_f32_e32 v134, 1.0, v134
	v_add_f32_e32 v135, 1.0, v135
	v_add_f32_e32 v136, 1.0, v136
	v_add_f32_e32 v137, 1.0, v137
	v_rcp_f32_e32 v134, v134
	v_rcp_f32_e32 v135, v135
	v_rcp_f32_e32 v136, v136
	v_rcp_f32_e32 v137, v137
	s_nop 0
	v_mul_f32_e32 v50, v50, v134
	v_mul_f32_e32 v51, v51, v135
	v_mul_f32_e32 v52, v52, v136
	v_mul_f32_e32 v53, v53, v137
	v_pk_mul_f32 v[136:137], v[62:63], v[62:63]
	v_pk_mul_f32 v[138:139], v[64:65], v[64:65]
	v_add_f32_e32 v140, 0, v136
	v_add_f32_e32 v140, v137, v140
	v_add_f32_e32 v140, v138, v140
	v_add_f32_e32 v140, v139, v140
	v_pk_mul_f32 v[136:137], v[58:59], v[58:59]
	v_pk_mul_f32 v[138:139], v[60:61], v[60:61]
	v_add_f32_e32 v140, v136, v140
	v_add_f32_e32 v140, v137, v140
	v_add_f32_e32 v140, v138, v140
	v_add_f32_e32 v140, v139, v140
	v_pk_mul_f32 v[136:137], v[54:55], v[54:55]
	v_pk_mul_f32 v[138:139], v[56:57], v[56:57]
	v_add_f32_e32 v140, v136, v140
	v_add_f32_e32 v140, v137, v140
	v_add_f32_e32 v140, v138, v140
	v_add_f32_e32 v140, v139, v140
	v_pk_mul_f32 v[136:137], v[50:51], v[50:51]
	v_pk_mul_f32 v[138:139], v[52:53], v[52:53]
	v_add_f32_e32 v140, v136, v140
	v_add_f32_e32 v140, v137, v140
	v_add_f32_e32 v140, v138, v140
	v_add_f32_e32 v140, v139, v140
	ds_bpermute_b32 v141, v186, v140
	s_waitcnt lgkmcnt(0)
	v_add_f32_e32 v140, v140, v141
	ds_bpermute_b32 v141, v185, v140
	s_waitcnt lgkmcnt(0)
	v_add_f32_e32 v140, v140, v141
	v_mov_b32_e32 v141, 0x358637bd
	v_fmamk_f32 v140, v140, 0x3c800000, v141
	v_mul_f32_e32 v141, 0x4b800000, v140
	v_cmp_gt_f32_e32 vcc, 0x800000, v140
	s_nop 1
	v_cndmask_b32_e32 v140, v140, v141, vcc
	v_rsq_f32_e32 v140, v140
	s_nop 0
	v_mul_f32_e32 v141, 0x45800000, v140
	v_cndmask_b32_e32 v148, v140, v141, vcc
	v_mul_f32_e32 v130, 0x3d372713, v46
	v_mul_f32_e32 v131, 0x3d372713, v47
	v_mul_f32_e32 v132, 0x3d372713, v48
	v_mul_f32_e32 v133, 0x3d372713, v49
	v_mul_f32_e32 v130, v46, v130
	v_mul_f32_e32 v131, v47, v131
	v_mul_f32_e32 v132, v48, v132
	v_mul_f32_e32 v133, v49, v133
	v_fma_f32 v130, v46, v130, v46
	v_fma_f32 v131, v47, v131, v47
	v_fma_f32 v132, v48, v132, v48
	v_fma_f32 v133, v49, v133, v49
	v_mul_f32_e32 v130, 0x3f4c422a, v130
	v_mul_f32_e32 v131, 0x3f4c422a, v131
	v_mul_f32_e32 v132, 0x3f4c422a, v132
	v_mul_f32_e32 v133, 0x3f4c422a, v133
	v_mul_f32_e32 v130, -2.0, v130
	v_mul_f32_e32 v131, -2.0, v131
	v_mul_f32_e32 v132, -2.0, v132
	v_mul_f32_e32 v133, -2.0, v133
	v_mul_f32_e32 v130, 0x3fb8aa3b, v130
	v_mul_f32_e32 v131, 0x3fb8aa3b, v131
	v_mul_f32_e32 v132, 0x3fb8aa3b, v132
	v_mul_f32_e32 v133, 0x3fb8aa3b, v133
	v_exp_f32_e32 v130, v130
	v_exp_f32_e32 v131, v131
	v_exp_f32_e32 v132, v132
	v_exp_f32_e32 v133, v133
	v_add_f32_e32 v130, 1.0, v130
	v_add_f32_e32 v131, 1.0, v131
	v_add_f32_e32 v132, 1.0, v132
	v_add_f32_e32 v133, 1.0, v133
	v_rcp_f32_e32 v130, v130
	v_rcp_f32_e32 v131, v131
	v_rcp_f32_e32 v132, v132
	v_rcp_f32_e32 v133, v133
	s_nop 0
	v_mul_f32_e32 v46, v46, v130
	v_mul_f32_e32 v47, v47, v131
	v_mul_f32_e32 v48, v48, v132
	v_mul_f32_e32 v49, v49, v133
	v_mul_f32_e32 v134, 0x3d372713, v42
	v_mul_f32_e32 v135, 0x3d372713, v43
	v_mul_f32_e32 v136, 0x3d372713, v44
	v_mul_f32_e32 v137, 0x3d372713, v45
	v_mul_f32_e32 v134, v42, v134
	v_mul_f32_e32 v135, v43, v135
	v_mul_f32_e32 v136, v44, v136
	v_mul_f32_e32 v137, v45, v137
	v_fma_f32 v134, v42, v134, v42
	v_fma_f32 v135, v43, v135, v43
	v_fma_f32 v136, v44, v136, v44
	v_fma_f32 v137, v45, v137, v45
	v_mul_f32_e32 v134, 0x3f4c422a, v134
	v_mul_f32_e32 v135, 0x3f4c422a, v135
	v_mul_f32_e32 v136, 0x3f4c422a, v136
	v_mul_f32_e32 v137, 0x3f4c422a, v137
	v_mul_f32_e32 v134, -2.0, v134
	v_mul_f32_e32 v135, -2.0, v135
	v_mul_f32_e32 v136, -2.0, v136
	v_mul_f32_e32 v137, -2.0, v137
	v_mul_f32_e32 v134, 0x3fb8aa3b, v134
	v_mul_f32_e32 v135, 0x3fb8aa3b, v135
	v_mul_f32_e32 v136, 0x3fb8aa3b, v136
	v_mul_f32_e32 v137, 0x3fb8aa3b, v137
	v_exp_f32_e32 v134, v134
	v_exp_f32_e32 v135, v135
	v_exp_f32_e32 v136, v136
	v_exp_f32_e32 v137, v137
	v_add_f32_e32 v134, 1.0, v134
	v_add_f32_e32 v135, 1.0, v135
	v_add_f32_e32 v136, 1.0, v136
	v_add_f32_e32 v137, 1.0, v137
	v_rcp_f32_e32 v134, v134
	v_rcp_f32_e32 v135, v135
	v_rcp_f32_e32 v136, v136
	v_rcp_f32_e32 v137, v137
	s_nop 0
	v_mul_f32_e32 v42, v42, v134
	v_mul_f32_e32 v43, v43, v135
	v_mul_f32_e32 v44, v44, v136
	v_mul_f32_e32 v45, v45, v137
	v_mul_f32_e32 v130, 0x3d372713, v38
	v_mul_f32_e32 v131, 0x3d372713, v39
	v_mul_f32_e32 v132, 0x3d372713, v40
	v_mul_f32_e32 v133, 0x3d372713, v41
	v_mul_f32_e32 v130, v38, v130
	v_mul_f32_e32 v131, v39, v131
	v_mul_f32_e32 v132, v40, v132
	v_mul_f32_e32 v133, v41, v133
	v_fma_f32 v130, v38, v130, v38
	v_fma_f32 v131, v39, v131, v39
	v_fma_f32 v132, v40, v132, v40
	v_fma_f32 v133, v41, v133, v41
	v_mul_f32_e32 v130, 0x3f4c422a, v130
	v_mul_f32_e32 v131, 0x3f4c422a, v131
	v_mul_f32_e32 v132, 0x3f4c422a, v132
	v_mul_f32_e32 v133, 0x3f4c422a, v133
	v_mul_f32_e32 v130, -2.0, v130
	v_mul_f32_e32 v131, -2.0, v131
	v_mul_f32_e32 v132, -2.0, v132
	v_mul_f32_e32 v133, -2.0, v133
	v_mul_f32_e32 v130, 0x3fb8aa3b, v130
	v_mul_f32_e32 v131, 0x3fb8aa3b, v131
	v_mul_f32_e32 v132, 0x3fb8aa3b, v132
	v_mul_f32_e32 v133, 0x3fb8aa3b, v133
	v_exp_f32_e32 v130, v130
	v_exp_f32_e32 v131, v131
	v_exp_f32_e32 v132, v132
	v_exp_f32_e32 v133, v133
	v_add_f32_e32 v130, 1.0, v130
	v_add_f32_e32 v131, 1.0, v131
	v_add_f32_e32 v132, 1.0, v132
	v_add_f32_e32 v133, 1.0, v133
	v_rcp_f32_e32 v130, v130
	v_rcp_f32_e32 v131, v131
	v_rcp_f32_e32 v132, v132
	v_rcp_f32_e32 v133, v133
	s_nop 0
	v_mul_f32_e32 v38, v38, v130
	v_mul_f32_e32 v39, v39, v131
	v_mul_f32_e32 v40, v40, v132
	v_mul_f32_e32 v41, v41, v133
	v_mul_f32_e32 v134, 0x3d372713, v34
	v_mul_f32_e32 v135, 0x3d372713, v35
	v_mul_f32_e32 v136, 0x3d372713, v36
	v_mul_f32_e32 v137, 0x3d372713, v37
	v_mul_f32_e32 v134, v34, v134
	v_mul_f32_e32 v135, v35, v135
	v_mul_f32_e32 v136, v36, v136
	v_mul_f32_e32 v137, v37, v137
	v_fma_f32 v134, v34, v134, v34
	v_fma_f32 v135, v35, v135, v35
	v_fma_f32 v136, v36, v136, v36
	v_fma_f32 v137, v37, v137, v37
	v_mul_f32_e32 v134, 0x3f4c422a, v134
	v_mul_f32_e32 v135, 0x3f4c422a, v135
	v_mul_f32_e32 v136, 0x3f4c422a, v136
	v_mul_f32_e32 v137, 0x3f4c422a, v137
	v_mul_f32_e32 v134, -2.0, v134
	v_mul_f32_e32 v135, -2.0, v135
	v_mul_f32_e32 v136, -2.0, v136
	v_mul_f32_e32 v137, -2.0, v137
	v_mul_f32_e32 v134, 0x3fb8aa3b, v134
	v_mul_f32_e32 v135, 0x3fb8aa3b, v135
	v_mul_f32_e32 v136, 0x3fb8aa3b, v136
	v_mul_f32_e32 v137, 0x3fb8aa3b, v137
	v_exp_f32_e32 v134, v134
	v_exp_f32_e32 v135, v135
	v_exp_f32_e32 v136, v136
	v_exp_f32_e32 v137, v137
	v_add_f32_e32 v134, 1.0, v134
	v_add_f32_e32 v135, 1.0, v135
	v_add_f32_e32 v136, 1.0, v136
	v_add_f32_e32 v137, 1.0, v137
	v_rcp_f32_e32 v134, v134
	v_rcp_f32_e32 v135, v135
	v_rcp_f32_e32 v136, v136
	v_rcp_f32_e32 v137, v137
	s_nop 0
	v_mul_f32_e32 v34, v34, v134
	v_mul_f32_e32 v35, v35, v135
	v_mul_f32_e32 v36, v36, v136
	v_mul_f32_e32 v37, v37, v137
	v_pk_mul_f32 v[136:137], v[46:47], v[46:47]
	v_pk_mul_f32 v[138:139], v[48:49], v[48:49]
	v_add_f32_e32 v140, 0, v136
	v_add_f32_e32 v140, v137, v140
	v_add_f32_e32 v140, v138, v140
	v_add_f32_e32 v140, v139, v140
	v_pk_mul_f32 v[136:137], v[42:43], v[42:43]
	v_pk_mul_f32 v[138:139], v[44:45], v[44:45]
	v_add_f32_e32 v140, v136, v140
	v_add_f32_e32 v140, v137, v140
	v_add_f32_e32 v140, v138, v140
	v_add_f32_e32 v140, v139, v140
	v_pk_mul_f32 v[136:137], v[38:39], v[38:39]
	v_pk_mul_f32 v[138:139], v[40:41], v[40:41]
	v_add_f32_e32 v140, v136, v140
	v_add_f32_e32 v140, v137, v140
	v_add_f32_e32 v140, v138, v140
	v_add_f32_e32 v140, v139, v140
	v_pk_mul_f32 v[136:137], v[34:35], v[34:35]
	v_pk_mul_f32 v[138:139], v[36:37], v[36:37]
	v_add_f32_e32 v140, v136, v140
	v_add_f32_e32 v140, v137, v140
	v_add_f32_e32 v140, v138, v140
	v_add_f32_e32 v140, v139, v140
	ds_bpermute_b32 v141, v186, v140
	s_waitcnt lgkmcnt(0)
	v_add_f32_e32 v140, v140, v141
	ds_bpermute_b32 v141, v185, v140
	s_waitcnt lgkmcnt(0)
	v_add_f32_e32 v140, v140, v141
	v_mov_b32_e32 v141, 0x358637bd
	v_fmamk_f32 v140, v140, 0x3c800000, v141
	v_mul_f32_e32 v141, 0x4b800000, v140
	v_cmp_gt_f32_e32 vcc, 0x800000, v140
	s_nop 1
	v_cndmask_b32_e32 v140, v140, v141, vcc
	v_rsq_f32_e32 v140, v140
	s_nop 0
	v_mul_f32_e32 v141, 0x45800000, v140
	v_cndmask_b32_e32 v149, v140, v141, vcc
	v_mul_f32_e32 v130, 0x3d372713, v30
	v_mul_f32_e32 v131, 0x3d372713, v31
	v_mul_f32_e32 v132, 0x3d372713, v32
	v_mul_f32_e32 v133, 0x3d372713, v33
	v_mul_f32_e32 v130, v30, v130
	v_mul_f32_e32 v131, v31, v131
	v_mul_f32_e32 v132, v32, v132
	v_mul_f32_e32 v133, v33, v133
	v_fma_f32 v130, v30, v130, v30
	v_fma_f32 v131, v31, v131, v31
	v_fma_f32 v132, v32, v132, v32
	v_fma_f32 v133, v33, v133, v33
	v_mul_f32_e32 v130, 0x3f4c422a, v130
	v_mul_f32_e32 v131, 0x3f4c422a, v131
	v_mul_f32_e32 v132, 0x3f4c422a, v132
	v_mul_f32_e32 v133, 0x3f4c422a, v133
	v_mul_f32_e32 v130, -2.0, v130
	v_mul_f32_e32 v131, -2.0, v131
	v_mul_f32_e32 v132, -2.0, v132
	v_mul_f32_e32 v133, -2.0, v133
	v_mul_f32_e32 v130, 0x3fb8aa3b, v130
	v_mul_f32_e32 v131, 0x3fb8aa3b, v131
	v_mul_f32_e32 v132, 0x3fb8aa3b, v132
	v_mul_f32_e32 v133, 0x3fb8aa3b, v133
	v_exp_f32_e32 v130, v130
	v_exp_f32_e32 v131, v131
	v_exp_f32_e32 v132, v132
	v_exp_f32_e32 v133, v133
	v_add_f32_e32 v130, 1.0, v130
	v_add_f32_e32 v131, 1.0, v131
	v_add_f32_e32 v132, 1.0, v132
	v_add_f32_e32 v133, 1.0, v133
	v_rcp_f32_e32 v130, v130
	v_rcp_f32_e32 v131, v131
	v_rcp_f32_e32 v132, v132
	v_rcp_f32_e32 v133, v133
	s_nop 0
	v_mul_f32_e32 v30, v30, v130
	v_mul_f32_e32 v31, v31, v131
	v_mul_f32_e32 v32, v32, v132
	v_mul_f32_e32 v33, v33, v133
	v_mul_f32_e32 v134, 0x3d372713, v26
	v_mul_f32_e32 v135, 0x3d372713, v27
	v_mul_f32_e32 v136, 0x3d372713, v28
	v_mul_f32_e32 v137, 0x3d372713, v29
	v_mul_f32_e32 v134, v26, v134
	v_mul_f32_e32 v135, v27, v135
	v_mul_f32_e32 v136, v28, v136
	v_mul_f32_e32 v137, v29, v137
	v_fma_f32 v134, v26, v134, v26
	v_fma_f32 v135, v27, v135, v27
	v_fma_f32 v136, v28, v136, v28
	v_fma_f32 v137, v29, v137, v29
	v_mul_f32_e32 v134, 0x3f4c422a, v134
	v_mul_f32_e32 v135, 0x3f4c422a, v135
	v_mul_f32_e32 v136, 0x3f4c422a, v136
	v_mul_f32_e32 v137, 0x3f4c422a, v137
	v_mul_f32_e32 v134, -2.0, v134
	v_mul_f32_e32 v135, -2.0, v135
	v_mul_f32_e32 v136, -2.0, v136
	v_mul_f32_e32 v137, -2.0, v137
	v_mul_f32_e32 v134, 0x3fb8aa3b, v134
	v_mul_f32_e32 v135, 0x3fb8aa3b, v135
	v_mul_f32_e32 v136, 0x3fb8aa3b, v136
	v_mul_f32_e32 v137, 0x3fb8aa3b, v137
	v_exp_f32_e32 v134, v134
	v_exp_f32_e32 v135, v135
	v_exp_f32_e32 v136, v136
	v_exp_f32_e32 v137, v137
	v_add_f32_e32 v134, 1.0, v134
	v_add_f32_e32 v135, 1.0, v135
	v_add_f32_e32 v136, 1.0, v136
	v_add_f32_e32 v137, 1.0, v137
	v_rcp_f32_e32 v134, v134
	v_rcp_f32_e32 v135, v135
	v_rcp_f32_e32 v136, v136
	v_rcp_f32_e32 v137, v137
	s_nop 0
	v_mul_f32_e32 v26, v26, v134
	v_mul_f32_e32 v27, v27, v135
	v_mul_f32_e32 v28, v28, v136
	v_mul_f32_e32 v29, v29, v137
	v_mul_f32_e32 v130, 0x3d372713, v22
	v_mul_f32_e32 v131, 0x3d372713, v23
	v_mul_f32_e32 v132, 0x3d372713, v24
	v_mul_f32_e32 v133, 0x3d372713, v25
	v_mul_f32_e32 v130, v22, v130
	v_mul_f32_e32 v131, v23, v131
	v_mul_f32_e32 v132, v24, v132
	v_mul_f32_e32 v133, v25, v133
	v_fma_f32 v130, v22, v130, v22
	v_fma_f32 v131, v23, v131, v23
	v_fma_f32 v132, v24, v132, v24
	v_fma_f32 v133, v25, v133, v25
	v_mul_f32_e32 v130, 0x3f4c422a, v130
	v_mul_f32_e32 v131, 0x3f4c422a, v131
	v_mul_f32_e32 v132, 0x3f4c422a, v132
	v_mul_f32_e32 v133, 0x3f4c422a, v133
	v_mul_f32_e32 v130, -2.0, v130
	v_mul_f32_e32 v131, -2.0, v131
	v_mul_f32_e32 v132, -2.0, v132
	v_mul_f32_e32 v133, -2.0, v133
	v_mul_f32_e32 v130, 0x3fb8aa3b, v130
	v_mul_f32_e32 v131, 0x3fb8aa3b, v131
	v_mul_f32_e32 v132, 0x3fb8aa3b, v132
	v_mul_f32_e32 v133, 0x3fb8aa3b, v133
	v_exp_f32_e32 v130, v130
	v_exp_f32_e32 v131, v131
	v_exp_f32_e32 v132, v132
	v_exp_f32_e32 v133, v133
	v_add_f32_e32 v130, 1.0, v130
	v_add_f32_e32 v131, 1.0, v131
	v_add_f32_e32 v132, 1.0, v132
	v_add_f32_e32 v133, 1.0, v133
	v_rcp_f32_e32 v130, v130
	v_rcp_f32_e32 v131, v131
	v_rcp_f32_e32 v132, v132
	v_rcp_f32_e32 v133, v133
	s_nop 0
	v_mul_f32_e32 v22, v22, v130
	v_mul_f32_e32 v23, v23, v131
	v_mul_f32_e32 v24, v24, v132
	v_mul_f32_e32 v25, v25, v133
	v_mul_f32_e32 v134, 0x3d372713, v18
	v_mul_f32_e32 v135, 0x3d372713, v19
	v_mul_f32_e32 v136, 0x3d372713, v20
	v_mul_f32_e32 v137, 0x3d372713, v21
	v_mul_f32_e32 v134, v18, v134
	v_mul_f32_e32 v135, v19, v135
	v_mul_f32_e32 v136, v20, v136
	v_mul_f32_e32 v137, v21, v137
	v_fma_f32 v134, v18, v134, v18
	v_fma_f32 v135, v19, v135, v19
	v_fma_f32 v136, v20, v136, v20
	v_fma_f32 v137, v21, v137, v21
	v_mul_f32_e32 v134, 0x3f4c422a, v134
	v_mul_f32_e32 v135, 0x3f4c422a, v135
	v_mul_f32_e32 v136, 0x3f4c422a, v136
	v_mul_f32_e32 v137, 0x3f4c422a, v137
	v_mul_f32_e32 v134, -2.0, v134
	v_mul_f32_e32 v135, -2.0, v135
	v_mul_f32_e32 v136, -2.0, v136
	v_mul_f32_e32 v137, -2.0, v137
	v_mul_f32_e32 v134, 0x3fb8aa3b, v134
	v_mul_f32_e32 v135, 0x3fb8aa3b, v135
	v_mul_f32_e32 v136, 0x3fb8aa3b, v136
	v_mul_f32_e32 v137, 0x3fb8aa3b, v137
	v_exp_f32_e32 v134, v134
	v_exp_f32_e32 v135, v135
	v_exp_f32_e32 v136, v136
	v_exp_f32_e32 v137, v137
	v_add_f32_e32 v134, 1.0, v134
	v_add_f32_e32 v135, 1.0, v135
	v_add_f32_e32 v136, 1.0, v136
	v_add_f32_e32 v137, 1.0, v137
	v_rcp_f32_e32 v134, v134
	v_rcp_f32_e32 v135, v135
	v_rcp_f32_e32 v136, v136
	v_rcp_f32_e32 v137, v137
	s_nop 0
	v_mul_f32_e32 v18, v18, v134
	v_mul_f32_e32 v19, v19, v135
	v_mul_f32_e32 v20, v20, v136
	v_mul_f32_e32 v21, v21, v137
	v_pk_mul_f32 v[136:137], v[30:31], v[30:31]
	v_pk_mul_f32 v[138:139], v[32:33], v[32:33]
	v_add_f32_e32 v140, 0, v136
	v_add_f32_e32 v140, v137, v140
	v_add_f32_e32 v140, v138, v140
	v_add_f32_e32 v140, v139, v140
	v_pk_mul_f32 v[136:137], v[26:27], v[26:27]
	v_pk_mul_f32 v[138:139], v[28:29], v[28:29]
	v_add_f32_e32 v140, v136, v140
	v_add_f32_e32 v140, v137, v140
	v_add_f32_e32 v140, v138, v140
	v_add_f32_e32 v140, v139, v140
	v_pk_mul_f32 v[136:137], v[22:23], v[22:23]
	v_pk_mul_f32 v[138:139], v[24:25], v[24:25]
	v_add_f32_e32 v140, v136, v140
	v_add_f32_e32 v140, v137, v140
	v_add_f32_e32 v140, v138, v140
	v_add_f32_e32 v140, v139, v140
	v_pk_mul_f32 v[136:137], v[18:19], v[18:19]
	v_pk_mul_f32 v[138:139], v[20:21], v[20:21]
	v_add_f32_e32 v140, v136, v140
	v_add_f32_e32 v140, v137, v140
	v_add_f32_e32 v140, v138, v140
	v_add_f32_e32 v140, v139, v140
	ds_bpermute_b32 v141, v186, v140
	s_waitcnt lgkmcnt(0)
	v_add_f32_e32 v140, v140, v141
	ds_bpermute_b32 v141, v185, v140
	s_waitcnt lgkmcnt(0)
	v_add_f32_e32 v140, v140, v141
	v_mov_b32_e32 v141, 0x358637bd
	v_fmamk_f32 v140, v140, 0x3c800000, v141
	v_mul_f32_e32 v141, 0x4b800000, v140
	v_cmp_gt_f32_e32 vcc, 0x800000, v140
	s_nop 1
	v_cndmask_b32_e32 v140, v140, v141, vcc
	v_rsq_f32_e32 v140, v140
	s_nop 0
	v_mul_f32_e32 v141, 0x45800000, v140
	v_cndmask_b32_e32 v150, v140, v141, vcc
	v_mul_f32_e32 v130, 0x3d372713, v14
	v_mul_f32_e32 v131, 0x3d372713, v15
	v_mul_f32_e32 v132, 0x3d372713, v16
	v_mul_f32_e32 v133, 0x3d372713, v17
	v_mul_f32_e32 v130, v14, v130
	v_mul_f32_e32 v131, v15, v131
	v_mul_f32_e32 v132, v16, v132
	v_mul_f32_e32 v133, v17, v133
	v_fma_f32 v130, v14, v130, v14
	v_fma_f32 v131, v15, v131, v15
	v_fma_f32 v132, v16, v132, v16
	v_fma_f32 v133, v17, v133, v17
	v_mul_f32_e32 v130, 0x3f4c422a, v130
	v_mul_f32_e32 v131, 0x3f4c422a, v131
	v_mul_f32_e32 v132, 0x3f4c422a, v132
	v_mul_f32_e32 v133, 0x3f4c422a, v133
	v_mul_f32_e32 v130, -2.0, v130
	v_mul_f32_e32 v131, -2.0, v131
	v_mul_f32_e32 v132, -2.0, v132
	v_mul_f32_e32 v133, -2.0, v133
	v_mul_f32_e32 v130, 0x3fb8aa3b, v130
	v_mul_f32_e32 v131, 0x3fb8aa3b, v131
	v_mul_f32_e32 v132, 0x3fb8aa3b, v132
	v_mul_f32_e32 v133, 0x3fb8aa3b, v133
	v_exp_f32_e32 v130, v130
	v_exp_f32_e32 v131, v131
	v_exp_f32_e32 v132, v132
	v_exp_f32_e32 v133, v133
	v_add_f32_e32 v130, 1.0, v130
	v_add_f32_e32 v131, 1.0, v131
	v_add_f32_e32 v132, 1.0, v132
	v_add_f32_e32 v133, 1.0, v133
	v_rcp_f32_e32 v130, v130
	v_rcp_f32_e32 v131, v131
	v_rcp_f32_e32 v132, v132
	v_rcp_f32_e32 v133, v133
	s_nop 0
	v_mul_f32_e32 v14, v14, v130
	v_mul_f32_e32 v15, v15, v131
	v_mul_f32_e32 v16, v16, v132
	v_mul_f32_e32 v17, v17, v133
	v_mul_f32_e32 v134, 0x3d372713, v10
	v_mul_f32_e32 v135, 0x3d372713, v11
	v_mul_f32_e32 v136, 0x3d372713, v12
	v_mul_f32_e32 v137, 0x3d372713, v13
	v_mul_f32_e32 v134, v10, v134
	v_mul_f32_e32 v135, v11, v135
	v_mul_f32_e32 v136, v12, v136
	v_mul_f32_e32 v137, v13, v137
	v_fma_f32 v134, v10, v134, v10
	v_fma_f32 v135, v11, v135, v11
	v_fma_f32 v136, v12, v136, v12
	v_fma_f32 v137, v13, v137, v13
	v_mul_f32_e32 v134, 0x3f4c422a, v134
	v_mul_f32_e32 v135, 0x3f4c422a, v135
	v_mul_f32_e32 v136, 0x3f4c422a, v136
	v_mul_f32_e32 v137, 0x3f4c422a, v137
	v_mul_f32_e32 v134, -2.0, v134
	v_mul_f32_e32 v135, -2.0, v135
	v_mul_f32_e32 v136, -2.0, v136
	v_mul_f32_e32 v137, -2.0, v137
	v_mul_f32_e32 v134, 0x3fb8aa3b, v134
	v_mul_f32_e32 v135, 0x3fb8aa3b, v135
	v_mul_f32_e32 v136, 0x3fb8aa3b, v136
	v_mul_f32_e32 v137, 0x3fb8aa3b, v137
	v_exp_f32_e32 v134, v134
	v_exp_f32_e32 v135, v135
	v_exp_f32_e32 v136, v136
	v_exp_f32_e32 v137, v137
	v_add_f32_e32 v134, 1.0, v134
	v_add_f32_e32 v135, 1.0, v135
	v_add_f32_e32 v136, 1.0, v136
	v_add_f32_e32 v137, 1.0, v137
	v_rcp_f32_e32 v134, v134
	v_rcp_f32_e32 v135, v135
	v_rcp_f32_e32 v136, v136
	v_rcp_f32_e32 v137, v137
	s_nop 0
	v_mul_f32_e32 v10, v10, v134
	v_mul_f32_e32 v11, v11, v135
	v_mul_f32_e32 v12, v12, v136
	v_mul_f32_e32 v13, v13, v137
	v_mul_f32_e32 v130, 0x3d372713, v6
	v_mul_f32_e32 v131, 0x3d372713, v7
	v_mul_f32_e32 v132, 0x3d372713, v8
	v_mul_f32_e32 v133, 0x3d372713, v9
	v_mul_f32_e32 v130, v6, v130
	v_mul_f32_e32 v131, v7, v131
	v_mul_f32_e32 v132, v8, v132
	v_mul_f32_e32 v133, v9, v133
	v_fma_f32 v130, v6, v130, v6
	v_fma_f32 v131, v7, v131, v7
	v_fma_f32 v132, v8, v132, v8
	v_fma_f32 v133, v9, v133, v9
	v_mul_f32_e32 v130, 0x3f4c422a, v130
	v_mul_f32_e32 v131, 0x3f4c422a, v131
	v_mul_f32_e32 v132, 0x3f4c422a, v132
	v_mul_f32_e32 v133, 0x3f4c422a, v133
	v_mul_f32_e32 v130, -2.0, v130
	v_mul_f32_e32 v131, -2.0, v131
	v_mul_f32_e32 v132, -2.0, v132
	v_mul_f32_e32 v133, -2.0, v133
	v_mul_f32_e32 v130, 0x3fb8aa3b, v130
	v_mul_f32_e32 v131, 0x3fb8aa3b, v131
	v_mul_f32_e32 v132, 0x3fb8aa3b, v132
	v_mul_f32_e32 v133, 0x3fb8aa3b, v133
	v_exp_f32_e32 v130, v130
	v_exp_f32_e32 v131, v131
	v_exp_f32_e32 v132, v132
	v_exp_f32_e32 v133, v133
	v_add_f32_e32 v130, 1.0, v130
	v_add_f32_e32 v131, 1.0, v131
	v_add_f32_e32 v132, 1.0, v132
	v_add_f32_e32 v133, 1.0, v133
	v_rcp_f32_e32 v130, v130
	v_rcp_f32_e32 v131, v131
	v_rcp_f32_e32 v132, v132
	v_rcp_f32_e32 v133, v133
	s_nop 0
	v_mul_f32_e32 v6, v6, v130
	v_mul_f32_e32 v7, v7, v131
	v_mul_f32_e32 v8, v8, v132
	v_mul_f32_e32 v9, v9, v133
	v_mul_f32_e32 v134, 0x3d372713, v2
	v_mul_f32_e32 v135, 0x3d372713, v3
	v_mul_f32_e32 v136, 0x3d372713, v4
	v_mul_f32_e32 v137, 0x3d372713, v5
	v_mul_f32_e32 v134, v2, v134
	v_mul_f32_e32 v135, v3, v135
	v_mul_f32_e32 v136, v4, v136
	v_mul_f32_e32 v137, v5, v137
	v_fma_f32 v134, v2, v134, v2
	v_fma_f32 v135, v3, v135, v3
	v_fma_f32 v136, v4, v136, v4
	v_fma_f32 v137, v5, v137, v5
	v_mul_f32_e32 v134, 0x3f4c422a, v134
	v_mul_f32_e32 v135, 0x3f4c422a, v135
	v_mul_f32_e32 v136, 0x3f4c422a, v136
	v_mul_f32_e32 v137, 0x3f4c422a, v137
	v_mul_f32_e32 v134, -2.0, v134
	v_mul_f32_e32 v135, -2.0, v135
	v_mul_f32_e32 v136, -2.0, v136
	v_mul_f32_e32 v137, -2.0, v137
	v_mul_f32_e32 v134, 0x3fb8aa3b, v134
	v_mul_f32_e32 v135, 0x3fb8aa3b, v135
	v_mul_f32_e32 v136, 0x3fb8aa3b, v136
	v_mul_f32_e32 v137, 0x3fb8aa3b, v137
	v_exp_f32_e32 v134, v134
	v_exp_f32_e32 v135, v135
	v_exp_f32_e32 v136, v136
	v_exp_f32_e32 v137, v137
	v_add_f32_e32 v134, 1.0, v134
	v_add_f32_e32 v135, 1.0, v135
	v_add_f32_e32 v136, 1.0, v136
	v_add_f32_e32 v137, 1.0, v137
	v_rcp_f32_e32 v134, v134
	v_rcp_f32_e32 v135, v135
	v_rcp_f32_e32 v136, v136
	v_rcp_f32_e32 v137, v137
	s_nop 0
	v_mul_f32_e32 v2, v2, v134
	v_mul_f32_e32 v3, v3, v135
	v_mul_f32_e32 v4, v4, v136
	v_mul_f32_e32 v5, v5, v137
	v_pk_mul_f32 v[136:137], v[14:15], v[14:15]
	v_pk_mul_f32 v[138:139], v[16:17], v[16:17]
	v_add_f32_e32 v140, 0, v136
	v_add_f32_e32 v140, v137, v140
	v_add_f32_e32 v140, v138, v140
	v_add_f32_e32 v140, v139, v140
	v_pk_mul_f32 v[136:137], v[10:11], v[10:11]
	v_pk_mul_f32 v[138:139], v[12:13], v[12:13]
	v_add_f32_e32 v140, v136, v140
	v_add_f32_e32 v140, v137, v140
	v_add_f32_e32 v140, v138, v140
	v_add_f32_e32 v140, v139, v140
	v_pk_mul_f32 v[136:137], v[6:7], v[6:7]
	v_pk_mul_f32 v[138:139], v[8:9], v[8:9]
	v_add_f32_e32 v140, v136, v140
	v_add_f32_e32 v140, v137, v140
	v_add_f32_e32 v140, v138, v140
	v_add_f32_e32 v140, v139, v140
	v_pk_mul_f32 v[136:137], v[2:3], v[2:3]
	v_pk_mul_f32 v[138:139], v[4:5], v[4:5]
	v_add_f32_e32 v140, v136, v140
	v_add_f32_e32 v140, v137, v140
	v_add_f32_e32 v140, v138, v140
	v_add_f32_e32 v140, v139, v140
	ds_bpermute_b32 v141, v186, v140
	s_waitcnt lgkmcnt(0)
	v_add_f32_e32 v140, v140, v141
	ds_bpermute_b32 v141, v185, v140
	s_waitcnt lgkmcnt(0)
	v_add_f32_e32 v140, v140, v141
	v_mov_b32_e32 v141, 0x358637bd
	v_fmamk_f32 v140, v140, 0x3c800000, v141
	v_mul_f32_e32 v141, 0x4b800000, v140
	v_cmp_gt_f32_e32 vcc, 0x800000, v140
	s_nop 1
	v_cndmask_b32_e32 v140, v140, v141, vcc
	v_rsq_f32_e32 v140, v140
	s_nop 0
	v_mul_f32_e32 v141, 0x45800000, v140
	v_cndmask_b32_e32 v151, v140, v141, vcc
	v_fma_mixlo_f16 v130, v126, v144, 0
	v_fma_mixhi_f16 v130, v127, v144, 0
	ds_write_b16 v187, v130 offset:0
	ds_write_b16_d16_hi v187, v130 offset:144
	v_fma_mixlo_f16 v131, v128, v144, 0
	v_fma_mixhi_f16 v131, v129, v144, 0
	ds_write_b16 v187, v131 offset:288
	ds_write_b16_d16_hi v187, v131 offset:432
	v_fma_mixlo_f16 v132, v122, v144, 0
	v_fma_mixhi_f16 v132, v123, v144, 0
	ds_write_b16 v187, v132 offset:2304
	ds_write_b16_d16_hi v187, v132 offset:2448
	v_fma_mixlo_f16 v133, v124, v144, 0
	v_fma_mixhi_f16 v133, v125, v144, 0
	ds_write_b16 v187, v133 offset:2592
	ds_write_b16_d16_hi v187, v133 offset:2736
	v_fma_mixlo_f16 v134, v118, v144, 0
	v_fma_mixhi_f16 v134, v119, v144, 0
	ds_write_b16 v187, v134 offset:4608
	ds_write_b16_d16_hi v187, v134 offset:4752
	v_fma_mixlo_f16 v135, v120, v144, 0
	v_fma_mixhi_f16 v135, v121, v144, 0
	ds_write_b16 v187, v135 offset:4896
	ds_write_b16_d16_hi v187, v135 offset:5040
	v_fma_mixlo_f16 v136, v114, v144, 0
	v_fma_mixhi_f16 v136, v115, v144, 0
	ds_write_b16 v187, v136 offset:6912
	ds_write_b16_d16_hi v187, v136 offset:7056
	v_fma_mixlo_f16 v137, v116, v144, 0
	v_fma_mixhi_f16 v137, v117, v144, 0
	ds_write_b16 v187, v137 offset:7200
	ds_write_b16_d16_hi v187, v137 offset:7344
	v_fma_mixlo_f16 v130, v110, v145, 0
	v_fma_mixhi_f16 v130, v111, v145, 0
	ds_write_b16 v187, v130 offset:32
	ds_write_b16_d16_hi v187, v130 offset:176
	v_fma_mixlo_f16 v131, v112, v145, 0
	v_fma_mixhi_f16 v131, v113, v145, 0
	ds_write_b16 v187, v131 offset:320
	ds_write_b16_d16_hi v187, v131 offset:464
	v_fma_mixlo_f16 v132, v106, v145, 0
	v_fma_mixhi_f16 v132, v107, v145, 0
	ds_write_b16 v187, v132 offset:2336
	ds_write_b16_d16_hi v187, v132 offset:2480
	v_fma_mixlo_f16 v133, v108, v145, 0
	v_fma_mixhi_f16 v133, v109, v145, 0
	ds_write_b16 v187, v133 offset:2624
	ds_write_b16_d16_hi v187, v133 offset:2768
	v_fma_mixlo_f16 v134, v102, v145, 0
	v_fma_mixhi_f16 v134, v103, v145, 0
	ds_write_b16 v187, v134 offset:4640
	ds_write_b16_d16_hi v187, v134 offset:4784
	v_fma_mixlo_f16 v135, v104, v145, 0
	v_fma_mixhi_f16 v135, v105, v145, 0
	ds_write_b16 v187, v135 offset:4928
	ds_write_b16_d16_hi v187, v135 offset:5072
	v_fma_mixlo_f16 v136, v98, v145, 0
	v_fma_mixhi_f16 v136, v99, v145, 0
	ds_write_b16 v187, v136 offset:6944
	ds_write_b16_d16_hi v187, v136 offset:7088
	v_fma_mixlo_f16 v137, v100, v145, 0
	v_fma_mixhi_f16 v137, v101, v145, 0
	ds_write_b16 v187, v137 offset:7232
	ds_write_b16_d16_hi v187, v137 offset:7376
	v_fma_mixlo_f16 v130, v94, v146, 0
	v_fma_mixhi_f16 v130, v95, v146, 0
	ds_write_b16 v187, v130 offset:64
	ds_write_b16_d16_hi v187, v130 offset:208
	v_fma_mixlo_f16 v131, v96, v146, 0
	v_fma_mixhi_f16 v131, v97, v146, 0
	ds_write_b16 v187, v131 offset:352
	ds_write_b16_d16_hi v187, v131 offset:496
	v_fma_mixlo_f16 v132, v90, v146, 0
	v_fma_mixhi_f16 v132, v91, v146, 0
	ds_write_b16 v187, v132 offset:2368
	ds_write_b16_d16_hi v187, v132 offset:2512
	v_fma_mixlo_f16 v133, v92, v146, 0
	v_fma_mixhi_f16 v133, v93, v146, 0
	ds_write_b16 v187, v133 offset:2656
	ds_write_b16_d16_hi v187, v133 offset:2800
	v_fma_mixlo_f16 v134, v86, v146, 0
	v_fma_mixhi_f16 v134, v87, v146, 0
	ds_write_b16 v187, v134 offset:4672
	ds_write_b16_d16_hi v187, v134 offset:4816
	v_fma_mixlo_f16 v135, v88, v146, 0
	v_fma_mixhi_f16 v135, v89, v146, 0
	ds_write_b16 v187, v135 offset:4960
	ds_write_b16_d16_hi v187, v135 offset:5104
	v_fma_mixlo_f16 v136, v82, v146, 0
	v_fma_mixhi_f16 v136, v83, v146, 0
	ds_write_b16 v187, v136 offset:6976
	ds_write_b16_d16_hi v187, v136 offset:7120
	v_fma_mixlo_f16 v137, v84, v146, 0
	v_fma_mixhi_f16 v137, v85, v146, 0
	ds_write_b16 v187, v137 offset:7264
	ds_write_b16_d16_hi v187, v137 offset:7408
	v_fma_mixlo_f16 v130, v78, v147, 0
	v_fma_mixhi_f16 v130, v79, v147, 0
	ds_write_b16 v187, v130 offset:96
	ds_write_b16_d16_hi v187, v130 offset:240
	v_fma_mixlo_f16 v131, v80, v147, 0
	v_fma_mixhi_f16 v131, v81, v147, 0
	ds_write_b16 v187, v131 offset:384
	ds_write_b16_d16_hi v187, v131 offset:528
	v_fma_mixlo_f16 v132, v74, v147, 0
	v_fma_mixhi_f16 v132, v75, v147, 0
	ds_write_b16 v187, v132 offset:2400
	ds_write_b16_d16_hi v187, v132 offset:2544
	v_fma_mixlo_f16 v133, v76, v147, 0
	v_fma_mixhi_f16 v133, v77, v147, 0
	ds_write_b16 v187, v133 offset:2688
	ds_write_b16_d16_hi v187, v133 offset:2832
	v_fma_mixlo_f16 v134, v70, v147, 0
	v_fma_mixhi_f16 v134, v71, v147, 0
	ds_write_b16 v187, v134 offset:4704
	ds_write_b16_d16_hi v187, v134 offset:4848
	v_fma_mixlo_f16 v135, v72, v147, 0
	v_fma_mixhi_f16 v135, v73, v147, 0
	ds_write_b16 v187, v135 offset:4992
	ds_write_b16_d16_hi v187, v135 offset:5136
	v_fma_mixlo_f16 v136, v66, v147, 0
	v_fma_mixhi_f16 v136, v67, v147, 0
	ds_write_b16 v187, v136 offset:7008
	ds_write_b16_d16_hi v187, v136 offset:7152
	v_fma_mixlo_f16 v137, v68, v147, 0
	v_fma_mixhi_f16 v137, v69, v147, 0
	ds_write_b16 v187, v137 offset:7296
	ds_write_b16_d16_hi v187, v137 offset:7440
	s_waitcnt lgkmcnt(0)
	ds_read_b128 v[152:155], v189 offset:0
	ds_read_b128 v[156:159], v189 offset:1152
	ds_read_b128 v[160:163], v189 offset:2304
	ds_read_b128 v[164:167], v189 offset:3456
	ds_read_b128 v[168:171], v189 offset:4608
	ds_read_b128 v[172:175], v189 offset:5760
	ds_read_b128 v[176:179], v189 offset:6912
	ds_read_b128 v[180:183], v189 offset:8064
	s_waitcnt lgkmcnt(7)
	global_store_dwordx4 v193, v[152:155], s[22:23]
	v_add_u32_e32 v193, s3, v193
	s_waitcnt lgkmcnt(6)
	global_store_dwordx4 v193, v[156:159], s[22:23]
	v_add_u32_e32 v193, s3, v193
	s_waitcnt lgkmcnt(5)
	global_store_dwordx4 v193, v[160:163], s[22:23]
	v_add_u32_e32 v193, s3, v193
	s_waitcnt lgkmcnt(4)
	global_store_dwordx4 v193, v[164:167], s[22:23]
	v_add_u32_e32 v193, s3, v193
	s_waitcnt lgkmcnt(3)
	global_store_dwordx4 v193, v[168:171], s[22:23]
	v_add_u32_e32 v193, s3, v193
	s_waitcnt lgkmcnt(2)
	global_store_dwordx4 v193, v[172:175], s[22:23]
	v_add_u32_e32 v193, s3, v193
	s_waitcnt lgkmcnt(1)
	global_store_dwordx4 v193, v[176:179], s[22:23]
	v_add_u32_e32 v193, s3, v193
	s_waitcnt lgkmcnt(0)
	global_store_dwordx4 v193, v[180:183], s[22:23]
	s_lshl_b32 s2, s3, 3
	s_sub_i32 s2, 0x80, s2
	s_add_i32 s2, s2, s3
	v_add_u32_e32 v193, s2, v193
	v_fma_mixlo_f16 v130, v62, v148, 0
	v_fma_mixhi_f16 v130, v63, v148, 0
	ds_write_b16 v187, v130 offset:0
	ds_write_b16_d16_hi v187, v130 offset:144
	v_fma_mixlo_f16 v131, v64, v148, 0
	v_fma_mixhi_f16 v131, v65, v148, 0
	ds_write_b16 v187, v131 offset:288
	ds_write_b16_d16_hi v187, v131 offset:432
	v_fma_mixlo_f16 v132, v58, v148, 0
	v_fma_mixhi_f16 v132, v59, v148, 0
	ds_write_b16 v187, v132 offset:2304
	ds_write_b16_d16_hi v187, v132 offset:2448
	v_fma_mixlo_f16 v133, v60, v148, 0
	v_fma_mixhi_f16 v133, v61, v148, 0
	ds_write_b16 v187, v133 offset:2592
	ds_write_b16_d16_hi v187, v133 offset:2736
	v_fma_mixlo_f16 v134, v54, v148, 0
	v_fma_mixhi_f16 v134, v55, v148, 0
	ds_write_b16 v187, v134 offset:4608
	ds_write_b16_d16_hi v187, v134 offset:4752
	v_fma_mixlo_f16 v135, v56, v148, 0
	v_fma_mixhi_f16 v135, v57, v148, 0
	ds_write_b16 v187, v135 offset:4896
	ds_write_b16_d16_hi v187, v135 offset:5040
	v_fma_mixlo_f16 v136, v50, v148, 0
	v_fma_mixhi_f16 v136, v51, v148, 0
	ds_write_b16 v187, v136 offset:6912
	ds_write_b16_d16_hi v187, v136 offset:7056
	v_fma_mixlo_f16 v137, v52, v148, 0
	v_fma_mixhi_f16 v137, v53, v148, 0
	ds_write_b16 v187, v137 offset:7200
	ds_write_b16_d16_hi v187, v137 offset:7344
	v_fma_mixlo_f16 v130, v46, v149, 0
	v_fma_mixhi_f16 v130, v47, v149, 0
	ds_write_b16 v187, v130 offset:32
	ds_write_b16_d16_hi v187, v130 offset:176
	v_fma_mixlo_f16 v131, v48, v149, 0
	v_fma_mixhi_f16 v131, v49, v149, 0
	ds_write_b16 v187, v131 offset:320
	ds_write_b16_d16_hi v187, v131 offset:464
	v_fma_mixlo_f16 v132, v42, v149, 0
	v_fma_mixhi_f16 v132, v43, v149, 0
	ds_write_b16 v187, v132 offset:2336
	ds_write_b16_d16_hi v187, v132 offset:2480
	v_fma_mixlo_f16 v133, v44, v149, 0
	v_fma_mixhi_f16 v133, v45, v149, 0
	ds_write_b16 v187, v133 offset:2624
	ds_write_b16_d16_hi v187, v133 offset:2768
	v_fma_mixlo_f16 v134, v38, v149, 0
	v_fma_mixhi_f16 v134, v39, v149, 0
	ds_write_b16 v187, v134 offset:4640
	ds_write_b16_d16_hi v187, v134 offset:4784
	v_fma_mixlo_f16 v135, v40, v149, 0
	v_fma_mixhi_f16 v135, v41, v149, 0
	ds_write_b16 v187, v135 offset:4928
	ds_write_b16_d16_hi v187, v135 offset:5072
	v_fma_mixlo_f16 v136, v34, v149, 0
	v_fma_mixhi_f16 v136, v35, v149, 0
	ds_write_b16 v187, v136 offset:6944
	ds_write_b16_d16_hi v187, v136 offset:7088
	v_fma_mixlo_f16 v137, v36, v149, 0
	v_fma_mixhi_f16 v137, v37, v149, 0
	ds_write_b16 v187, v137 offset:7232
	ds_write_b16_d16_hi v187, v137 offset:7376
	v_fma_mixlo_f16 v130, v30, v150, 0
	v_fma_mixhi_f16 v130, v31, v150, 0
	ds_write_b16 v187, v130 offset:64
	ds_write_b16_d16_hi v187, v130 offset:208
	v_fma_mixlo_f16 v131, v32, v150, 0
	v_fma_mixhi_f16 v131, v33, v150, 0
	ds_write_b16 v187, v131 offset:352
	ds_write_b16_d16_hi v187, v131 offset:496
	v_fma_mixlo_f16 v132, v26, v150, 0
	v_fma_mixhi_f16 v132, v27, v150, 0
	ds_write_b16 v187, v132 offset:2368
	ds_write_b16_d16_hi v187, v132 offset:2512
	v_fma_mixlo_f16 v133, v28, v150, 0
	v_fma_mixhi_f16 v133, v29, v150, 0
	ds_write_b16 v187, v133 offset:2656
	ds_write_b16_d16_hi v187, v133 offset:2800
	v_fma_mixlo_f16 v134, v22, v150, 0
	v_fma_mixhi_f16 v134, v23, v150, 0
	ds_write_b16 v187, v134 offset:4672
	ds_write_b16_d16_hi v187, v134 offset:4816
	v_fma_mixlo_f16 v135, v24, v150, 0
	v_fma_mixhi_f16 v135, v25, v150, 0
	ds_write_b16 v187, v135 offset:4960
	ds_write_b16_d16_hi v187, v135 offset:5104
	v_fma_mixlo_f16 v136, v18, v150, 0
	v_fma_mixhi_f16 v136, v19, v150, 0
	ds_write_b16 v187, v136 offset:6976
	ds_write_b16_d16_hi v187, v136 offset:7120
	v_fma_mixlo_f16 v137, v20, v150, 0
	v_fma_mixhi_f16 v137, v21, v150, 0
	ds_write_b16 v187, v137 offset:7264
	ds_write_b16_d16_hi v187, v137 offset:7408
	v_fma_mixlo_f16 v130, v14, v151, 0
	v_fma_mixhi_f16 v130, v15, v151, 0
	ds_write_b16 v187, v130 offset:96
	ds_write_b16_d16_hi v187, v130 offset:240
	v_fma_mixlo_f16 v131, v16, v151, 0
	v_fma_mixhi_f16 v131, v17, v151, 0
	ds_write_b16 v187, v131 offset:384
	ds_write_b16_d16_hi v187, v131 offset:528
	v_fma_mixlo_f16 v132, v10, v151, 0
	v_fma_mixhi_f16 v132, v11, v151, 0
	ds_write_b16 v187, v132 offset:2400
	ds_write_b16_d16_hi v187, v132 offset:2544
	v_fma_mixlo_f16 v133, v12, v151, 0
	v_fma_mixhi_f16 v133, v13, v151, 0
	ds_write_b16 v187, v133 offset:2688
	ds_write_b16_d16_hi v187, v133 offset:2832
	v_fma_mixlo_f16 v134, v6, v151, 0
	v_fma_mixhi_f16 v134, v7, v151, 0
	ds_write_b16 v187, v134 offset:4704
	ds_write_b16_d16_hi v187, v134 offset:4848
	v_fma_mixlo_f16 v135, v8, v151, 0
	v_fma_mixhi_f16 v135, v9, v151, 0
	ds_write_b16 v187, v135 offset:4992
	ds_write_b16_d16_hi v187, v135 offset:5136
	v_fma_mixlo_f16 v136, v2, v151, 0
	v_fma_mixhi_f16 v136, v3, v151, 0
	ds_write_b16 v187, v136 offset:7008
	ds_write_b16_d16_hi v187, v136 offset:7152
	v_fma_mixlo_f16 v137, v4, v151, 0
	v_fma_mixhi_f16 v137, v5, v151, 0
	ds_write_b16 v187, v137 offset:7296
	ds_write_b16_d16_hi v187, v137 offset:7440
	s_waitcnt lgkmcnt(0)
	ds_read_b128 v[152:155], v189 offset:0
	ds_read_b128 v[156:159], v189 offset:1152
	ds_read_b128 v[160:163], v189 offset:2304
	ds_read_b128 v[164:167], v189 offset:3456
	ds_read_b128 v[168:171], v189 offset:4608
	ds_read_b128 v[172:175], v189 offset:5760
	ds_read_b128 v[176:179], v189 offset:6912
	ds_read_b128 v[180:183], v189 offset:8064
	s_waitcnt lgkmcnt(7)
	global_store_dwordx4 v193, v[152:155], s[22:23]
	v_add_u32_e32 v193, s3, v193
	s_waitcnt lgkmcnt(6)
	global_store_dwordx4 v193, v[156:159], s[22:23]
	v_add_u32_e32 v193, s3, v193
	s_waitcnt lgkmcnt(5)
	global_store_dwordx4 v193, v[160:163], s[22:23]
	v_add_u32_e32 v193, s3, v193
	s_waitcnt lgkmcnt(4)
	global_store_dwordx4 v193, v[164:167], s[22:23]
	v_add_u32_e32 v193, s3, v193
	s_waitcnt lgkmcnt(3)
	global_store_dwordx4 v193, v[168:171], s[22:23]
	v_add_u32_e32 v193, s3, v193
	s_waitcnt lgkmcnt(2)
	global_store_dwordx4 v193, v[172:175], s[22:23]
	v_add_u32_e32 v193, s3, v193
	s_waitcnt lgkmcnt(1)
	global_store_dwordx4 v193, v[176:179], s[22:23]
	v_add_u32_e32 v193, s3, v193
	s_waitcnt lgkmcnt(0)
	global_store_dwordx4 v193, v[180:183], s[22:23]
	s_waitcnt vmcnt(16)
	s_branch .Lp1_join
.Lp1_e_plain:
	v_and_b32_e32 v194, 15, v222
	v_bfe_u32 v195, v222, 4, 2
	v_bfe_u32 v196, v222, 6, 2
	v_lshrrev_b32_e32 v197, 8, v222
	v_lshl_or_b32 v198, v197, 7, v194
	v_lshlrev_b32_e32 v199, 2, v195
	v_lshl_or_b32 v199, v196, 6, v199
	v_readlane_b32 s22, v254, 14
	v_readlane_b32 s23, v254, 15
	s_nop 3
	s_add_u32 s22, s22, 0xbcae500
	s_addc_u32 s23, s23, 0
	s_mul_i32 s2, s4, 0x60000
	s_add_i32 s3, s5, -2
	s_lshl_b32 s3, s3, 9
	s_add_i32 s2, s2, s3
	s_add_u32 s22, s22, s2
	s_addc_u32 s23, s23, 0
	v_mul_u32_u24_e32 v193, 0x600, v198
	v_lshl_add_u32 v193, v199, 1, v193
	s_add_i32 s2, s53, s95
	s_cmp_lt_i32 s2, s58
	s_cselect_b32 s21, 1, 0
	s_cselect_b32 s53, s2, s53
	s_lshr_b32 s2, s53, 5
	s_mul_hi_u32 s2, s2, 0xcccccccd
	s_lshr_b32 s2, s2, 2
	s_lshl_b32 s3, s2, 4
	s_mul_i32 s2, s2, 0xa0
	s_sub_i32 s2, s53, s2
	s_lshr_b32 s2, s2, 4
	s_and_b32 s6, s53, 15
	s_add_i32 s3, s3, s6
	s_sub_i32 s28, s53, s58
	s_lshr_b32 s28, s28, 4
	s_add_i32 s28, s28, 8
	s_or_b32 s6, s6, 0x80
	s_cmp_ge_i32 s53, s58
	s_cselect_b32 s6, s6, s3
	s_cselect_b32 s28, s28, s2
	s_lshl_b32 s2, s6, 19
	s_add_u32 s12, s64, s2
	s_addc_u32 s13, s65, 0
	s_lshl_b32 s2, s28, 19
	s_add_u32 s14, s34, s2
	s_addc_u32 s15, s35, 0
	s_mov_b32 m0, s18
	s_nop 0
	global_load_lds_dwordx4 v1, s[12:13]
	s_add_i32 m0, s18, 0x2000
	s_add_u32 s16, s12, 0x20000
	s_addc_u32 s17, s13, 0
	global_load_lds_dwordx4 v1, s[16:17]
	s_add_i32 m0, s18, 0x4000
	s_add_u32 s16, s12, 0x40000
	s_addc_u32 s17, s13, 0
	global_load_lds_dwordx4 v1, s[16:17]
	s_add_i32 m0, s18, 0x6000
	s_add_u32 s16, s12, 0x60000
	s_addc_u32 s17, s13, 0
	global_load_lds_dwordx4 v1, s[16:17]
	s_add_i32 m0, s18, 0x8000
	s_nop 0
	global_load_lds_dwordx4 v1, s[14:15]
	s_add_i32 m0, s18, 0xa000
	s_add_u32 s16, s14, 0x20000
	s_addc_u32 s17, s15, 0
	global_load_lds_dwordx4 v1, s[16:17]
	s_add_i32 m0, s18, 0xc000
	s_add_u32 s16, s14, 0x40000
	s_addc_u32 s17, s15, 0
	global_load_lds_dwordx4 v1, s[16:17]
	s_add_i32 m0, s18, 0xe000
	s_add_u32 s16, s14, 0x60000
	s_addc_u32 s17, s15, 0
	global_load_lds_dwordx4 v1, s[16:17]
	v_cvt_pk_f16_f32 v126, v126, v127
	v_cvt_pk_f16_f32 v127, v128, v129
	global_store_dwordx2 v193, v[126:127], s[22:23] offset:0
	v_cvt_pk_f16_f32 v122, v122, v123
	v_cvt_pk_f16_f32 v123, v124, v125
	global_store_dwordx2 v193, v[122:123], s[22:23] offset:32
	v_cvt_pk_f16_f32 v118, v118, v119
	v_cvt_pk_f16_f32 v119, v120, v121
	global_store_dwordx2 v193, v[118:119], s[22:23] offset:64
	v_cvt_pk_f16_f32 v114, v114, v115
	v_cvt_pk_f16_f32 v115, v116, v117
	global_store_dwordx2 v193, v[114:115], s[22:23] offset:96
	v_add_u32_e32 v193, 0x6000, v193
	v_cvt_pk_f16_f32 v110, v110, v111
	v_cvt_pk_f16_f32 v111, v112, v113
	global_store_dwordx2 v193, v[110:111], s[22:23] offset:0
	v_cvt_pk_f16_f32 v106, v106, v107
	v_cvt_pk_f16_f32 v107, v108, v109
	global_store_dwordx2 v193, v[106:107], s[22:23] offset:32
	v_cvt_pk_f16_f32 v102, v102, v103
	v_cvt_pk_f16_f32 v103, v104, v105
	global_store_dwordx2 v193, v[102:103], s[22:23] offset:64
	v_cvt_pk_f16_f32 v98, v98, v99
	v_cvt_pk_f16_f32 v99, v100, v101
	global_store_dwordx2 v193, v[98:99], s[22:23] offset:96
	v_add_u32_e32 v193, 0x6000, v193
	v_cvt_pk_f16_f32 v94, v94, v95
	v_cvt_pk_f16_f32 v95, v96, v97
	global_store_dwordx2 v193, v[94:95], s[22:23] offset:0
	v_cvt_pk_f16_f32 v90, v90, v91
	v_cvt_pk_f16_f32 v91, v92, v93
	global_store_dwordx2 v193, v[90:91], s[22:23] offset:32
	v_cvt_pk_f16_f32 v86, v86, v87
	v_cvt_pk_f16_f32 v87, v88, v89
	global_store_dwordx2 v193, v[86:87], s[22:23] offset:64
	v_cvt_pk_f16_f32 v82, v82, v83
	v_cvt_pk_f16_f32 v83, v84, v85
	global_store_dwordx2 v193, v[82:83], s[22:23] offset:96
	v_add_u32_e32 v193, 0x6000, v193
	v_cvt_pk_f16_f32 v78, v78, v79
	v_cvt_pk_f16_f32 v79, v80, v81
	global_store_dwordx2 v193, v[78:79], s[22:23] offset:0
	v_cvt_pk_f16_f32 v74, v74, v75
	v_cvt_pk_f16_f32 v75, v76, v77
	global_store_dwordx2 v193, v[74:75], s[22:23] offset:32
	v_cvt_pk_f16_f32 v70, v70, v71
	v_cvt_pk_f16_f32 v71, v72, v73
	global_store_dwordx2 v193, v[70:71], s[22:23] offset:64
	v_cvt_pk_f16_f32 v66, v66, v67
	v_cvt_pk_f16_f32 v67, v68, v69
	global_store_dwordx2 v193, v[66:67], s[22:23] offset:96
	v_add_u32_e32 v193, 0x6000, v193
	v_cvt_pk_f16_f32 v62, v62, v63
	v_cvt_pk_f16_f32 v63, v64, v65
	global_store_dwordx2 v193, v[62:63], s[22:23] offset:0
	v_cvt_pk_f16_f32 v58, v58, v59
	v_cvt_pk_f16_f32 v59, v60, v61
	global_store_dwordx2 v193, v[58:59], s[22:23] offset:32
	v_cvt_pk_f16_f32 v54, v54, v55
	v_cvt_pk_f16_f32 v55, v56, v57
	global_store_dwordx2 v193, v[54:55], s[22:23] offset:64
	v_cvt_pk_f16_f32 v50, v50, v51
	v_cvt_pk_f16_f32 v51, v52, v53
	global_store_dwordx2 v193, v[50:51], s[22:23] offset:96
	v_add_u32_e32 v193, 0x6000, v193
	v_cvt_pk_f16_f32 v46, v46, v47
	v_cvt_pk_f16_f32 v47, v48, v49
	global_store_dwordx2 v193, v[46:47], s[22:23] offset:0
	v_cvt_pk_f16_f32 v42, v42, v43
	v_cvt_pk_f16_f32 v43, v44, v45
	global_store_dwordx2 v193, v[42:43], s[22:23] offset:32
	v_cvt_pk_f16_f32 v38, v38, v39
	v_cvt_pk_f16_f32 v39, v40, v41
	global_store_dwordx2 v193, v[38:39], s[22:23] offset:64
	v_cvt_pk_f16_f32 v34, v34, v35
	v_cvt_pk_f16_f32 v35, v36, v37
	global_store_dwordx2 v193, v[34:35], s[22:23] offset:96
	v_add_u32_e32 v193, 0x6000, v193
	v_cvt_pk_f16_f32 v30, v30, v31
	v_cvt_pk_f16_f32 v31, v32, v33
	global_store_dwordx2 v193, v[30:31], s[22:23] offset:0
	v_cvt_pk_f16_f32 v26, v26, v27
	v_cvt_pk_f16_f32 v27, v28, v29
	global_store_dwordx2 v193, v[26:27], s[22:23] offset:32
	v_cvt_pk_f16_f32 v22, v22, v23
	v_cvt_pk_f16_f32 v23, v24, v25
	global_store_dwordx2 v193, v[22:23], s[22:23] offset:64
	v_cvt_pk_f16_f32 v18, v18, v19
	v_cvt_pk_f16_f32 v19, v20, v21
	global_store_dwordx2 v193, v[18:19], s[22:23] offset:96
	v_add_u32_e32 v193, 0x6000, v193
	v_cvt_pk_f16_f32 v14, v14, v15
	v_cvt_pk_f16_f32 v15, v16, v17
	global_store_dwordx2 v193, v[14:15], s[22:23] offset:0
	v_cvt_pk_f16_f32 v10, v10, v11
	v_cvt_pk_f16_f32 v11, v12, v13
	global_store_dwordx2 v193, v[10:11], s[22:23] offset:32
	v_cvt_pk_f16_f32 v6, v6, v7
	v_cvt_pk_f16_f32 v7, v8, v9
	global_store_dwordx2 v193, v[6:7], s[22:23] offset:64
	v_cvt_pk_f16_f32 v2, v2, v3
	v_cvt_pk_f16_f32 v3, v4, v5
	global_store_dwordx2 v193, v[2:3], s[22:23] offset:96
	s_waitcnt vmcnt(32)
	s_branch .Lp1_join
.Lp1_e_gelu:
	v_and_b32_e32 v194, 15, v222
	v_bfe_u32 v195, v222, 4, 2
	v_bfe_u32 v196, v222, 6, 2
	v_lshrrev_b32_e32 v197, 8, v222
	v_lshl_or_b32 v198, v197, 7, v194
	v_lshlrev_b32_e32 v199, 2, v195
	v_lshl_or_b32 v199, v196, 6, v199
	v_readlane_b32 s22, v254, 14
	v_readlane_b32 s23, v254, 15
	s_nop 3
	s_add_u32 s22, s22, 0x98ae500
	s_addc_u32 s23, s23, 0
	s_lshl_b32 s2, s4, 17
	s_add_u32 s22, s22, s2
	s_addc_u32 s23, s23, 0
	v_lshlrev_b32_e32 v193, 9, v198
	v_lshl_add_u32 v193, v199, 1, v193
	s_add_i32 s2, s53, s95
	s_cmp_lt_i32 s2, s58
	s_cselect_b32 s21, 1, 0
	s_cselect_b32 s53, s2, s53
	s_lshr_b32 s2, s53, 5
	s_mul_hi_u32 s2, s2, 0xcccccccd
	s_lshr_b32 s2, s2, 2
	s_lshl_b32 s3, s2, 4
	s_mul_i32 s2, s2, 0xa0
	s_sub_i32 s2, s53, s2
	s_lshr_b32 s2, s2, 4
	s_and_b32 s6, s53, 15
	s_add_i32 s3, s3, s6
	s_sub_i32 s28, s53, s58
	s_lshr_b32 s28, s28, 4
	s_add_i32 s28, s28, 8
	s_or_b32 s6, s6, 0x80
	s_cmp_ge_i32 s53, s58
	s_cselect_b32 s6, s6, s3
	s_cselect_b32 s28, s28, s2
	s_lshl_b32 s2, s6, 19
	s_add_u32 s12, s64, s2
	s_addc_u32 s13, s65, 0
	s_lshl_b32 s2, s28, 19
	s_add_u32 s14, s34, s2
	s_addc_u32 s15, s35, 0
	s_mov_b32 m0, s18
	s_nop 0
	global_load_lds_dwordx4 v1, s[12:13]
	s_add_i32 m0, s18, 0x2000
	s_add_u32 s16, s12, 0x20000
	s_addc_u32 s17, s13, 0
	global_load_lds_dwordx4 v1, s[16:17]
	s_add_i32 m0, s18, 0x4000
	s_add_u32 s16, s12, 0x40000
	s_addc_u32 s17, s13, 0
	global_load_lds_dwordx4 v1, s[16:17]
	s_add_i32 m0, s18, 0x6000
	s_add_u32 s16, s12, 0x60000
	s_addc_u32 s17, s13, 0
	global_load_lds_dwordx4 v1, s[16:17]
	s_add_i32 m0, s18, 0x8000
	s_nop 0
	global_load_lds_dwordx4 v1, s[14:15]
	s_add_i32 m0, s18, 0xa000
	s_add_u32 s16, s14, 0x20000
	s_addc_u32 s17, s15, 0
	global_load_lds_dwordx4 v1, s[16:17]
	s_add_i32 m0, s18, 0xc000
	s_add_u32 s16, s14, 0x40000
	s_addc_u32 s17, s15, 0
	global_load_lds_dwordx4 v1, s[16:17]
	s_add_i32 m0, s18, 0xe000
	s_add_u32 s16, s14, 0x60000
	s_addc_u32 s17, s15, 0
	global_load_lds_dwordx4 v1, s[16:17]
	v_mul_f32_e32 v130, 0x3d372713, v126
	v_mul_f32_e32 v131, 0x3d372713, v127
	v_mul_f32_e32 v132, 0x3d372713, v128
	v_mul_f32_e32 v133, 0x3d372713, v129
	v_mul_f32_e32 v130, v126, v130
	v_mul_f32_e32 v131, v127, v131
	v_mul_f32_e32 v132, v128, v132
	v_mul_f32_e32 v133, v129, v133
	v_fma_f32 v130, v126, v130, v126
	v_fma_f32 v131, v127, v131, v127
	v_fma_f32 v132, v128, v132, v128
	v_fma_f32 v133, v129, v133, v129
	v_mul_f32_e32 v130, 0x3f4c422a, v130
	v_mul_f32_e32 v131, 0x3f4c422a, v131
	v_mul_f32_e32 v132, 0x3f4c422a, v132
	v_mul_f32_e32 v133, 0x3f4c422a, v133
	v_mul_f32_e32 v130, -2.0, v130
	v_mul_f32_e32 v131, -2.0, v131
	v_mul_f32_e32 v132, -2.0, v132
	v_mul_f32_e32 v133, -2.0, v133
	v_mul_f32_e32 v130, 0x3fb8aa3b, v130
	v_mul_f32_e32 v131, 0x3fb8aa3b, v131
	v_mul_f32_e32 v132, 0x3fb8aa3b, v132
	v_mul_f32_e32 v133, 0x3fb8aa3b, v133
	v_exp_f32_e32 v130, v130
	v_exp_f32_e32 v131, v131
	v_exp_f32_e32 v132, v132
	v_exp_f32_e32 v133, v133
	v_add_f32_e32 v130, 1.0, v130
	v_add_f32_e32 v131, 1.0, v131
	v_add_f32_e32 v132, 1.0, v132
	v_add_f32_e32 v133, 1.0, v133
	v_rcp_f32_e32 v130, v130
	v_rcp_f32_e32 v131, v131
	v_rcp_f32_e32 v132, v132
	v_rcp_f32_e32 v133, v133
	s_nop 0
	v_mul_f32_e32 v126, v126, v130
	v_mul_f32_e32 v127, v127, v131
	v_mul_f32_e32 v128, v128, v132
	v_mul_f32_e32 v129, v129, v133
	v_cvt_pk_f16_f32 v126, v126, v127
	v_cvt_pk_f16_f32 v127, v128, v129
	global_store_dwordx2 v193, v[126:127], s[22:23] offset:0
	v_mul_f32_e32 v134, 0x3d372713, v122
	v_mul_f32_e32 v135, 0x3d372713, v123
	v_mul_f32_e32 v136, 0x3d372713, v124
	v_mul_f32_e32 v137, 0x3d372713, v125
	v_mul_f32_e32 v134, v122, v134
	v_mul_f32_e32 v135, v123, v135
	v_mul_f32_e32 v136, v124, v136
	v_mul_f32_e32 v137, v125, v137
	v_fma_f32 v134, v122, v134, v122
	v_fma_f32 v135, v123, v135, v123
	v_fma_f32 v136, v124, v136, v124
	v_fma_f32 v137, v125, v137, v125
	v_mul_f32_e32 v134, 0x3f4c422a, v134
	v_mul_f32_e32 v135, 0x3f4c422a, v135
	v_mul_f32_e32 v136, 0x3f4c422a, v136
	v_mul_f32_e32 v137, 0x3f4c422a, v137
	v_mul_f32_e32 v134, -2.0, v134
	v_mul_f32_e32 v135, -2.0, v135
	v_mul_f32_e32 v136, -2.0, v136
	v_mul_f32_e32 v137, -2.0, v137
	v_mul_f32_e32 v134, 0x3fb8aa3b, v134
	v_mul_f32_e32 v135, 0x3fb8aa3b, v135
	v_mul_f32_e32 v136, 0x3fb8aa3b, v136
	v_mul_f32_e32 v137, 0x3fb8aa3b, v137
	v_exp_f32_e32 v134, v134
	v_exp_f32_e32 v135, v135
	v_exp_f32_e32 v136, v136
	v_exp_f32_e32 v137, v137
	v_add_f32_e32 v134, 1.0, v134
	v_add_f32_e32 v135, 1.0, v135
	v_add_f32_e32 v136, 1.0, v136
	v_add_f32_e32 v137, 1.0, v137
	v_rcp_f32_e32 v134, v134
	v_rcp_f32_e32 v135, v135
	v_rcp_f32_e32 v136, v136
	v_rcp_f32_e32 v137, v137
	s_nop 0
	v_mul_f32_e32 v122, v122, v134
	v_mul_f32_e32 v123, v123, v135
	v_mul_f32_e32 v124, v124, v136
	v_mul_f32_e32 v125, v125, v137
	v_cvt_pk_f16_f32 v122, v122, v123
	v_cvt_pk_f16_f32 v123, v124, v125
	global_store_dwordx2 v193, v[122:123], s[22:23] offset:32
	v_mul_f32_e32 v130, 0x3d372713, v118
	v_mul_f32_e32 v131, 0x3d372713, v119
	v_mul_f32_e32 v132, 0x3d372713, v120
	v_mul_f32_e32 v133, 0x3d372713, v121
	v_mul_f32_e32 v130, v118, v130
	v_mul_f32_e32 v131, v119, v131
	v_mul_f32_e32 v132, v120, v132
	v_mul_f32_e32 v133, v121, v133
	v_fma_f32 v130, v118, v130, v118
	v_fma_f32 v131, v119, v131, v119
	v_fma_f32 v132, v120, v132, v120
	v_fma_f32 v133, v121, v133, v121
	v_mul_f32_e32 v130, 0x3f4c422a, v130
	v_mul_f32_e32 v131, 0x3f4c422a, v131
	v_mul_f32_e32 v132, 0x3f4c422a, v132
	v_mul_f32_e32 v133, 0x3f4c422a, v133
	v_mul_f32_e32 v130, -2.0, v130
	v_mul_f32_e32 v131, -2.0, v131
	v_mul_f32_e32 v132, -2.0, v132
	v_mul_f32_e32 v133, -2.0, v133
	v_mul_f32_e32 v130, 0x3fb8aa3b, v130
	v_mul_f32_e32 v131, 0x3fb8aa3b, v131
	v_mul_f32_e32 v132, 0x3fb8aa3b, v132
	v_mul_f32_e32 v133, 0x3fb8aa3b, v133
	v_exp_f32_e32 v130, v130
	v_exp_f32_e32 v131, v131
	v_exp_f32_e32 v132, v132
	v_exp_f32_e32 v133, v133
	v_add_f32_e32 v130, 1.0, v130
	v_add_f32_e32 v131, 1.0, v131
	v_add_f32_e32 v132, 1.0, v132
	v_add_f32_e32 v133, 1.0, v133
	v_rcp_f32_e32 v130, v130
	v_rcp_f32_e32 v131, v131
	v_rcp_f32_e32 v132, v132
	v_rcp_f32_e32 v133, v133
	s_nop 0
	v_mul_f32_e32 v118, v118, v130
	v_mul_f32_e32 v119, v119, v131
	v_mul_f32_e32 v120, v120, v132
	v_mul_f32_e32 v121, v121, v133
	v_cvt_pk_f16_f32 v118, v118, v119
	v_cvt_pk_f16_f32 v119, v120, v121
	global_store_dwordx2 v193, v[118:119], s[22:23] offset:64
	v_mul_f32_e32 v134, 0x3d372713, v114
	v_mul_f32_e32 v135, 0x3d372713, v115
	v_mul_f32_e32 v136, 0x3d372713, v116
	v_mul_f32_e32 v137, 0x3d372713, v117
	v_mul_f32_e32 v134, v114, v134
	v_mul_f32_e32 v135, v115, v135
	v_mul_f32_e32 v136, v116, v136
	v_mul_f32_e32 v137, v117, v137
	v_fma_f32 v134, v114, v134, v114
	v_fma_f32 v135, v115, v135, v115
	v_fma_f32 v136, v116, v136, v116
	v_fma_f32 v137, v117, v137, v117
	v_mul_f32_e32 v134, 0x3f4c422a, v134
	v_mul_f32_e32 v135, 0x3f4c422a, v135
	v_mul_f32_e32 v136, 0x3f4c422a, v136
	v_mul_f32_e32 v137, 0x3f4c422a, v137
	v_mul_f32_e32 v134, -2.0, v134
	v_mul_f32_e32 v135, -2.0, v135
	v_mul_f32_e32 v136, -2.0, v136
	v_mul_f32_e32 v137, -2.0, v137
	v_mul_f32_e32 v134, 0x3fb8aa3b, v134
	v_mul_f32_e32 v135, 0x3fb8aa3b, v135
	v_mul_f32_e32 v136, 0x3fb8aa3b, v136
	v_mul_f32_e32 v137, 0x3fb8aa3b, v137
	v_exp_f32_e32 v134, v134
	v_exp_f32_e32 v135, v135
	v_exp_f32_e32 v136, v136
	v_exp_f32_e32 v137, v137
	v_add_f32_e32 v134, 1.0, v134
	v_add_f32_e32 v135, 1.0, v135
	v_add_f32_e32 v136, 1.0, v136
	v_add_f32_e32 v137, 1.0, v137
	v_rcp_f32_e32 v134, v134
	v_rcp_f32_e32 v135, v135
	v_rcp_f32_e32 v136, v136
	v_rcp_f32_e32 v137, v137
	s_nop 0
	v_mul_f32_e32 v114, v114, v134
	v_mul_f32_e32 v115, v115, v135
	v_mul_f32_e32 v116, v116, v136
	v_mul_f32_e32 v117, v117, v137
	v_cvt_pk_f16_f32 v114, v114, v115
	v_cvt_pk_f16_f32 v115, v116, v117
	global_store_dwordx2 v193, v[114:115], s[22:23] offset:96
	v_add_u32_e32 v193, 0x2000, v193
	v_mul_f32_e32 v130, 0x3d372713, v110
	v_mul_f32_e32 v131, 0x3d372713, v111
	v_mul_f32_e32 v132, 0x3d372713, v112
	v_mul_f32_e32 v133, 0x3d372713, v113
	v_mul_f32_e32 v130, v110, v130
	v_mul_f32_e32 v131, v111, v131
	v_mul_f32_e32 v132, v112, v132
	v_mul_f32_e32 v133, v113, v133
	v_fma_f32 v130, v110, v130, v110
	v_fma_f32 v131, v111, v131, v111
	v_fma_f32 v132, v112, v132, v112
	v_fma_f32 v133, v113, v133, v113
	v_mul_f32_e32 v130, 0x3f4c422a, v130
	v_mul_f32_e32 v131, 0x3f4c422a, v131
	v_mul_f32_e32 v132, 0x3f4c422a, v132
	v_mul_f32_e32 v133, 0x3f4c422a, v133
	v_mul_f32_e32 v130, -2.0, v130
	v_mul_f32_e32 v131, -2.0, v131
	v_mul_f32_e32 v132, -2.0, v132
	v_mul_f32_e32 v133, -2.0, v133
	v_mul_f32_e32 v130, 0x3fb8aa3b, v130
	v_mul_f32_e32 v131, 0x3fb8aa3b, v131
	v_mul_f32_e32 v132, 0x3fb8aa3b, v132
	v_mul_f32_e32 v133, 0x3fb8aa3b, v133
	v_exp_f32_e32 v130, v130
	v_exp_f32_e32 v131, v131
	v_exp_f32_e32 v132, v132
	v_exp_f32_e32 v133, v133
	v_add_f32_e32 v130, 1.0, v130
	v_add_f32_e32 v131, 1.0, v131
	v_add_f32_e32 v132, 1.0, v132
	v_add_f32_e32 v133, 1.0, v133
	v_rcp_f32_e32 v130, v130
	v_rcp_f32_e32 v131, v131
	v_rcp_f32_e32 v132, v132
	v_rcp_f32_e32 v133, v133
	s_nop 0
	v_mul_f32_e32 v110, v110, v130
	v_mul_f32_e32 v111, v111, v131
	v_mul_f32_e32 v112, v112, v132
	v_mul_f32_e32 v113, v113, v133
	v_cvt_pk_f16_f32 v110, v110, v111
	v_cvt_pk_f16_f32 v111, v112, v113
	global_store_dwordx2 v193, v[110:111], s[22:23] offset:0
	v_mul_f32_e32 v134, 0x3d372713, v106
	v_mul_f32_e32 v135, 0x3d372713, v107
	v_mul_f32_e32 v136, 0x3d372713, v108
	v_mul_f32_e32 v137, 0x3d372713, v109
	v_mul_f32_e32 v134, v106, v134
	v_mul_f32_e32 v135, v107, v135
	v_mul_f32_e32 v136, v108, v136
	v_mul_f32_e32 v137, v109, v137
	v_fma_f32 v134, v106, v134, v106
	v_fma_f32 v135, v107, v135, v107
	v_fma_f32 v136, v108, v136, v108
	v_fma_f32 v137, v109, v137, v109
	v_mul_f32_e32 v134, 0x3f4c422a, v134
	v_mul_f32_e32 v135, 0x3f4c422a, v135
	v_mul_f32_e32 v136, 0x3f4c422a, v136
	v_mul_f32_e32 v137, 0x3f4c422a, v137
	v_mul_f32_e32 v134, -2.0, v134
	v_mul_f32_e32 v135, -2.0, v135
	v_mul_f32_e32 v136, -2.0, v136
	v_mul_f32_e32 v137, -2.0, v137
	v_mul_f32_e32 v134, 0x3fb8aa3b, v134
	v_mul_f32_e32 v135, 0x3fb8aa3b, v135
	v_mul_f32_e32 v136, 0x3fb8aa3b, v136
	v_mul_f32_e32 v137, 0x3fb8aa3b, v137
	v_exp_f32_e32 v134, v134
	v_exp_f32_e32 v135, v135
	v_exp_f32_e32 v136, v136
	v_exp_f32_e32 v137, v137
	v_add_f32_e32 v134, 1.0, v134
	v_add_f32_e32 v135, 1.0, v135
	v_add_f32_e32 v136, 1.0, v136
	v_add_f32_e32 v137, 1.0, v137
	v_rcp_f32_e32 v134, v134
	v_rcp_f32_e32 v135, v135
	v_rcp_f32_e32 v136, v136
	v_rcp_f32_e32 v137, v137
	s_nop 0
	v_mul_f32_e32 v106, v106, v134
	v_mul_f32_e32 v107, v107, v135
	v_mul_f32_e32 v108, v108, v136
	v_mul_f32_e32 v109, v109, v137
	v_cvt_pk_f16_f32 v106, v106, v107
	v_cvt_pk_f16_f32 v107, v108, v109
	global_store_dwordx2 v193, v[106:107], s[22:23] offset:32
	v_mul_f32_e32 v130, 0x3d372713, v102
	v_mul_f32_e32 v131, 0x3d372713, v103
	v_mul_f32_e32 v132, 0x3d372713, v104
	v_mul_f32_e32 v133, 0x3d372713, v105
	v_mul_f32_e32 v130, v102, v130
	v_mul_f32_e32 v131, v103, v131
	v_mul_f32_e32 v132, v104, v132
	v_mul_f32_e32 v133, v105, v133
	v_fma_f32 v130, v102, v130, v102
	v_fma_f32 v131, v103, v131, v103
	v_fma_f32 v132, v104, v132, v104
	v_fma_f32 v133, v105, v133, v105
	v_mul_f32_e32 v130, 0x3f4c422a, v130
	v_mul_f32_e32 v131, 0x3f4c422a, v131
	v_mul_f32_e32 v132, 0x3f4c422a, v132
	v_mul_f32_e32 v133, 0x3f4c422a, v133
	v_mul_f32_e32 v130, -2.0, v130
	v_mul_f32_e32 v131, -2.0, v131
	v_mul_f32_e32 v132, -2.0, v132
	v_mul_f32_e32 v133, -2.0, v133
	v_mul_f32_e32 v130, 0x3fb8aa3b, v130
	v_mul_f32_e32 v131, 0x3fb8aa3b, v131
	v_mul_f32_e32 v132, 0x3fb8aa3b, v132
	v_mul_f32_e32 v133, 0x3fb8aa3b, v133
	v_exp_f32_e32 v130, v130
	v_exp_f32_e32 v131, v131
	v_exp_f32_e32 v132, v132
	v_exp_f32_e32 v133, v133
	v_add_f32_e32 v130, 1.0, v130
	v_add_f32_e32 v131, 1.0, v131
	v_add_f32_e32 v132, 1.0, v132
	v_add_f32_e32 v133, 1.0, v133
	v_rcp_f32_e32 v130, v130
	v_rcp_f32_e32 v131, v131
	v_rcp_f32_e32 v132, v132
	v_rcp_f32_e32 v133, v133
	s_nop 0
	v_mul_f32_e32 v102, v102, v130
	v_mul_f32_e32 v103, v103, v131
	v_mul_f32_e32 v104, v104, v132
	v_mul_f32_e32 v105, v105, v133
	v_cvt_pk_f16_f32 v102, v102, v103
	v_cvt_pk_f16_f32 v103, v104, v105
	global_store_dwordx2 v193, v[102:103], s[22:23] offset:64
	v_mul_f32_e32 v134, 0x3d372713, v98
	v_mul_f32_e32 v135, 0x3d372713, v99
	v_mul_f32_e32 v136, 0x3d372713, v100
	v_mul_f32_e32 v137, 0x3d372713, v101
	v_mul_f32_e32 v134, v98, v134
	v_mul_f32_e32 v135, v99, v135
	v_mul_f32_e32 v136, v100, v136
	v_mul_f32_e32 v137, v101, v137
	v_fma_f32 v134, v98, v134, v98
	v_fma_f32 v135, v99, v135, v99
	v_fma_f32 v136, v100, v136, v100
	v_fma_f32 v137, v101, v137, v101
	v_mul_f32_e32 v134, 0x3f4c422a, v134
	v_mul_f32_e32 v135, 0x3f4c422a, v135
	v_mul_f32_e32 v136, 0x3f4c422a, v136
	v_mul_f32_e32 v137, 0x3f4c422a, v137
	v_mul_f32_e32 v134, -2.0, v134
	v_mul_f32_e32 v135, -2.0, v135
	v_mul_f32_e32 v136, -2.0, v136
	v_mul_f32_e32 v137, -2.0, v137
	v_mul_f32_e32 v134, 0x3fb8aa3b, v134
	v_mul_f32_e32 v135, 0x3fb8aa3b, v135
	v_mul_f32_e32 v136, 0x3fb8aa3b, v136
	v_mul_f32_e32 v137, 0x3fb8aa3b, v137
	v_exp_f32_e32 v134, v134
	v_exp_f32_e32 v135, v135
	v_exp_f32_e32 v136, v136
	v_exp_f32_e32 v137, v137
	v_add_f32_e32 v134, 1.0, v134
	v_add_f32_e32 v135, 1.0, v135
	v_add_f32_e32 v136, 1.0, v136
	v_add_f32_e32 v137, 1.0, v137
	v_rcp_f32_e32 v134, v134
	v_rcp_f32_e32 v135, v135
	v_rcp_f32_e32 v136, v136
	v_rcp_f32_e32 v137, v137
	s_nop 0
	v_mul_f32_e32 v98, v98, v134
	v_mul_f32_e32 v99, v99, v135
	v_mul_f32_e32 v100, v100, v136
	v_mul_f32_e32 v101, v101, v137
	v_cvt_pk_f16_f32 v98, v98, v99
	v_cvt_pk_f16_f32 v99, v100, v101
	global_store_dwordx2 v193, v[98:99], s[22:23] offset:96
	v_add_u32_e32 v193, 0x2000, v193
	v_mul_f32_e32 v130, 0x3d372713, v94
	v_mul_f32_e32 v131, 0x3d372713, v95
	v_mul_f32_e32 v132, 0x3d372713, v96
	v_mul_f32_e32 v133, 0x3d372713, v97
	v_mul_f32_e32 v130, v94, v130
	v_mul_f32_e32 v131, v95, v131
	v_mul_f32_e32 v132, v96, v132
	v_mul_f32_e32 v133, v97, v133
	v_fma_f32 v130, v94, v130, v94
	v_fma_f32 v131, v95, v131, v95
	v_fma_f32 v132, v96, v132, v96
	v_fma_f32 v133, v97, v133, v97
	v_mul_f32_e32 v130, 0x3f4c422a, v130
	v_mul_f32_e32 v131, 0x3f4c422a, v131
	v_mul_f32_e32 v132, 0x3f4c422a, v132
	v_mul_f32_e32 v133, 0x3f4c422a, v133
	v_mul_f32_e32 v130, -2.0, v130
	v_mul_f32_e32 v131, -2.0, v131
	v_mul_f32_e32 v132, -2.0, v132
	v_mul_f32_e32 v133, -2.0, v133
	v_mul_f32_e32 v130, 0x3fb8aa3b, v130
	v_mul_f32_e32 v131, 0x3fb8aa3b, v131
	v_mul_f32_e32 v132, 0x3fb8aa3b, v132
	v_mul_f32_e32 v133, 0x3fb8aa3b, v133
	v_exp_f32_e32 v130, v130
	v_exp_f32_e32 v131, v131
	v_exp_f32_e32 v132, v132
	v_exp_f32_e32 v133, v133
	v_add_f32_e32 v130, 1.0, v130
	v_add_f32_e32 v131, 1.0, v131
	v_add_f32_e32 v132, 1.0, v132
	v_add_f32_e32 v133, 1.0, v133
	v_rcp_f32_e32 v130, v130
	v_rcp_f32_e32 v131, v131
	v_rcp_f32_e32 v132, v132
	v_rcp_f32_e32 v133, v133
	s_nop 0
	v_mul_f32_e32 v94, v94, v130
	v_mul_f32_e32 v95, v95, v131
	v_mul_f32_e32 v96, v96, v132
	v_mul_f32_e32 v97, v97, v133
	v_cvt_pk_f16_f32 v94, v94, v95
	v_cvt_pk_f16_f32 v95, v96, v97
	global_store_dwordx2 v193, v[94:95], s[22:23] offset:0
	v_mul_f32_e32 v134, 0x3d372713, v90
	v_mul_f32_e32 v135, 0x3d372713, v91
	v_mul_f32_e32 v136, 0x3d372713, v92
	v_mul_f32_e32 v137, 0x3d372713, v93
	v_mul_f32_e32 v134, v90, v134
	v_mul_f32_e32 v135, v91, v135
	v_mul_f32_e32 v136, v92, v136
	v_mul_f32_e32 v137, v93, v137
	v_fma_f32 v134, v90, v134, v90
	v_fma_f32 v135, v91, v135, v91
	v_fma_f32 v136, v92, v136, v92
	v_fma_f32 v137, v93, v137, v93
	v_mul_f32_e32 v134, 0x3f4c422a, v134
	v_mul_f32_e32 v135, 0x3f4c422a, v135
	v_mul_f32_e32 v136, 0x3f4c422a, v136
	v_mul_f32_e32 v137, 0x3f4c422a, v137
	v_mul_f32_e32 v134, -2.0, v134
	v_mul_f32_e32 v135, -2.0, v135
	v_mul_f32_e32 v136, -2.0, v136
	v_mul_f32_e32 v137, -2.0, v137
	v_mul_f32_e32 v134, 0x3fb8aa3b, v134
	v_mul_f32_e32 v135, 0x3fb8aa3b, v135
	v_mul_f32_e32 v136, 0x3fb8aa3b, v136
	v_mul_f32_e32 v137, 0x3fb8aa3b, v137
	v_exp_f32_e32 v134, v134
	v_exp_f32_e32 v135, v135
	v_exp_f32_e32 v136, v136
	v_exp_f32_e32 v137, v137
	v_add_f32_e32 v134, 1.0, v134
	v_add_f32_e32 v135, 1.0, v135
	v_add_f32_e32 v136, 1.0, v136
	v_add_f32_e32 v137, 1.0, v137
	v_rcp_f32_e32 v134, v134
	v_rcp_f32_e32 v135, v135
	v_rcp_f32_e32 v136, v136
	v_rcp_f32_e32 v137, v137
	s_nop 0
	v_mul_f32_e32 v90, v90, v134
	v_mul_f32_e32 v91, v91, v135
	v_mul_f32_e32 v92, v92, v136
	v_mul_f32_e32 v93, v93, v137
	v_cvt_pk_f16_f32 v90, v90, v91
	v_cvt_pk_f16_f32 v91, v92, v93
	global_store_dwordx2 v193, v[90:91], s[22:23] offset:32
	v_mul_f32_e32 v130, 0x3d372713, v86
	v_mul_f32_e32 v131, 0x3d372713, v87
	v_mul_f32_e32 v132, 0x3d372713, v88
	v_mul_f32_e32 v133, 0x3d372713, v89
	v_mul_f32_e32 v130, v86, v130
	v_mul_f32_e32 v131, v87, v131
	v_mul_f32_e32 v132, v88, v132
	v_mul_f32_e32 v133, v89, v133
	v_fma_f32 v130, v86, v130, v86
	v_fma_f32 v131, v87, v131, v87
	v_fma_f32 v132, v88, v132, v88
	v_fma_f32 v133, v89, v133, v89
	v_mul_f32_e32 v130, 0x3f4c422a, v130
	v_mul_f32_e32 v131, 0x3f4c422a, v131
	v_mul_f32_e32 v132, 0x3f4c422a, v132
	v_mul_f32_e32 v133, 0x3f4c422a, v133
	v_mul_f32_e32 v130, -2.0, v130
	v_mul_f32_e32 v131, -2.0, v131
	v_mul_f32_e32 v132, -2.0, v132
	v_mul_f32_e32 v133, -2.0, v133
	v_mul_f32_e32 v130, 0x3fb8aa3b, v130
	v_mul_f32_e32 v131, 0x3fb8aa3b, v131
	v_mul_f32_e32 v132, 0x3fb8aa3b, v132
	v_mul_f32_e32 v133, 0x3fb8aa3b, v133
	v_exp_f32_e32 v130, v130
	v_exp_f32_e32 v131, v131
	v_exp_f32_e32 v132, v132
	v_exp_f32_e32 v133, v133
	v_add_f32_e32 v130, 1.0, v130
	v_add_f32_e32 v131, 1.0, v131
	v_add_f32_e32 v132, 1.0, v132
	v_add_f32_e32 v133, 1.0, v133
	v_rcp_f32_e32 v130, v130
	v_rcp_f32_e32 v131, v131
	v_rcp_f32_e32 v132, v132
	v_rcp_f32_e32 v133, v133
	s_nop 0
	v_mul_f32_e32 v86, v86, v130
	v_mul_f32_e32 v87, v87, v131
	v_mul_f32_e32 v88, v88, v132
	v_mul_f32_e32 v89, v89, v133
	v_cvt_pk_f16_f32 v86, v86, v87
	v_cvt_pk_f16_f32 v87, v88, v89
	global_store_dwordx2 v193, v[86:87], s[22:23] offset:64
	v_mul_f32_e32 v134, 0x3d372713, v82
	v_mul_f32_e32 v135, 0x3d372713, v83
	v_mul_f32_e32 v136, 0x3d372713, v84
	v_mul_f32_e32 v137, 0x3d372713, v85
	v_mul_f32_e32 v134, v82, v134
	v_mul_f32_e32 v135, v83, v135
	v_mul_f32_e32 v136, v84, v136
	v_mul_f32_e32 v137, v85, v137
	v_fma_f32 v134, v82, v134, v82
	v_fma_f32 v135, v83, v135, v83
	v_fma_f32 v136, v84, v136, v84
	v_fma_f32 v137, v85, v137, v85
	v_mul_f32_e32 v134, 0x3f4c422a, v134
	v_mul_f32_e32 v135, 0x3f4c422a, v135
	v_mul_f32_e32 v136, 0x3f4c422a, v136
	v_mul_f32_e32 v137, 0x3f4c422a, v137
	v_mul_f32_e32 v134, -2.0, v134
	v_mul_f32_e32 v135, -2.0, v135
	v_mul_f32_e32 v136, -2.0, v136
	v_mul_f32_e32 v137, -2.0, v137
	v_mul_f32_e32 v134, 0x3fb8aa3b, v134
	v_mul_f32_e32 v135, 0x3fb8aa3b, v135
	v_mul_f32_e32 v136, 0x3fb8aa3b, v136
	v_mul_f32_e32 v137, 0x3fb8aa3b, v137
	v_exp_f32_e32 v134, v134
	v_exp_f32_e32 v135, v135
	v_exp_f32_e32 v136, v136
	v_exp_f32_e32 v137, v137
	v_add_f32_e32 v134, 1.0, v134
	v_add_f32_e32 v135, 1.0, v135
	v_add_f32_e32 v136, 1.0, v136
	v_add_f32_e32 v137, 1.0, v137
	v_rcp_f32_e32 v134, v134
	v_rcp_f32_e32 v135, v135
	v_rcp_f32_e32 v136, v136
	v_rcp_f32_e32 v137, v137
	s_nop 0
	v_mul_f32_e32 v82, v82, v134
	v_mul_f32_e32 v83, v83, v135
	v_mul_f32_e32 v84, v84, v136
	v_mul_f32_e32 v85, v85, v137
	v_cvt_pk_f16_f32 v82, v82, v83
	v_cvt_pk_f16_f32 v83, v84, v85
	global_store_dwordx2 v193, v[82:83], s[22:23] offset:96
	v_add_u32_e32 v193, 0x2000, v193
	v_mul_f32_e32 v130, 0x3d372713, v78
	v_mul_f32_e32 v131, 0x3d372713, v79
	v_mul_f32_e32 v132, 0x3d372713, v80
	v_mul_f32_e32 v133, 0x3d372713, v81
	v_mul_f32_e32 v130, v78, v130
	v_mul_f32_e32 v131, v79, v131
	v_mul_f32_e32 v132, v80, v132
	v_mul_f32_e32 v133, v81, v133
	v_fma_f32 v130, v78, v130, v78
	v_fma_f32 v131, v79, v131, v79
	v_fma_f32 v132, v80, v132, v80
	v_fma_f32 v133, v81, v133, v81
	v_mul_f32_e32 v130, 0x3f4c422a, v130
	v_mul_f32_e32 v131, 0x3f4c422a, v131
	v_mul_f32_e32 v132, 0x3f4c422a, v132
	v_mul_f32_e32 v133, 0x3f4c422a, v133
	v_mul_f32_e32 v130, -2.0, v130
	v_mul_f32_e32 v131, -2.0, v131
	v_mul_f32_e32 v132, -2.0, v132
	v_mul_f32_e32 v133, -2.0, v133
	v_mul_f32_e32 v130, 0x3fb8aa3b, v130
	v_mul_f32_e32 v131, 0x3fb8aa3b, v131
	v_mul_f32_e32 v132, 0x3fb8aa3b, v132
	v_mul_f32_e32 v133, 0x3fb8aa3b, v133
	v_exp_f32_e32 v130, v130
	v_exp_f32_e32 v131, v131
	v_exp_f32_e32 v132, v132
	v_exp_f32_e32 v133, v133
	v_add_f32_e32 v130, 1.0, v130
	v_add_f32_e32 v131, 1.0, v131
	v_add_f32_e32 v132, 1.0, v132
	v_add_f32_e32 v133, 1.0, v133
	v_rcp_f32_e32 v130, v130
	v_rcp_f32_e32 v131, v131
	v_rcp_f32_e32 v132, v132
	v_rcp_f32_e32 v133, v133
	s_nop 0
	v_mul_f32_e32 v78, v78, v130
	v_mul_f32_e32 v79, v79, v131
	v_mul_f32_e32 v80, v80, v132
	v_mul_f32_e32 v81, v81, v133
	v_cvt_pk_f16_f32 v78, v78, v79
	v_cvt_pk_f16_f32 v79, v80, v81
	global_store_dwordx2 v193, v[78:79], s[22:23] offset:0
	v_mul_f32_e32 v134, 0x3d372713, v74
	v_mul_f32_e32 v135, 0x3d372713, v75
	v_mul_f32_e32 v136, 0x3d372713, v76
	v_mul_f32_e32 v137, 0x3d372713, v77
	v_mul_f32_e32 v134, v74, v134
	v_mul_f32_e32 v135, v75, v135
	v_mul_f32_e32 v136, v76, v136
	v_mul_f32_e32 v137, v77, v137
	v_fma_f32 v134, v74, v134, v74
	v_fma_f32 v135, v75, v135, v75
	v_fma_f32 v136, v76, v136, v76
	v_fma_f32 v137, v77, v137, v77
	v_mul_f32_e32 v134, 0x3f4c422a, v134
	v_mul_f32_e32 v135, 0x3f4c422a, v135
	v_mul_f32_e32 v136, 0x3f4c422a, v136
	v_mul_f32_e32 v137, 0x3f4c422a, v137
	v_mul_f32_e32 v134, -2.0, v134
	v_mul_f32_e32 v135, -2.0, v135
	v_mul_f32_e32 v136, -2.0, v136
	v_mul_f32_e32 v137, -2.0, v137
	v_mul_f32_e32 v134, 0x3fb8aa3b, v134
	v_mul_f32_e32 v135, 0x3fb8aa3b, v135
	v_mul_f32_e32 v136, 0x3fb8aa3b, v136
	v_mul_f32_e32 v137, 0x3fb8aa3b, v137
	v_exp_f32_e32 v134, v134
	v_exp_f32_e32 v135, v135
	v_exp_f32_e32 v136, v136
	v_exp_f32_e32 v137, v137
	v_add_f32_e32 v134, 1.0, v134
	v_add_f32_e32 v135, 1.0, v135
	v_add_f32_e32 v136, 1.0, v136
	v_add_f32_e32 v137, 1.0, v137
	v_rcp_f32_e32 v134, v134
	v_rcp_f32_e32 v135, v135
	v_rcp_f32_e32 v136, v136
	v_rcp_f32_e32 v137, v137
	s_nop 0
	v_mul_f32_e32 v74, v74, v134
	v_mul_f32_e32 v75, v75, v135
	v_mul_f32_e32 v76, v76, v136
	v_mul_f32_e32 v77, v77, v137
	v_cvt_pk_f16_f32 v74, v74, v75
	v_cvt_pk_f16_f32 v75, v76, v77
	global_store_dwordx2 v193, v[74:75], s[22:23] offset:32
	v_mul_f32_e32 v130, 0x3d372713, v70
	v_mul_f32_e32 v131, 0x3d372713, v71
	v_mul_f32_e32 v132, 0x3d372713, v72
	v_mul_f32_e32 v133, 0x3d372713, v73
	v_mul_f32_e32 v130, v70, v130
	v_mul_f32_e32 v131, v71, v131
	v_mul_f32_e32 v132, v72, v132
	v_mul_f32_e32 v133, v73, v133
	v_fma_f32 v130, v70, v130, v70
	v_fma_f32 v131, v71, v131, v71
	v_fma_f32 v132, v72, v132, v72
	v_fma_f32 v133, v73, v133, v73
	v_mul_f32_e32 v130, 0x3f4c422a, v130
	v_mul_f32_e32 v131, 0x3f4c422a, v131
	v_mul_f32_e32 v132, 0x3f4c422a, v132
	v_mul_f32_e32 v133, 0x3f4c422a, v133
	v_mul_f32_e32 v130, -2.0, v130
	v_mul_f32_e32 v131, -2.0, v131
	v_mul_f32_e32 v132, -2.0, v132
	v_mul_f32_e32 v133, -2.0, v133
	v_mul_f32_e32 v130, 0x3fb8aa3b, v130
	v_mul_f32_e32 v131, 0x3fb8aa3b, v131
	v_mul_f32_e32 v132, 0x3fb8aa3b, v132
	v_mul_f32_e32 v133, 0x3fb8aa3b, v133
	v_exp_f32_e32 v130, v130
	v_exp_f32_e32 v131, v131
	v_exp_f32_e32 v132, v132
	v_exp_f32_e32 v133, v133
	v_add_f32_e32 v130, 1.0, v130
	v_add_f32_e32 v131, 1.0, v131
	v_add_f32_e32 v132, 1.0, v132
	v_add_f32_e32 v133, 1.0, v133
	v_rcp_f32_e32 v130, v130
	v_rcp_f32_e32 v131, v131
	v_rcp_f32_e32 v132, v132
	v_rcp_f32_e32 v133, v133
	s_nop 0
	v_mul_f32_e32 v70, v70, v130
	v_mul_f32_e32 v71, v71, v131
	v_mul_f32_e32 v72, v72, v132
	v_mul_f32_e32 v73, v73, v133
	v_cvt_pk_f16_f32 v70, v70, v71
	v_cvt_pk_f16_f32 v71, v72, v73
	global_store_dwordx2 v193, v[70:71], s[22:23] offset:64
	v_mul_f32_e32 v134, 0x3d372713, v66
	v_mul_f32_e32 v135, 0x3d372713, v67
	v_mul_f32_e32 v136, 0x3d372713, v68
	v_mul_f32_e32 v137, 0x3d372713, v69
	v_mul_f32_e32 v134, v66, v134
	v_mul_f32_e32 v135, v67, v135
	v_mul_f32_e32 v136, v68, v136
	v_mul_f32_e32 v137, v69, v137
	v_fma_f32 v134, v66, v134, v66
	v_fma_f32 v135, v67, v135, v67
	v_fma_f32 v136, v68, v136, v68
	v_fma_f32 v137, v69, v137, v69
	v_mul_f32_e32 v134, 0x3f4c422a, v134
	v_mul_f32_e32 v135, 0x3f4c422a, v135
	v_mul_f32_e32 v136, 0x3f4c422a, v136
	v_mul_f32_e32 v137, 0x3f4c422a, v137
	v_mul_f32_e32 v134, -2.0, v134
	v_mul_f32_e32 v135, -2.0, v135
	v_mul_f32_e32 v136, -2.0, v136
	v_mul_f32_e32 v137, -2.0, v137
	v_mul_f32_e32 v134, 0x3fb8aa3b, v134
	v_mul_f32_e32 v135, 0x3fb8aa3b, v135
	v_mul_f32_e32 v136, 0x3fb8aa3b, v136
	v_mul_f32_e32 v137, 0x3fb8aa3b, v137
	v_exp_f32_e32 v134, v134
	v_exp_f32_e32 v135, v135
	v_exp_f32_e32 v136, v136
	v_exp_f32_e32 v137, v137
	v_add_f32_e32 v134, 1.0, v134
	v_add_f32_e32 v135, 1.0, v135
	v_add_f32_e32 v136, 1.0, v136
	v_add_f32_e32 v137, 1.0, v137
	v_rcp_f32_e32 v134, v134
	v_rcp_f32_e32 v135, v135
	v_rcp_f32_e32 v136, v136
	v_rcp_f32_e32 v137, v137
	s_nop 0
	v_mul_f32_e32 v66, v66, v134
	v_mul_f32_e32 v67, v67, v135
	v_mul_f32_e32 v68, v68, v136
	v_mul_f32_e32 v69, v69, v137
	v_cvt_pk_f16_f32 v66, v66, v67
	v_cvt_pk_f16_f32 v67, v68, v69
	global_store_dwordx2 v193, v[66:67], s[22:23] offset:96
	v_add_u32_e32 v193, 0x2000, v193
	v_mul_f32_e32 v130, 0x3d372713, v62
	v_mul_f32_e32 v131, 0x3d372713, v63
	v_mul_f32_e32 v132, 0x3d372713, v64
	v_mul_f32_e32 v133, 0x3d372713, v65
	v_mul_f32_e32 v130, v62, v130
	v_mul_f32_e32 v131, v63, v131
	v_mul_f32_e32 v132, v64, v132
	v_mul_f32_e32 v133, v65, v133
	v_fma_f32 v130, v62, v130, v62
	v_fma_f32 v131, v63, v131, v63
	v_fma_f32 v132, v64, v132, v64
	v_fma_f32 v133, v65, v133, v65
	v_mul_f32_e32 v130, 0x3f4c422a, v130
	v_mul_f32_e32 v131, 0x3f4c422a, v131
	v_mul_f32_e32 v132, 0x3f4c422a, v132
	v_mul_f32_e32 v133, 0x3f4c422a, v133
	v_mul_f32_e32 v130, -2.0, v130
	v_mul_f32_e32 v131, -2.0, v131
	v_mul_f32_e32 v132, -2.0, v132
	v_mul_f32_e32 v133, -2.0, v133
	v_mul_f32_e32 v130, 0x3fb8aa3b, v130
	v_mul_f32_e32 v131, 0x3fb8aa3b, v131
	v_mul_f32_e32 v132, 0x3fb8aa3b, v132
	v_mul_f32_e32 v133, 0x3fb8aa3b, v133
	v_exp_f32_e32 v130, v130
	v_exp_f32_e32 v131, v131
	v_exp_f32_e32 v132, v132
	v_exp_f32_e32 v133, v133
	v_add_f32_e32 v130, 1.0, v130
	v_add_f32_e32 v131, 1.0, v131
	v_add_f32_e32 v132, 1.0, v132
	v_add_f32_e32 v133, 1.0, v133
	v_rcp_f32_e32 v130, v130
	v_rcp_f32_e32 v131, v131
	v_rcp_f32_e32 v132, v132
	v_rcp_f32_e32 v133, v133
	s_nop 0
	v_mul_f32_e32 v62, v62, v130
	v_mul_f32_e32 v63, v63, v131
	v_mul_f32_e32 v64, v64, v132
	v_mul_f32_e32 v65, v65, v133
	v_cvt_pk_f16_f32 v62, v62, v63
	v_cvt_pk_f16_f32 v63, v64, v65
	global_store_dwordx2 v193, v[62:63], s[22:23] offset:0
	v_mul_f32_e32 v134, 0x3d372713, v58
	v_mul_f32_e32 v135, 0x3d372713, v59
	v_mul_f32_e32 v136, 0x3d372713, v60
	v_mul_f32_e32 v137, 0x3d372713, v61
	v_mul_f32_e32 v134, v58, v134
	v_mul_f32_e32 v135, v59, v135
	v_mul_f32_e32 v136, v60, v136
	v_mul_f32_e32 v137, v61, v137
	v_fma_f32 v134, v58, v134, v58
	v_fma_f32 v135, v59, v135, v59
	v_fma_f32 v136, v60, v136, v60
	v_fma_f32 v137, v61, v137, v61
	v_mul_f32_e32 v134, 0x3f4c422a, v134
	v_mul_f32_e32 v135, 0x3f4c422a, v135
	v_mul_f32_e32 v136, 0x3f4c422a, v136
	v_mul_f32_e32 v137, 0x3f4c422a, v137
	v_mul_f32_e32 v134, -2.0, v134
	v_mul_f32_e32 v135, -2.0, v135
	v_mul_f32_e32 v136, -2.0, v136
	v_mul_f32_e32 v137, -2.0, v137
	v_mul_f32_e32 v134, 0x3fb8aa3b, v134
	v_mul_f32_e32 v135, 0x3fb8aa3b, v135
	v_mul_f32_e32 v136, 0x3fb8aa3b, v136
	v_mul_f32_e32 v137, 0x3fb8aa3b, v137
	v_exp_f32_e32 v134, v134
	v_exp_f32_e32 v135, v135
	v_exp_f32_e32 v136, v136
	v_exp_f32_e32 v137, v137
	v_add_f32_e32 v134, 1.0, v134
	v_add_f32_e32 v135, 1.0, v135
	v_add_f32_e32 v136, 1.0, v136
	v_add_f32_e32 v137, 1.0, v137
	v_rcp_f32_e32 v134, v134
	v_rcp_f32_e32 v135, v135
	v_rcp_f32_e32 v136, v136
	v_rcp_f32_e32 v137, v137
	s_nop 0
	v_mul_f32_e32 v58, v58, v134
	v_mul_f32_e32 v59, v59, v135
	v_mul_f32_e32 v60, v60, v136
	v_mul_f32_e32 v61, v61, v137
	v_cvt_pk_f16_f32 v58, v58, v59
	v_cvt_pk_f16_f32 v59, v60, v61
	global_store_dwordx2 v193, v[58:59], s[22:23] offset:32
	v_mul_f32_e32 v130, 0x3d372713, v54
	v_mul_f32_e32 v131, 0x3d372713, v55
	v_mul_f32_e32 v132, 0x3d372713, v56
	v_mul_f32_e32 v133, 0x3d372713, v57
	v_mul_f32_e32 v130, v54, v130
	v_mul_f32_e32 v131, v55, v131
	v_mul_f32_e32 v132, v56, v132
	v_mul_f32_e32 v133, v57, v133
	v_fma_f32 v130, v54, v130, v54
	v_fma_f32 v131, v55, v131, v55
	v_fma_f32 v132, v56, v132, v56
	v_fma_f32 v133, v57, v133, v57
	v_mul_f32_e32 v130, 0x3f4c422a, v130
	v_mul_f32_e32 v131, 0x3f4c422a, v131
	v_mul_f32_e32 v132, 0x3f4c422a, v132
	v_mul_f32_e32 v133, 0x3f4c422a, v133
	v_mul_f32_e32 v130, -2.0, v130
	v_mul_f32_e32 v131, -2.0, v131
	v_mul_f32_e32 v132, -2.0, v132
	v_mul_f32_e32 v133, -2.0, v133
	v_mul_f32_e32 v130, 0x3fb8aa3b, v130
	v_mul_f32_e32 v131, 0x3fb8aa3b, v131
	v_mul_f32_e32 v132, 0x3fb8aa3b, v132
	v_mul_f32_e32 v133, 0x3fb8aa3b, v133
	v_exp_f32_e32 v130, v130
	v_exp_f32_e32 v131, v131
	v_exp_f32_e32 v132, v132
	v_exp_f32_e32 v133, v133
	v_add_f32_e32 v130, 1.0, v130
	v_add_f32_e32 v131, 1.0, v131
	v_add_f32_e32 v132, 1.0, v132
	v_add_f32_e32 v133, 1.0, v133
	v_rcp_f32_e32 v130, v130
	v_rcp_f32_e32 v131, v131
	v_rcp_f32_e32 v132, v132
	v_rcp_f32_e32 v133, v133
	s_nop 0
	v_mul_f32_e32 v54, v54, v130
	v_mul_f32_e32 v55, v55, v131
	v_mul_f32_e32 v56, v56, v132
	v_mul_f32_e32 v57, v57, v133
	v_cvt_pk_f16_f32 v54, v54, v55
	v_cvt_pk_f16_f32 v55, v56, v57
	global_store_dwordx2 v193, v[54:55], s[22:23] offset:64
	v_mul_f32_e32 v134, 0x3d372713, v50
	v_mul_f32_e32 v135, 0x3d372713, v51
	v_mul_f32_e32 v136, 0x3d372713, v52
	v_mul_f32_e32 v137, 0x3d372713, v53
	v_mul_f32_e32 v134, v50, v134
	v_mul_f32_e32 v135, v51, v135
	v_mul_f32_e32 v136, v52, v136
	v_mul_f32_e32 v137, v53, v137
	v_fma_f32 v134, v50, v134, v50
	v_fma_f32 v135, v51, v135, v51
	v_fma_f32 v136, v52, v136, v52
	v_fma_f32 v137, v53, v137, v53
	v_mul_f32_e32 v134, 0x3f4c422a, v134
	v_mul_f32_e32 v135, 0x3f4c422a, v135
	v_mul_f32_e32 v136, 0x3f4c422a, v136
	v_mul_f32_e32 v137, 0x3f4c422a, v137
	v_mul_f32_e32 v134, -2.0, v134
	v_mul_f32_e32 v135, -2.0, v135
	v_mul_f32_e32 v136, -2.0, v136
	v_mul_f32_e32 v137, -2.0, v137
	v_mul_f32_e32 v134, 0x3fb8aa3b, v134
	v_mul_f32_e32 v135, 0x3fb8aa3b, v135
	v_mul_f32_e32 v136, 0x3fb8aa3b, v136
	v_mul_f32_e32 v137, 0x3fb8aa3b, v137
	v_exp_f32_e32 v134, v134
	v_exp_f32_e32 v135, v135
	v_exp_f32_e32 v136, v136
	v_exp_f32_e32 v137, v137
	v_add_f32_e32 v134, 1.0, v134
	v_add_f32_e32 v135, 1.0, v135
	v_add_f32_e32 v136, 1.0, v136
	v_add_f32_e32 v137, 1.0, v137
	v_rcp_f32_e32 v134, v134
	v_rcp_f32_e32 v135, v135
	v_rcp_f32_e32 v136, v136
	v_rcp_f32_e32 v137, v137
	s_nop 0
	v_mul_f32_e32 v50, v50, v134
	v_mul_f32_e32 v51, v51, v135
	v_mul_f32_e32 v52, v52, v136
	v_mul_f32_e32 v53, v53, v137
	v_cvt_pk_f16_f32 v50, v50, v51
	v_cvt_pk_f16_f32 v51, v52, v53
	global_store_dwordx2 v193, v[50:51], s[22:23] offset:96
	v_add_u32_e32 v193, 0x2000, v193
	v_mul_f32_e32 v130, 0x3d372713, v46
	v_mul_f32_e32 v131, 0x3d372713, v47
	v_mul_f32_e32 v132, 0x3d372713, v48
	v_mul_f32_e32 v133, 0x3d372713, v49
	v_mul_f32_e32 v130, v46, v130
	v_mul_f32_e32 v131, v47, v131
	v_mul_f32_e32 v132, v48, v132
	v_mul_f32_e32 v133, v49, v133
	v_fma_f32 v130, v46, v130, v46
	v_fma_f32 v131, v47, v131, v47
	v_fma_f32 v132, v48, v132, v48
	v_fma_f32 v133, v49, v133, v49
	v_mul_f32_e32 v130, 0x3f4c422a, v130
	v_mul_f32_e32 v131, 0x3f4c422a, v131
	v_mul_f32_e32 v132, 0x3f4c422a, v132
	v_mul_f32_e32 v133, 0x3f4c422a, v133
	v_mul_f32_e32 v130, -2.0, v130
	v_mul_f32_e32 v131, -2.0, v131
	v_mul_f32_e32 v132, -2.0, v132
	v_mul_f32_e32 v133, -2.0, v133
	v_mul_f32_e32 v130, 0x3fb8aa3b, v130
	v_mul_f32_e32 v131, 0x3fb8aa3b, v131
	v_mul_f32_e32 v132, 0x3fb8aa3b, v132
	v_mul_f32_e32 v133, 0x3fb8aa3b, v133
	v_exp_f32_e32 v130, v130
	v_exp_f32_e32 v131, v131
	v_exp_f32_e32 v132, v132
	v_exp_f32_e32 v133, v133
	v_add_f32_e32 v130, 1.0, v130
	v_add_f32_e32 v131, 1.0, v131
	v_add_f32_e32 v132, 1.0, v132
	v_add_f32_e32 v133, 1.0, v133
	v_rcp_f32_e32 v130, v130
	v_rcp_f32_e32 v131, v131
	v_rcp_f32_e32 v132, v132
	v_rcp_f32_e32 v133, v133
	s_nop 0
	v_mul_f32_e32 v46, v46, v130
	v_mul_f32_e32 v47, v47, v131
	v_mul_f32_e32 v48, v48, v132
	v_mul_f32_e32 v49, v49, v133
	v_cvt_pk_f16_f32 v46, v46, v47
	v_cvt_pk_f16_f32 v47, v48, v49
	global_store_dwordx2 v193, v[46:47], s[22:23] offset:0
	v_mul_f32_e32 v134, 0x3d372713, v42
	v_mul_f32_e32 v135, 0x3d372713, v43
	v_mul_f32_e32 v136, 0x3d372713, v44
	v_mul_f32_e32 v137, 0x3d372713, v45
	v_mul_f32_e32 v134, v42, v134
	v_mul_f32_e32 v135, v43, v135
	v_mul_f32_e32 v136, v44, v136
	v_mul_f32_e32 v137, v45, v137
	v_fma_f32 v134, v42, v134, v42
	v_fma_f32 v135, v43, v135, v43
	v_fma_f32 v136, v44, v136, v44
	v_fma_f32 v137, v45, v137, v45
	v_mul_f32_e32 v134, 0x3f4c422a, v134
	v_mul_f32_e32 v135, 0x3f4c422a, v135
	v_mul_f32_e32 v136, 0x3f4c422a, v136
	v_mul_f32_e32 v137, 0x3f4c422a, v137
	v_mul_f32_e32 v134, -2.0, v134
	v_mul_f32_e32 v135, -2.0, v135
	v_mul_f32_e32 v136, -2.0, v136
	v_mul_f32_e32 v137, -2.0, v137
	v_mul_f32_e32 v134, 0x3fb8aa3b, v134
	v_mul_f32_e32 v135, 0x3fb8aa3b, v135
	v_mul_f32_e32 v136, 0x3fb8aa3b, v136
	v_mul_f32_e32 v137, 0x3fb8aa3b, v137
	v_exp_f32_e32 v134, v134
	v_exp_f32_e32 v135, v135
	v_exp_f32_e32 v136, v136
	v_exp_f32_e32 v137, v137
	v_add_f32_e32 v134, 1.0, v134
	v_add_f32_e32 v135, 1.0, v135
	v_add_f32_e32 v136, 1.0, v136
	v_add_f32_e32 v137, 1.0, v137
	v_rcp_f32_e32 v134, v134
	v_rcp_f32_e32 v135, v135
	v_rcp_f32_e32 v136, v136
	v_rcp_f32_e32 v137, v137
	s_nop 0
	v_mul_f32_e32 v42, v42, v134
	v_mul_f32_e32 v43, v43, v135
	v_mul_f32_e32 v44, v44, v136
	v_mul_f32_e32 v45, v45, v137
	v_cvt_pk_f16_f32 v42, v42, v43
	v_cvt_pk_f16_f32 v43, v44, v45
	global_store_dwordx2 v193, v[42:43], s[22:23] offset:32
	v_mul_f32_e32 v130, 0x3d372713, v38
	v_mul_f32_e32 v131, 0x3d372713, v39
	v_mul_f32_e32 v132, 0x3d372713, v40
	v_mul_f32_e32 v133, 0x3d372713, v41
	v_mul_f32_e32 v130, v38, v130
	v_mul_f32_e32 v131, v39, v131
	v_mul_f32_e32 v132, v40, v132
	v_mul_f32_e32 v133, v41, v133
	v_fma_f32 v130, v38, v130, v38
	v_fma_f32 v131, v39, v131, v39
	v_fma_f32 v132, v40, v132, v40
	v_fma_f32 v133, v41, v133, v41
	v_mul_f32_e32 v130, 0x3f4c422a, v130
	v_mul_f32_e32 v131, 0x3f4c422a, v131
	v_mul_f32_e32 v132, 0x3f4c422a, v132
	v_mul_f32_e32 v133, 0x3f4c422a, v133
	v_mul_f32_e32 v130, -2.0, v130
	v_mul_f32_e32 v131, -2.0, v131
	v_mul_f32_e32 v132, -2.0, v132
	v_mul_f32_e32 v133, -2.0, v133
	v_mul_f32_e32 v130, 0x3fb8aa3b, v130
	v_mul_f32_e32 v131, 0x3fb8aa3b, v131
	v_mul_f32_e32 v132, 0x3fb8aa3b, v132
	v_mul_f32_e32 v133, 0x3fb8aa3b, v133
	v_exp_f32_e32 v130, v130
	v_exp_f32_e32 v131, v131
	v_exp_f32_e32 v132, v132
	v_exp_f32_e32 v133, v133
	v_add_f32_e32 v130, 1.0, v130
	v_add_f32_e32 v131, 1.0, v131
	v_add_f32_e32 v132, 1.0, v132
	v_add_f32_e32 v133, 1.0, v133
	v_rcp_f32_e32 v130, v130
	v_rcp_f32_e32 v131, v131
	v_rcp_f32_e32 v132, v132
	v_rcp_f32_e32 v133, v133
	s_nop 0
	v_mul_f32_e32 v38, v38, v130
	v_mul_f32_e32 v39, v39, v131
	v_mul_f32_e32 v40, v40, v132
	v_mul_f32_e32 v41, v41, v133
	v_cvt_pk_f16_f32 v38, v38, v39
	v_cvt_pk_f16_f32 v39, v40, v41
	global_store_dwordx2 v193, v[38:39], s[22:23] offset:64
	v_mul_f32_e32 v134, 0x3d372713, v34
	v_mul_f32_e32 v135, 0x3d372713, v35
	v_mul_f32_e32 v136, 0x3d372713, v36
	v_mul_f32_e32 v137, 0x3d372713, v37
	v_mul_f32_e32 v134, v34, v134
	v_mul_f32_e32 v135, v35, v135
	v_mul_f32_e32 v136, v36, v136
	v_mul_f32_e32 v137, v37, v137
	v_fma_f32 v134, v34, v134, v34
	v_fma_f32 v135, v35, v135, v35
	v_fma_f32 v136, v36, v136, v36
	v_fma_f32 v137, v37, v137, v37
	v_mul_f32_e32 v134, 0x3f4c422a, v134
	v_mul_f32_e32 v135, 0x3f4c422a, v135
	v_mul_f32_e32 v136, 0x3f4c422a, v136
	v_mul_f32_e32 v137, 0x3f4c422a, v137
	v_mul_f32_e32 v134, -2.0, v134
	v_mul_f32_e32 v135, -2.0, v135
	v_mul_f32_e32 v136, -2.0, v136
	v_mul_f32_e32 v137, -2.0, v137
	v_mul_f32_e32 v134, 0x3fb8aa3b, v134
	v_mul_f32_e32 v135, 0x3fb8aa3b, v135
	v_mul_f32_e32 v136, 0x3fb8aa3b, v136
	v_mul_f32_e32 v137, 0x3fb8aa3b, v137
	v_exp_f32_e32 v134, v134
	v_exp_f32_e32 v135, v135
	v_exp_f32_e32 v136, v136
	v_exp_f32_e32 v137, v137
	v_add_f32_e32 v134, 1.0, v134
	v_add_f32_e32 v135, 1.0, v135
	v_add_f32_e32 v136, 1.0, v136
	v_add_f32_e32 v137, 1.0, v137
	v_rcp_f32_e32 v134, v134
	v_rcp_f32_e32 v135, v135
	v_rcp_f32_e32 v136, v136
	v_rcp_f32_e32 v137, v137
	s_nop 0
	v_mul_f32_e32 v34, v34, v134
	v_mul_f32_e32 v35, v35, v135
	v_mul_f32_e32 v36, v36, v136
	v_mul_f32_e32 v37, v37, v137
	v_cvt_pk_f16_f32 v34, v34, v35
	v_cvt_pk_f16_f32 v35, v36, v37
	global_store_dwordx2 v193, v[34:35], s[22:23] offset:96
	v_add_u32_e32 v193, 0x2000, v193
	v_mul_f32_e32 v130, 0x3d372713, v30
	v_mul_f32_e32 v131, 0x3d372713, v31
	v_mul_f32_e32 v132, 0x3d372713, v32
	v_mul_f32_e32 v133, 0x3d372713, v33
	v_mul_f32_e32 v130, v30, v130
	v_mul_f32_e32 v131, v31, v131
	v_mul_f32_e32 v132, v32, v132
	v_mul_f32_e32 v133, v33, v133
	v_fma_f32 v130, v30, v130, v30
	v_fma_f32 v131, v31, v131, v31
	v_fma_f32 v132, v32, v132, v32
	v_fma_f32 v133, v33, v133, v33
	v_mul_f32_e32 v130, 0x3f4c422a, v130
	v_mul_f32_e32 v131, 0x3f4c422a, v131
	v_mul_f32_e32 v132, 0x3f4c422a, v132
	v_mul_f32_e32 v133, 0x3f4c422a, v133
	v_mul_f32_e32 v130, -2.0, v130
	v_mul_f32_e32 v131, -2.0, v131
	v_mul_f32_e32 v132, -2.0, v132
	v_mul_f32_e32 v133, -2.0, v133
	v_mul_f32_e32 v130, 0x3fb8aa3b, v130
	v_mul_f32_e32 v131, 0x3fb8aa3b, v131
	v_mul_f32_e32 v132, 0x3fb8aa3b, v132
	v_mul_f32_e32 v133, 0x3fb8aa3b, v133
	v_exp_f32_e32 v130, v130
	v_exp_f32_e32 v131, v131
	v_exp_f32_e32 v132, v132
	v_exp_f32_e32 v133, v133
	v_add_f32_e32 v130, 1.0, v130
	v_add_f32_e32 v131, 1.0, v131
	v_add_f32_e32 v132, 1.0, v132
	v_add_f32_e32 v133, 1.0, v133
	v_rcp_f32_e32 v130, v130
	v_rcp_f32_e32 v131, v131
	v_rcp_f32_e32 v132, v132
	v_rcp_f32_e32 v133, v133
	s_nop 0
	v_mul_f32_e32 v30, v30, v130
	v_mul_f32_e32 v31, v31, v131
	v_mul_f32_e32 v32, v32, v132
	v_mul_f32_e32 v33, v33, v133
	v_cvt_pk_f16_f32 v30, v30, v31
	v_cvt_pk_f16_f32 v31, v32, v33
	global_store_dwordx2 v193, v[30:31], s[22:23] offset:0
	v_mul_f32_e32 v134, 0x3d372713, v26
	v_mul_f32_e32 v135, 0x3d372713, v27
	v_mul_f32_e32 v136, 0x3d372713, v28
	v_mul_f32_e32 v137, 0x3d372713, v29
	v_mul_f32_e32 v134, v26, v134
	v_mul_f32_e32 v135, v27, v135
	v_mul_f32_e32 v136, v28, v136
	v_mul_f32_e32 v137, v29, v137
	v_fma_f32 v134, v26, v134, v26
	v_fma_f32 v135, v27, v135, v27
	v_fma_f32 v136, v28, v136, v28
	v_fma_f32 v137, v29, v137, v29
	v_mul_f32_e32 v134, 0x3f4c422a, v134
	v_mul_f32_e32 v135, 0x3f4c422a, v135
	v_mul_f32_e32 v136, 0x3f4c422a, v136
	v_mul_f32_e32 v137, 0x3f4c422a, v137
	v_mul_f32_e32 v134, -2.0, v134
	v_mul_f32_e32 v135, -2.0, v135
	v_mul_f32_e32 v136, -2.0, v136
	v_mul_f32_e32 v137, -2.0, v137
	v_mul_f32_e32 v134, 0x3fb8aa3b, v134
	v_mul_f32_e32 v135, 0x3fb8aa3b, v135
	v_mul_f32_e32 v136, 0x3fb8aa3b, v136
	v_mul_f32_e32 v137, 0x3fb8aa3b, v137
	v_exp_f32_e32 v134, v134
	v_exp_f32_e32 v135, v135
	v_exp_f32_e32 v136, v136
	v_exp_f32_e32 v137, v137
	v_add_f32_e32 v134, 1.0, v134
	v_add_f32_e32 v135, 1.0, v135
	v_add_f32_e32 v136, 1.0, v136
	v_add_f32_e32 v137, 1.0, v137
	v_rcp_f32_e32 v134, v134
	v_rcp_f32_e32 v135, v135
	v_rcp_f32_e32 v136, v136
	v_rcp_f32_e32 v137, v137
	s_nop 0
	v_mul_f32_e32 v26, v26, v134
	v_mul_f32_e32 v27, v27, v135
	v_mul_f32_e32 v28, v28, v136
	v_mul_f32_e32 v29, v29, v137
	v_cvt_pk_f16_f32 v26, v26, v27
	v_cvt_pk_f16_f32 v27, v28, v29
	global_store_dwordx2 v193, v[26:27], s[22:23] offset:32
	v_mul_f32_e32 v130, 0x3d372713, v22
	v_mul_f32_e32 v131, 0x3d372713, v23
	v_mul_f32_e32 v132, 0x3d372713, v24
	v_mul_f32_e32 v133, 0x3d372713, v25
	v_mul_f32_e32 v130, v22, v130
	v_mul_f32_e32 v131, v23, v131
	v_mul_f32_e32 v132, v24, v132
	v_mul_f32_e32 v133, v25, v133
	v_fma_f32 v130, v22, v130, v22
	v_fma_f32 v131, v23, v131, v23
	v_fma_f32 v132, v24, v132, v24
	v_fma_f32 v133, v25, v133, v25
	v_mul_f32_e32 v130, 0x3f4c422a, v130
	v_mul_f32_e32 v131, 0x3f4c422a, v131
	v_mul_f32_e32 v132, 0x3f4c422a, v132
	v_mul_f32_e32 v133, 0x3f4c422a, v133
	v_mul_f32_e32 v130, -2.0, v130
	v_mul_f32_e32 v131, -2.0, v131
	v_mul_f32_e32 v132, -2.0, v132
	v_mul_f32_e32 v133, -2.0, v133
	v_mul_f32_e32 v130, 0x3fb8aa3b, v130
	v_mul_f32_e32 v131, 0x3fb8aa3b, v131
	v_mul_f32_e32 v132, 0x3fb8aa3b, v132
	v_mul_f32_e32 v133, 0x3fb8aa3b, v133
	v_exp_f32_e32 v130, v130
	v_exp_f32_e32 v131, v131
	v_exp_f32_e32 v132, v132
	v_exp_f32_e32 v133, v133
	v_add_f32_e32 v130, 1.0, v130
	v_add_f32_e32 v131, 1.0, v131
	v_add_f32_e32 v132, 1.0, v132
	v_add_f32_e32 v133, 1.0, v133
	v_rcp_f32_e32 v130, v130
	v_rcp_f32_e32 v131, v131
	v_rcp_f32_e32 v132, v132
	v_rcp_f32_e32 v133, v133
	s_nop 0
	v_mul_f32_e32 v22, v22, v130
	v_mul_f32_e32 v23, v23, v131
	v_mul_f32_e32 v24, v24, v132
	v_mul_f32_e32 v25, v25, v133
	v_cvt_pk_f16_f32 v22, v22, v23
	v_cvt_pk_f16_f32 v23, v24, v25
	global_store_dwordx2 v193, v[22:23], s[22:23] offset:64
	v_mul_f32_e32 v134, 0x3d372713, v18
	v_mul_f32_e32 v135, 0x3d372713, v19
	v_mul_f32_e32 v136, 0x3d372713, v20
	v_mul_f32_e32 v137, 0x3d372713, v21
	v_mul_f32_e32 v134, v18, v134
	v_mul_f32_e32 v135, v19, v135
	v_mul_f32_e32 v136, v20, v136
	v_mul_f32_e32 v137, v21, v137
	v_fma_f32 v134, v18, v134, v18
	v_fma_f32 v135, v19, v135, v19
	v_fma_f32 v136, v20, v136, v20
	v_fma_f32 v137, v21, v137, v21
	v_mul_f32_e32 v134, 0x3f4c422a, v134
	v_mul_f32_e32 v135, 0x3f4c422a, v135
	v_mul_f32_e32 v136, 0x3f4c422a, v136
	v_mul_f32_e32 v137, 0x3f4c422a, v137
	v_mul_f32_e32 v134, -2.0, v134
	v_mul_f32_e32 v135, -2.0, v135
	v_mul_f32_e32 v136, -2.0, v136
	v_mul_f32_e32 v137, -2.0, v137
	v_mul_f32_e32 v134, 0x3fb8aa3b, v134
	v_mul_f32_e32 v135, 0x3fb8aa3b, v135
	v_mul_f32_e32 v136, 0x3fb8aa3b, v136
	v_mul_f32_e32 v137, 0x3fb8aa3b, v137
	v_exp_f32_e32 v134, v134
	v_exp_f32_e32 v135, v135
	v_exp_f32_e32 v136, v136
	v_exp_f32_e32 v137, v137
	v_add_f32_e32 v134, 1.0, v134
	v_add_f32_e32 v135, 1.0, v135
	v_add_f32_e32 v136, 1.0, v136
	v_add_f32_e32 v137, 1.0, v137
	v_rcp_f32_e32 v134, v134
	v_rcp_f32_e32 v135, v135
	v_rcp_f32_e32 v136, v136
	v_rcp_f32_e32 v137, v137
	s_nop 0
	v_mul_f32_e32 v18, v18, v134
	v_mul_f32_e32 v19, v19, v135
	v_mul_f32_e32 v20, v20, v136
	v_mul_f32_e32 v21, v21, v137
	v_cvt_pk_f16_f32 v18, v18, v19
	v_cvt_pk_f16_f32 v19, v20, v21
	global_store_dwordx2 v193, v[18:19], s[22:23] offset:96
	v_add_u32_e32 v193, 0x2000, v193
	v_mul_f32_e32 v130, 0x3d372713, v14
	v_mul_f32_e32 v131, 0x3d372713, v15
	v_mul_f32_e32 v132, 0x3d372713, v16
	v_mul_f32_e32 v133, 0x3d372713, v17
	v_mul_f32_e32 v130, v14, v130
	v_mul_f32_e32 v131, v15, v131
	v_mul_f32_e32 v132, v16, v132
	v_mul_f32_e32 v133, v17, v133
	v_fma_f32 v130, v14, v130, v14
	v_fma_f32 v131, v15, v131, v15
	v_fma_f32 v132, v16, v132, v16
	v_fma_f32 v133, v17, v133, v17
	v_mul_f32_e32 v130, 0x3f4c422a, v130
	v_mul_f32_e32 v131, 0x3f4c422a, v131
	v_mul_f32_e32 v132, 0x3f4c422a, v132
	v_mul_f32_e32 v133, 0x3f4c422a, v133
	v_mul_f32_e32 v130, -2.0, v130
	v_mul_f32_e32 v131, -2.0, v131
	v_mul_f32_e32 v132, -2.0, v132
	v_mul_f32_e32 v133, -2.0, v133
	v_mul_f32_e32 v130, 0x3fb8aa3b, v130
	v_mul_f32_e32 v131, 0x3fb8aa3b, v131
	v_mul_f32_e32 v132, 0x3fb8aa3b, v132
	v_mul_f32_e32 v133, 0x3fb8aa3b, v133
	v_exp_f32_e32 v130, v130
	v_exp_f32_e32 v131, v131
	v_exp_f32_e32 v132, v132
	v_exp_f32_e32 v133, v133
	v_add_f32_e32 v130, 1.0, v130
	v_add_f32_e32 v131, 1.0, v131
	v_add_f32_e32 v132, 1.0, v132
	v_add_f32_e32 v133, 1.0, v133
	v_rcp_f32_e32 v130, v130
	v_rcp_f32_e32 v131, v131
	v_rcp_f32_e32 v132, v132
	v_rcp_f32_e32 v133, v133
	s_nop 0
	v_mul_f32_e32 v14, v14, v130
	v_mul_f32_e32 v15, v15, v131
	v_mul_f32_e32 v16, v16, v132
	v_mul_f32_e32 v17, v17, v133
	v_cvt_pk_f16_f32 v14, v14, v15
	v_cvt_pk_f16_f32 v15, v16, v17
	global_store_dwordx2 v193, v[14:15], s[22:23] offset:0
	v_mul_f32_e32 v134, 0x3d372713, v10
	v_mul_f32_e32 v135, 0x3d372713, v11
	v_mul_f32_e32 v136, 0x3d372713, v12
	v_mul_f32_e32 v137, 0x3d372713, v13
	v_mul_f32_e32 v134, v10, v134
	v_mul_f32_e32 v135, v11, v135
	v_mul_f32_e32 v136, v12, v136
	v_mul_f32_e32 v137, v13, v137
	v_fma_f32 v134, v10, v134, v10
	v_fma_f32 v135, v11, v135, v11
	v_fma_f32 v136, v12, v136, v12
	v_fma_f32 v137, v13, v137, v13
	v_mul_f32_e32 v134, 0x3f4c422a, v134
	v_mul_f32_e32 v135, 0x3f4c422a, v135
	v_mul_f32_e32 v136, 0x3f4c422a, v136
	v_mul_f32_e32 v137, 0x3f4c422a, v137
	v_mul_f32_e32 v134, -2.0, v134
	v_mul_f32_e32 v135, -2.0, v135
	v_mul_f32_e32 v136, -2.0, v136
	v_mul_f32_e32 v137, -2.0, v137
	v_mul_f32_e32 v134, 0x3fb8aa3b, v134
	v_mul_f32_e32 v135, 0x3fb8aa3b, v135
	v_mul_f32_e32 v136, 0x3fb8aa3b, v136
	v_mul_f32_e32 v137, 0x3fb8aa3b, v137
	v_exp_f32_e32 v134, v134
	v_exp_f32_e32 v135, v135
	v_exp_f32_e32 v136, v136
	v_exp_f32_e32 v137, v137
	v_add_f32_e32 v134, 1.0, v134
	v_add_f32_e32 v135, 1.0, v135
	v_add_f32_e32 v136, 1.0, v136
	v_add_f32_e32 v137, 1.0, v137
	v_rcp_f32_e32 v134, v134
	v_rcp_f32_e32 v135, v135
	v_rcp_f32_e32 v136, v136
	v_rcp_f32_e32 v137, v137
	s_nop 0
	v_mul_f32_e32 v10, v10, v134
	v_mul_f32_e32 v11, v11, v135
	v_mul_f32_e32 v12, v12, v136
	v_mul_f32_e32 v13, v13, v137
	v_cvt_pk_f16_f32 v10, v10, v11
	v_cvt_pk_f16_f32 v11, v12, v13
	global_store_dwordx2 v193, v[10:11], s[22:23] offset:32
	v_mul_f32_e32 v130, 0x3d372713, v6
	v_mul_f32_e32 v131, 0x3d372713, v7
	v_mul_f32_e32 v132, 0x3d372713, v8
	v_mul_f32_e32 v133, 0x3d372713, v9
	v_mul_f32_e32 v130, v6, v130
	v_mul_f32_e32 v131, v7, v131
	v_mul_f32_e32 v132, v8, v132
	v_mul_f32_e32 v133, v9, v133
	v_fma_f32 v130, v6, v130, v6
	v_fma_f32 v131, v7, v131, v7
	v_fma_f32 v132, v8, v132, v8
	v_fma_f32 v133, v9, v133, v9
	v_mul_f32_e32 v130, 0x3f4c422a, v130
	v_mul_f32_e32 v131, 0x3f4c422a, v131
	v_mul_f32_e32 v132, 0x3f4c422a, v132
	v_mul_f32_e32 v133, 0x3f4c422a, v133
	v_mul_f32_e32 v130, -2.0, v130
	v_mul_f32_e32 v131, -2.0, v131
	v_mul_f32_e32 v132, -2.0, v132
	v_mul_f32_e32 v133, -2.0, v133
	v_mul_f32_e32 v130, 0x3fb8aa3b, v130
	v_mul_f32_e32 v131, 0x3fb8aa3b, v131
	v_mul_f32_e32 v132, 0x3fb8aa3b, v132
	v_mul_f32_e32 v133, 0x3fb8aa3b, v133
	v_exp_f32_e32 v130, v130
	v_exp_f32_e32 v131, v131
	v_exp_f32_e32 v132, v132
	v_exp_f32_e32 v133, v133
	v_add_f32_e32 v130, 1.0, v130
	v_add_f32_e32 v131, 1.0, v131
	v_add_f32_e32 v132, 1.0, v132
	v_add_f32_e32 v133, 1.0, v133
	v_rcp_f32_e32 v130, v130
	v_rcp_f32_e32 v131, v131
	v_rcp_f32_e32 v132, v132
	v_rcp_f32_e32 v133, v133
	s_nop 0
	v_mul_f32_e32 v6, v6, v130
	v_mul_f32_e32 v7, v7, v131
	v_mul_f32_e32 v8, v8, v132
	v_mul_f32_e32 v9, v9, v133
	v_cvt_pk_f16_f32 v6, v6, v7
	v_cvt_pk_f16_f32 v7, v8, v9
	global_store_dwordx2 v193, v[6:7], s[22:23] offset:64
	v_mul_f32_e32 v134, 0x3d372713, v2
	v_mul_f32_e32 v135, 0x3d372713, v3
	v_mul_f32_e32 v136, 0x3d372713, v4
	v_mul_f32_e32 v137, 0x3d372713, v5
	v_mul_f32_e32 v134, v2, v134
	v_mul_f32_e32 v135, v3, v135
	v_mul_f32_e32 v136, v4, v136
	v_mul_f32_e32 v137, v5, v137
	v_fma_f32 v134, v2, v134, v2
	v_fma_f32 v135, v3, v135, v3
	v_fma_f32 v136, v4, v136, v4
	v_fma_f32 v137, v5, v137, v5
	v_mul_f32_e32 v134, 0x3f4c422a, v134
	v_mul_f32_e32 v135, 0x3f4c422a, v135
	v_mul_f32_e32 v136, 0x3f4c422a, v136
	v_mul_f32_e32 v137, 0x3f4c422a, v137
	v_mul_f32_e32 v134, -2.0, v134
	v_mul_f32_e32 v135, -2.0, v135
	v_mul_f32_e32 v136, -2.0, v136
	v_mul_f32_e32 v137, -2.0, v137
	v_mul_f32_e32 v134, 0x3fb8aa3b, v134
	v_mul_f32_e32 v135, 0x3fb8aa3b, v135
	v_mul_f32_e32 v136, 0x3fb8aa3b, v136
	v_mul_f32_e32 v137, 0x3fb8aa3b, v137
	v_exp_f32_e32 v134, v134
	v_exp_f32_e32 v135, v135
	v_exp_f32_e32 v136, v136
	v_exp_f32_e32 v137, v137
	v_add_f32_e32 v134, 1.0, v134
	v_add_f32_e32 v135, 1.0, v135
	v_add_f32_e32 v136, 1.0, v136
	v_add_f32_e32 v137, 1.0, v137
	v_rcp_f32_e32 v134, v134
	v_rcp_f32_e32 v135, v135
	v_rcp_f32_e32 v136, v136
	v_rcp_f32_e32 v137, v137
	s_nop 0
	v_mul_f32_e32 v2, v2, v134
	v_mul_f32_e32 v3, v3, v135
	v_mul_f32_e32 v4, v4, v136
	v_mul_f32_e32 v5, v5, v137
	v_cvt_pk_f16_f32 v2, v2, v3
	v_cvt_pk_f16_f32 v3, v4, v5
	global_store_dwordx2 v193, v[2:3], s[22:23] offset:96
	s_waitcnt vmcnt(32)
	s_branch .Lp1_join

.Lp1_rope_j:
	v_lshlrev_b32_e32 v193, 9, v198
	v_lshl_add_u32 v193, v199, 1, v193
	s_cmp_lg_u32 s3, 0
	s_cbranch_scc0 .Lp1_rope_ctx
	v_readlane_b32 s2, v254, 18
	v_readlane_b32 s3, v254, 19
	s_and_b32 s4, s4, 7
	s_lshl_b32 s4, s4, 15
	s_add_u32 s4, s2, s4
	s_addc_u32 s5, s3, 0
	v_and_b32_e32 v192, 1, v195
	v_lshlrev_b32_e32 v192, 4, v192
	v_lshl_or_b32 v192, v198, 7, v192
	v_cmp_gt_u32_e32 vcc, 2, v195
	v_bfrev_b32_e32 v191, 1
	s_nop 0
	v_cndmask_b32_e32 v191, 0, v191, vcc
	v_xor_b32_e32 v190, 32, v222
	v_and_b32_e32 v190, 63, v190
	v_lshlrev_b32_e32 v190, 2, v190
	global_load_dwordx4 v[130:133], v192, s[4:5] offset:0
	global_load_dwordx4 v[134:137], v192, s[4:5] offset:32
	global_load_dwordx4 v[138:141], v192, s[4:5] offset:64
	global_load_dwordx4 v[142:145], v192, s[4:5] offset:96
	v_add_u32_e32 v192, 0x800, v192
	global_load_dwordx4 v[146:149], v192, s[4:5] offset:0
	global_load_dwordx4 v[150:153], v192, s[4:5] offset:32
	global_load_dwordx4 v[154:157], v192, s[4:5] offset:64
	global_load_dwordx4 v[158:161], v192, s[4:5] offset:96
	v_add_u32_e32 v192, 0x800, v192
	s_add_i32 s2, s53, s95
	s_cmp_lt_i32 s2, s58
	s_cselect_b32 s21, 1, 0
	s_cselect_b32 s53, s2, s53
	s_lshr_b32 s2, s53, 5
	s_mul_hi_u32 s2, s2, 0xcccccccd
	s_lshr_b32 s2, s2, 2
	s_lshl_b32 s3, s2, 4
	s_mul_i32 s2, s2, 0xa0
	s_sub_i32 s2, s53, s2
	s_lshr_b32 s2, s2, 4
	s_and_b32 s6, s53, 15
	s_add_i32 s3, s3, s6
	s_sub_i32 s28, s53, s58
	s_lshr_b32 s28, s28, 4
	s_add_i32 s28, s28, 8
	s_or_b32 s6, s6, 0x80
	s_cmp_ge_i32 s53, s58
	s_cselect_b32 s6, s6, s3
	s_cselect_b32 s28, s28, s2
	s_lshl_b32 s2, s6, 19
	s_add_u32 s12, s64, s2
	s_addc_u32 s13, s65, 0
	s_lshl_b32 s2, s28, 19
	s_add_u32 s14, s34, s2
	s_addc_u32 s15, s35, 0
	s_mov_b32 m0, s18
	s_nop 0
	global_load_lds_dwordx4 v1, s[12:13]
	s_add_i32 m0, s18, 0x2000
	s_add_u32 s16, s12, 0x20000
	s_addc_u32 s17, s13, 0
	global_load_lds_dwordx4 v1, s[16:17]
	s_add_i32 m0, s18, 0x4000
	s_add_u32 s16, s12, 0x40000
	s_addc_u32 s17, s13, 0
	global_load_lds_dwordx4 v1, s[16:17]
	s_add_i32 m0, s18, 0x6000
	s_add_u32 s16, s12, 0x60000
	s_addc_u32 s17, s13, 0
	global_load_lds_dwordx4 v1, s[16:17]
	s_add_i32 m0, s18, 0x8000
	s_nop 0
	global_load_lds_dwordx4 v1, s[14:15]
	s_add_i32 m0, s18, 0xa000
	s_add_u32 s16, s14, 0x20000
	s_addc_u32 s17, s15, 0
	global_load_lds_dwordx4 v1, s[16:17]
	s_add_i32 m0, s18, 0xc000
	s_add_u32 s16, s14, 0x40000
	s_addc_u32 s17, s15, 0
	global_load_lds_dwordx4 v1, s[16:17]
	s_add_i32 m0, s18, 0xe000
	s_add_u32 s16, s14, 0x60000
	s_addc_u32 s17, s15, 0
	global_load_lds_dwordx4 v1, s[16:17]
	ds_bpermute_b32 v162, v190, v126
	ds_bpermute_b32 v163, v190, v127
	ds_bpermute_b32 v164, v190, v128
	ds_bpermute_b32 v165, v190, v129
	ds_bpermute_b32 v166, v190, v122
	ds_bpermute_b32 v167, v190, v123
	ds_bpermute_b32 v168, v190, v124
	ds_bpermute_b32 v169, v190, v125
	ds_bpermute_b32 v170, v190, v118
	ds_bpermute_b32 v171, v190, v119
	ds_bpermute_b32 v172, v190, v120
	ds_bpermute_b32 v173, v190, v121
	ds_bpermute_b32 v174, v190, v114
	ds_bpermute_b32 v175, v190, v115
	ds_bpermute_b32 v176, v190, v116
	ds_bpermute_b32 v177, v190, v117
	s_waitcnt vmcnt(12)
	v_xor_b32_e32 v134, v191, v134
	v_xor_b32_e32 v142, v191, v142
	v_xor_b32_e32 v135, v191, v135
	v_xor_b32_e32 v143, v191, v143
	v_xor_b32_e32 v136, v191, v136
	v_xor_b32_e32 v144, v191, v144
	v_xor_b32_e32 v137, v191, v137
	v_xor_b32_e32 v145, v191, v145
	s_waitcnt lgkmcnt(0)
	v_pk_mul_f32 v[162:163], v[134:135], v[162:163]
	v_pk_mul_f32 v[164:165], v[136:137], v[164:165]
	v_pk_fma_f32 v[126:127], v[126:127], v[130:131], v[162:163]
	v_pk_fma_f32 v[128:129], v[128:129], v[132:133], v[164:165]
	v_pk_mul_f32 v[166:167], v[142:143], v[166:167]
	v_pk_mul_f32 v[168:169], v[144:145], v[168:169]
	v_pk_fma_f32 v[122:123], v[122:123], v[138:139], v[166:167]
	v_pk_fma_f32 v[124:125], v[124:125], v[140:141], v[168:169]
	v_pk_mul_f32 v[170:171], v[134:135], v[170:171]
	v_pk_mul_f32 v[172:173], v[136:137], v[172:173]
	v_pk_fma_f32 v[118:119], v[118:119], v[130:131], v[170:171]
	v_pk_fma_f32 v[120:121], v[120:121], v[132:133], v[172:173]
	v_pk_mul_f32 v[174:175], v[142:143], v[174:175]
	v_pk_mul_f32 v[176:177], v[144:145], v[176:177]
	v_pk_fma_f32 v[114:115], v[114:115], v[138:139], v[174:175]
	v_pk_fma_f32 v[116:117], v[116:117], v[140:141], v[176:177]
	global_load_dwordx4 v[130:133], v192, s[4:5] offset:0
	global_load_dwordx4 v[134:137], v192, s[4:5] offset:32
	global_load_dwordx4 v[138:141], v192, s[4:5] offset:64
	global_load_dwordx4 v[142:145], v192, s[4:5] offset:96
	v_add_u32_e32 v192, 0x800, v192
	v_mul_f32_e32 v126, s7, v126
	v_mul_f32_e32 v127, s7, v127
	v_mul_f32_e32 v128, s7, v128
	v_mul_f32_e32 v129, s7, v129
	v_cvt_pk_f16_f32 v126, v126, v127
	v_cvt_pk_f16_f32 v127, v128, v129
	global_store_dwordx2 v193, v[126:127], s[22:23] offset:0
	v_mul_f32_e32 v122, s7, v122
	v_mul_f32_e32 v123, s7, v123
	v_mul_f32_e32 v124, s7, v124
	v_mul_f32_e32 v125, s7, v125
	v_cvt_pk_f16_f32 v122, v122, v123
	v_cvt_pk_f16_f32 v123, v124, v125
	global_store_dwordx2 v193, v[122:123], s[22:23] offset:32
	v_mul_f32_e32 v118, s7, v118
	v_mul_f32_e32 v119, s7, v119
	v_mul_f32_e32 v120, s7, v120
	v_mul_f32_e32 v121, s7, v121
	v_cvt_pk_f16_f32 v118, v118, v119
	v_cvt_pk_f16_f32 v119, v120, v121
	global_store_dwordx2 v193, v[118:119], s[22:23] offset:64
	v_mul_f32_e32 v114, s7, v114
	v_mul_f32_e32 v115, s7, v115
	v_mul_f32_e32 v116, s7, v116
	v_mul_f32_e32 v117, s7, v117
	v_cvt_pk_f16_f32 v114, v114, v115
	v_cvt_pk_f16_f32 v115, v116, v117
	global_store_dwordx2 v193, v[114:115], s[22:23] offset:96
	v_add_u32_e32 v193, 0x2000, v193
	ds_bpermute_b32 v162, v190, v110
	ds_bpermute_b32 v163, v190, v111
	ds_bpermute_b32 v164, v190, v112
	ds_bpermute_b32 v165, v190, v113
	ds_bpermute_b32 v166, v190, v106
	ds_bpermute_b32 v167, v190, v107
	ds_bpermute_b32 v168, v190, v108
	ds_bpermute_b32 v169, v190, v109
	ds_bpermute_b32 v170, v190, v102
	ds_bpermute_b32 v171, v190, v103
	ds_bpermute_b32 v172, v190, v104
	ds_bpermute_b32 v173, v190, v105
	ds_bpermute_b32 v174, v190, v98
	ds_bpermute_b32 v175, v190, v99
	ds_bpermute_b32 v176, v190, v100
	ds_bpermute_b32 v177, v190, v101
	s_waitcnt vmcnt(16)
	v_xor_b32_e32 v150, v191, v150
	v_xor_b32_e32 v158, v191, v158
	v_xor_b32_e32 v151, v191, v151
	v_xor_b32_e32 v159, v191, v159
	v_xor_b32_e32 v152, v191, v152
	v_xor_b32_e32 v160, v191, v160
	v_xor_b32_e32 v153, v191, v153
	v_xor_b32_e32 v161, v191, v161
	s_waitcnt lgkmcnt(0)
	v_pk_mul_f32 v[162:163], v[150:151], v[162:163]
	v_pk_mul_f32 v[164:165], v[152:153], v[164:165]
	v_pk_fma_f32 v[110:111], v[110:111], v[146:147], v[162:163]
	v_pk_fma_f32 v[112:113], v[112:113], v[148:149], v[164:165]
	v_pk_mul_f32 v[166:167], v[158:159], v[166:167]
	v_pk_mul_f32 v[168:169], v[160:161], v[168:169]
	v_pk_fma_f32 v[106:107], v[106:107], v[154:155], v[166:167]
	v_pk_fma_f32 v[108:109], v[108:109], v[156:157], v[168:169]
	v_pk_mul_f32 v[170:171], v[150:151], v[170:171]
	v_pk_mul_f32 v[172:173], v[152:153], v[172:173]
	v_pk_fma_f32 v[102:103], v[102:103], v[146:147], v[170:171]
	v_pk_fma_f32 v[104:105], v[104:105], v[148:149], v[172:173]
	v_pk_mul_f32 v[174:175], v[158:159], v[174:175]
	v_pk_mul_f32 v[176:177], v[160:161], v[176:177]
	v_pk_fma_f32 v[98:99], v[98:99], v[154:155], v[174:175]
	v_pk_fma_f32 v[100:101], v[100:101], v[156:157], v[176:177]
	global_load_dwordx4 v[146:149], v192, s[4:5] offset:0
	global_load_dwordx4 v[150:153], v192, s[4:5] offset:32
	global_load_dwordx4 v[154:157], v192, s[4:5] offset:64
	global_load_dwordx4 v[158:161], v192, s[4:5] offset:96
	v_add_u32_e32 v192, 0x800, v192
	v_mul_f32_e32 v110, s7, v110
	v_mul_f32_e32 v111, s7, v111
	v_mul_f32_e32 v112, s7, v112
	v_mul_f32_e32 v113, s7, v113
	v_cvt_pk_f16_f32 v110, v110, v111
	v_cvt_pk_f16_f32 v111, v112, v113
	global_store_dwordx2 v193, v[110:111], s[22:23] offset:0
	v_mul_f32_e32 v106, s7, v106
	v_mul_f32_e32 v107, s7, v107
	v_mul_f32_e32 v108, s7, v108
	v_mul_f32_e32 v109, s7, v109
	v_cvt_pk_f16_f32 v106, v106, v107
	v_cvt_pk_f16_f32 v107, v108, v109
	global_store_dwordx2 v193, v[106:107], s[22:23] offset:32
	v_mul_f32_e32 v102, s7, v102
	v_mul_f32_e32 v103, s7, v103
	v_mul_f32_e32 v104, s7, v104
	v_mul_f32_e32 v105, s7, v105
	v_cvt_pk_f16_f32 v102, v102, v103
	v_cvt_pk_f16_f32 v103, v104, v105
	global_store_dwordx2 v193, v[102:103], s[22:23] offset:64
	v_mul_f32_e32 v98, s7, v98
	v_mul_f32_e32 v99, s7, v99
	v_mul_f32_e32 v100, s7, v100
	v_mul_f32_e32 v101, s7, v101
	v_cvt_pk_f16_f32 v98, v98, v99
	v_cvt_pk_f16_f32 v99, v100, v101
	global_store_dwordx2 v193, v[98:99], s[22:23] offset:96
	v_add_u32_e32 v193, 0x2000, v193
	ds_bpermute_b32 v162, v190, v94
	ds_bpermute_b32 v163, v190, v95
	ds_bpermute_b32 v164, v190, v96
	ds_bpermute_b32 v165, v190, v97
	ds_bpermute_b32 v166, v190, v90
	ds_bpermute_b32 v167, v190, v91
	ds_bpermute_b32 v168, v190, v92
	ds_bpermute_b32 v169, v190, v93
	ds_bpermute_b32 v170, v190, v86
	ds_bpermute_b32 v171, v190, v87
	ds_bpermute_b32 v172, v190, v88
	ds_bpermute_b32 v173, v190, v89
	ds_bpermute_b32 v174, v190, v82
	ds_bpermute_b32 v175, v190, v83
	ds_bpermute_b32 v176, v190, v84
	ds_bpermute_b32 v177, v190, v85
	s_waitcnt vmcnt(12)
	v_xor_b32_e32 v134, v191, v134
	v_xor_b32_e32 v142, v191, v142
	v_xor_b32_e32 v135, v191, v135
	v_xor_b32_e32 v143, v191, v143
	v_xor_b32_e32 v136, v191, v136
	v_xor_b32_e32 v144, v191, v144
	v_xor_b32_e32 v137, v191, v137
	v_xor_b32_e32 v145, v191, v145
	s_waitcnt lgkmcnt(0)
	v_pk_mul_f32 v[162:163], v[134:135], v[162:163]
	v_pk_mul_f32 v[164:165], v[136:137], v[164:165]
	v_pk_fma_f32 v[94:95], v[94:95], v[130:131], v[162:163]
	v_pk_fma_f32 v[96:97], v[96:97], v[132:133], v[164:165]
	v_pk_mul_f32 v[166:167], v[142:143], v[166:167]
	v_pk_mul_f32 v[168:169], v[144:145], v[168:169]
	v_pk_fma_f32 v[90:91], v[90:91], v[138:139], v[166:167]
	v_pk_fma_f32 v[92:93], v[92:93], v[140:141], v[168:169]
	v_pk_mul_f32 v[170:171], v[134:135], v[170:171]
	v_pk_mul_f32 v[172:173], v[136:137], v[172:173]
	v_pk_fma_f32 v[86:87], v[86:87], v[130:131], v[170:171]
	v_pk_fma_f32 v[88:89], v[88:89], v[132:133], v[172:173]
	v_pk_mul_f32 v[174:175], v[142:143], v[174:175]
	v_pk_mul_f32 v[176:177], v[144:145], v[176:177]
	v_pk_fma_f32 v[82:83], v[82:83], v[138:139], v[174:175]
	v_pk_fma_f32 v[84:85], v[84:85], v[140:141], v[176:177]
	global_load_dwordx4 v[130:133], v192, s[4:5] offset:0
	global_load_dwordx4 v[134:137], v192, s[4:5] offset:32
	global_load_dwordx4 v[138:141], v192, s[4:5] offset:64
	global_load_dwordx4 v[142:145], v192, s[4:5] offset:96
	v_add_u32_e32 v192, 0x800, v192
	v_mul_f32_e32 v94, s7, v94
	v_mul_f32_e32 v95, s7, v95
	v_mul_f32_e32 v96, s7, v96
	v_mul_f32_e32 v97, s7, v97
	v_cvt_pk_f16_f32 v94, v94, v95
	v_cvt_pk_f16_f32 v95, v96, v97
	global_store_dwordx2 v193, v[94:95], s[22:23] offset:0
	v_mul_f32_e32 v90, s7, v90
	v_mul_f32_e32 v91, s7, v91
	v_mul_f32_e32 v92, s7, v92
	v_mul_f32_e32 v93, s7, v93
	v_cvt_pk_f16_f32 v90, v90, v91
	v_cvt_pk_f16_f32 v91, v92, v93
	global_store_dwordx2 v193, v[90:91], s[22:23] offset:32
	v_mul_f32_e32 v86, s7, v86
	v_mul_f32_e32 v87, s7, v87
	v_mul_f32_e32 v88, s7, v88
	v_mul_f32_e32 v89, s7, v89
	v_cvt_pk_f16_f32 v86, v86, v87
	v_cvt_pk_f16_f32 v87, v88, v89
	global_store_dwordx2 v193, v[86:87], s[22:23] offset:64
	v_mul_f32_e32 v82, s7, v82
	v_mul_f32_e32 v83, s7, v83
	v_mul_f32_e32 v84, s7, v84
	v_mul_f32_e32 v85, s7, v85
	v_cvt_pk_f16_f32 v82, v82, v83
	v_cvt_pk_f16_f32 v83, v84, v85
	global_store_dwordx2 v193, v[82:83], s[22:23] offset:96
	v_add_u32_e32 v193, 0x2000, v193
	ds_bpermute_b32 v162, v190, v78
	ds_bpermute_b32 v163, v190, v79
	ds_bpermute_b32 v164, v190, v80
	ds_bpermute_b32 v165, v190, v81
	ds_bpermute_b32 v166, v190, v74
	ds_bpermute_b32 v167, v190, v75
	ds_bpermute_b32 v168, v190, v76
	ds_bpermute_b32 v169, v190, v77
	ds_bpermute_b32 v170, v190, v70
	ds_bpermute_b32 v171, v190, v71
	ds_bpermute_b32 v172, v190, v72
	ds_bpermute_b32 v173, v190, v73
	ds_bpermute_b32 v174, v190, v66
	ds_bpermute_b32 v175, v190, v67
	ds_bpermute_b32 v176, v190, v68
	ds_bpermute_b32 v177, v190, v69
	s_waitcnt vmcnt(12)
	v_xor_b32_e32 v150, v191, v150
	v_xor_b32_e32 v158, v191, v158
	v_xor_b32_e32 v151, v191, v151
	v_xor_b32_e32 v159, v191, v159
	v_xor_b32_e32 v152, v191, v152
	v_xor_b32_e32 v160, v191, v160
	v_xor_b32_e32 v153, v191, v153
	v_xor_b32_e32 v161, v191, v161
	s_waitcnt lgkmcnt(0)
	v_pk_mul_f32 v[162:163], v[150:151], v[162:163]
	v_pk_mul_f32 v[164:165], v[152:153], v[164:165]
	v_pk_fma_f32 v[78:79], v[78:79], v[146:147], v[162:163]
	v_pk_fma_f32 v[80:81], v[80:81], v[148:149], v[164:165]
	v_pk_mul_f32 v[166:167], v[158:159], v[166:167]
	v_pk_mul_f32 v[168:169], v[160:161], v[168:169]
	v_pk_fma_f32 v[74:75], v[74:75], v[154:155], v[166:167]
	v_pk_fma_f32 v[76:77], v[76:77], v[156:157], v[168:169]
	v_pk_mul_f32 v[170:171], v[150:151], v[170:171]
	v_pk_mul_f32 v[172:173], v[152:153], v[172:173]
	v_pk_fma_f32 v[70:71], v[70:71], v[146:147], v[170:171]
	v_pk_fma_f32 v[72:73], v[72:73], v[148:149], v[172:173]
	v_pk_mul_f32 v[174:175], v[158:159], v[174:175]
	v_pk_mul_f32 v[176:177], v[160:161], v[176:177]
	v_pk_fma_f32 v[66:67], v[66:67], v[154:155], v[174:175]
	v_pk_fma_f32 v[68:69], v[68:69], v[156:157], v[176:177]
	global_load_dwordx4 v[146:149], v192, s[4:5] offset:0
	global_load_dwordx4 v[150:153], v192, s[4:5] offset:32
	global_load_dwordx4 v[154:157], v192, s[4:5] offset:64
	global_load_dwordx4 v[158:161], v192, s[4:5] offset:96
	v_add_u32_e32 v192, 0x800, v192
	v_mul_f32_e32 v78, s7, v78
	v_mul_f32_e32 v79, s7, v79
	v_mul_f32_e32 v80, s7, v80
	v_mul_f32_e32 v81, s7, v81
	v_cvt_pk_f16_f32 v78, v78, v79
	v_cvt_pk_f16_f32 v79, v80, v81
	global_store_dwordx2 v193, v[78:79], s[22:23] offset:0
	v_mul_f32_e32 v74, s7, v74
	v_mul_f32_e32 v75, s7, v75
	v_mul_f32_e32 v76, s7, v76
	v_mul_f32_e32 v77, s7, v77
	v_cvt_pk_f16_f32 v74, v74, v75
	v_cvt_pk_f16_f32 v75, v76, v77
	global_store_dwordx2 v193, v[74:75], s[22:23] offset:32
	v_mul_f32_e32 v70, s7, v70
	v_mul_f32_e32 v71, s7, v71
	v_mul_f32_e32 v72, s7, v72
	v_mul_f32_e32 v73, s7, v73
	v_cvt_pk_f16_f32 v70, v70, v71
	v_cvt_pk_f16_f32 v71, v72, v73
	global_store_dwordx2 v193, v[70:71], s[22:23] offset:64
	v_mul_f32_e32 v66, s7, v66
	v_mul_f32_e32 v67, s7, v67
	v_mul_f32_e32 v68, s7, v68
	v_mul_f32_e32 v69, s7, v69
	v_cvt_pk_f16_f32 v66, v66, v67
	v_cvt_pk_f16_f32 v67, v68, v69
	global_store_dwordx2 v193, v[66:67], s[22:23] offset:96
	v_add_u32_e32 v193, 0x2000, v193
	ds_bpermute_b32 v162, v190, v62
	ds_bpermute_b32 v163, v190, v63
	ds_bpermute_b32 v164, v190, v64
	ds_bpermute_b32 v165, v190, v65
	ds_bpermute_b32 v166, v190, v58
	ds_bpermute_b32 v167, v190, v59
	ds_bpermute_b32 v168, v190, v60
	ds_bpermute_b32 v169, v190, v61
	ds_bpermute_b32 v170, v190, v54
	ds_bpermute_b32 v171, v190, v55
	ds_bpermute_b32 v172, v190, v56
	ds_bpermute_b32 v173, v190, v57
	ds_bpermute_b32 v174, v190, v50
	ds_bpermute_b32 v175, v190, v51
	ds_bpermute_b32 v176, v190, v52
	ds_bpermute_b32 v177, v190, v53
	s_waitcnt vmcnt(12)
	v_xor_b32_e32 v134, v191, v134
	v_xor_b32_e32 v142, v191, v142
	v_xor_b32_e32 v135, v191, v135
	v_xor_b32_e32 v143, v191, v143
	v_xor_b32_e32 v136, v191, v136
	v_xor_b32_e32 v144, v191, v144
	v_xor_b32_e32 v137, v191, v137
	v_xor_b32_e32 v145, v191, v145
	s_waitcnt lgkmcnt(0)
	v_pk_mul_f32 v[162:163], v[134:135], v[162:163]
	v_pk_mul_f32 v[164:165], v[136:137], v[164:165]
	v_pk_fma_f32 v[62:63], v[62:63], v[130:131], v[162:163]
	v_pk_fma_f32 v[64:65], v[64:65], v[132:133], v[164:165]
	v_pk_mul_f32 v[166:167], v[142:143], v[166:167]
	v_pk_mul_f32 v[168:169], v[144:145], v[168:169]
	v_pk_fma_f32 v[58:59], v[58:59], v[138:139], v[166:167]
	v_pk_fma_f32 v[60:61], v[60:61], v[140:141], v[168:169]
	v_pk_mul_f32 v[170:171], v[134:135], v[170:171]
	v_pk_mul_f32 v[172:173], v[136:137], v[172:173]
	v_pk_fma_f32 v[54:55], v[54:55], v[130:131], v[170:171]
	v_pk_fma_f32 v[56:57], v[56:57], v[132:133], v[172:173]
	v_pk_mul_f32 v[174:175], v[142:143], v[174:175]
	v_pk_mul_f32 v[176:177], v[144:145], v[176:177]
	v_pk_fma_f32 v[50:51], v[50:51], v[138:139], v[174:175]
	v_pk_fma_f32 v[52:53], v[52:53], v[140:141], v[176:177]
	global_load_dwordx4 v[130:133], v192, s[4:5] offset:0
	global_load_dwordx4 v[134:137], v192, s[4:5] offset:32
	global_load_dwordx4 v[138:141], v192, s[4:5] offset:64
	global_load_dwordx4 v[142:145], v192, s[4:5] offset:96
	v_add_u32_e32 v192, 0x800, v192
	v_mul_f32_e32 v62, s7, v62
	v_mul_f32_e32 v63, s7, v63
	v_mul_f32_e32 v64, s7, v64
	v_mul_f32_e32 v65, s7, v65
	v_cvt_pk_f16_f32 v62, v62, v63
	v_cvt_pk_f16_f32 v63, v64, v65
	global_store_dwordx2 v193, v[62:63], s[22:23] offset:0
	v_mul_f32_e32 v58, s7, v58
	v_mul_f32_e32 v59, s7, v59
	v_mul_f32_e32 v60, s7, v60
	v_mul_f32_e32 v61, s7, v61
	v_cvt_pk_f16_f32 v58, v58, v59
	v_cvt_pk_f16_f32 v59, v60, v61
	global_store_dwordx2 v193, v[58:59], s[22:23] offset:32
	v_mul_f32_e32 v54, s7, v54
	v_mul_f32_e32 v55, s7, v55
	v_mul_f32_e32 v56, s7, v56
	v_mul_f32_e32 v57, s7, v57
	v_cvt_pk_f16_f32 v54, v54, v55
	v_cvt_pk_f16_f32 v55, v56, v57
	global_store_dwordx2 v193, v[54:55], s[22:23] offset:64
	v_mul_f32_e32 v50, s7, v50
	v_mul_f32_e32 v51, s7, v51
	v_mul_f32_e32 v52, s7, v52
	v_mul_f32_e32 v53, s7, v53
	v_cvt_pk_f16_f32 v50, v50, v51
	v_cvt_pk_f16_f32 v51, v52, v53
	global_store_dwordx2 v193, v[50:51], s[22:23] offset:96
	v_add_u32_e32 v193, 0x2000, v193
	ds_bpermute_b32 v162, v190, v46
	ds_bpermute_b32 v163, v190, v47
	ds_bpermute_b32 v164, v190, v48
	ds_bpermute_b32 v165, v190, v49
	ds_bpermute_b32 v166, v190, v42
	ds_bpermute_b32 v167, v190, v43
	ds_bpermute_b32 v168, v190, v44
	ds_bpermute_b32 v169, v190, v45
	ds_bpermute_b32 v170, v190, v38
	ds_bpermute_b32 v171, v190, v39
	ds_bpermute_b32 v172, v190, v40
	ds_bpermute_b32 v173, v190, v41
	ds_bpermute_b32 v174, v190, v34
	ds_bpermute_b32 v175, v190, v35
	ds_bpermute_b32 v176, v190, v36
	ds_bpermute_b32 v177, v190, v37
	s_waitcnt vmcnt(12)
	v_xor_b32_e32 v150, v191, v150
	v_xor_b32_e32 v158, v191, v158
	v_xor_b32_e32 v151, v191, v151
	v_xor_b32_e32 v159, v191, v159
	v_xor_b32_e32 v152, v191, v152
	v_xor_b32_e32 v160, v191, v160
	v_xor_b32_e32 v153, v191, v153
	v_xor_b32_e32 v161, v191, v161
	s_waitcnt lgkmcnt(0)
	v_pk_mul_f32 v[162:163], v[150:151], v[162:163]
	v_pk_mul_f32 v[164:165], v[152:153], v[164:165]
	v_pk_fma_f32 v[46:47], v[46:47], v[146:147], v[162:163]
	v_pk_fma_f32 v[48:49], v[48:49], v[148:149], v[164:165]
	v_pk_mul_f32 v[166:167], v[158:159], v[166:167]
	v_pk_mul_f32 v[168:169], v[160:161], v[168:169]
	v_pk_fma_f32 v[42:43], v[42:43], v[154:155], v[166:167]
	v_pk_fma_f32 v[44:45], v[44:45], v[156:157], v[168:169]
	v_pk_mul_f32 v[170:171], v[150:151], v[170:171]
	v_pk_mul_f32 v[172:173], v[152:153], v[172:173]
	v_pk_fma_f32 v[38:39], v[38:39], v[146:147], v[170:171]
	v_pk_fma_f32 v[40:41], v[40:41], v[148:149], v[172:173]
	v_pk_mul_f32 v[174:175], v[158:159], v[174:175]
	v_pk_mul_f32 v[176:177], v[160:161], v[176:177]
	v_pk_fma_f32 v[34:35], v[34:35], v[154:155], v[174:175]
	v_pk_fma_f32 v[36:37], v[36:37], v[156:157], v[176:177]
	global_load_dwordx4 v[146:149], v192, s[4:5] offset:0
	global_load_dwordx4 v[150:153], v192, s[4:5] offset:32
	global_load_dwordx4 v[154:157], v192, s[4:5] offset:64
	global_load_dwordx4 v[158:161], v192, s[4:5] offset:96
	v_add_u32_e32 v192, 0x800, v192
	v_mul_f32_e32 v46, s7, v46
	v_mul_f32_e32 v47, s7, v47
	v_mul_f32_e32 v48, s7, v48
	v_mul_f32_e32 v49, s7, v49
	v_cvt_pk_f16_f32 v46, v46, v47
	v_cvt_pk_f16_f32 v47, v48, v49
	global_store_dwordx2 v193, v[46:47], s[22:23] offset:0
	v_mul_f32_e32 v42, s7, v42
	v_mul_f32_e32 v43, s7, v43
	v_mul_f32_e32 v44, s7, v44
	v_mul_f32_e32 v45, s7, v45
	v_cvt_pk_f16_f32 v42, v42, v43
	v_cvt_pk_f16_f32 v43, v44, v45
	global_store_dwordx2 v193, v[42:43], s[22:23] offset:32
	v_mul_f32_e32 v38, s7, v38
	v_mul_f32_e32 v39, s7, v39
	v_mul_f32_e32 v40, s7, v40
	v_mul_f32_e32 v41, s7, v41
	v_cvt_pk_f16_f32 v38, v38, v39
	v_cvt_pk_f16_f32 v39, v40, v41
	global_store_dwordx2 v193, v[38:39], s[22:23] offset:64
	v_mul_f32_e32 v34, s7, v34
	v_mul_f32_e32 v35, s7, v35
	v_mul_f32_e32 v36, s7, v36
	v_mul_f32_e32 v37, s7, v37
	v_cvt_pk_f16_f32 v34, v34, v35
	v_cvt_pk_f16_f32 v35, v36, v37
	global_store_dwordx2 v193, v[34:35], s[22:23] offset:96
	v_add_u32_e32 v193, 0x2000, v193
	ds_bpermute_b32 v162, v190, v30
	ds_bpermute_b32 v163, v190, v31
	ds_bpermute_b32 v164, v190, v32
	ds_bpermute_b32 v165, v190, v33
	ds_bpermute_b32 v166, v190, v26
	ds_bpermute_b32 v167, v190, v27
	ds_bpermute_b32 v168, v190, v28
	ds_bpermute_b32 v169, v190, v29
	ds_bpermute_b32 v170, v190, v22
	ds_bpermute_b32 v171, v190, v23
	ds_bpermute_b32 v172, v190, v24
	ds_bpermute_b32 v173, v190, v25
	ds_bpermute_b32 v174, v190, v18
	ds_bpermute_b32 v175, v190, v19
	ds_bpermute_b32 v176, v190, v20
	ds_bpermute_b32 v177, v190, v21
	s_waitcnt vmcnt(12)
	v_xor_b32_e32 v134, v191, v134
	v_xor_b32_e32 v142, v191, v142
	v_xor_b32_e32 v135, v191, v135
	v_xor_b32_e32 v143, v191, v143
	v_xor_b32_e32 v136, v191, v136
	v_xor_b32_e32 v144, v191, v144
	v_xor_b32_e32 v137, v191, v137
	v_xor_b32_e32 v145, v191, v145
	s_waitcnt lgkmcnt(0)
	v_pk_mul_f32 v[162:163], v[134:135], v[162:163]
	v_pk_mul_f32 v[164:165], v[136:137], v[164:165]
	v_pk_fma_f32 v[30:31], v[30:31], v[130:131], v[162:163]
	v_pk_fma_f32 v[32:33], v[32:33], v[132:133], v[164:165]
	v_pk_mul_f32 v[166:167], v[142:143], v[166:167]
	v_pk_mul_f32 v[168:169], v[144:145], v[168:169]
	v_pk_fma_f32 v[26:27], v[26:27], v[138:139], v[166:167]
	v_pk_fma_f32 v[28:29], v[28:29], v[140:141], v[168:169]
	v_pk_mul_f32 v[170:171], v[134:135], v[170:171]
	v_pk_mul_f32 v[172:173], v[136:137], v[172:173]
	v_pk_fma_f32 v[22:23], v[22:23], v[130:131], v[170:171]
	v_pk_fma_f32 v[24:25], v[24:25], v[132:133], v[172:173]
	v_pk_mul_f32 v[174:175], v[142:143], v[174:175]
	v_pk_mul_f32 v[176:177], v[144:145], v[176:177]
	v_pk_fma_f32 v[18:19], v[18:19], v[138:139], v[174:175]
	v_pk_fma_f32 v[20:21], v[20:21], v[140:141], v[176:177]
	v_mul_f32_e32 v30, s7, v30
	v_mul_f32_e32 v31, s7, v31
	v_mul_f32_e32 v32, s7, v32
	v_mul_f32_e32 v33, s7, v33
	v_cvt_pk_f16_f32 v30, v30, v31
	v_cvt_pk_f16_f32 v31, v32, v33
	global_store_dwordx2 v193, v[30:31], s[22:23] offset:0
	v_mul_f32_e32 v26, s7, v26
	v_mul_f32_e32 v27, s7, v27
	v_mul_f32_e32 v28, s7, v28
	v_mul_f32_e32 v29, s7, v29
	v_cvt_pk_f16_f32 v26, v26, v27
	v_cvt_pk_f16_f32 v27, v28, v29
	global_store_dwordx2 v193, v[26:27], s[22:23] offset:32
	v_mul_f32_e32 v22, s7, v22
	v_mul_f32_e32 v23, s7, v23
	v_mul_f32_e32 v24, s7, v24
	v_mul_f32_e32 v25, s7, v25
	v_cvt_pk_f16_f32 v22, v22, v23
	v_cvt_pk_f16_f32 v23, v24, v25
	global_store_dwordx2 v193, v[22:23], s[22:23] offset:64
	v_mul_f32_e32 v18, s7, v18
	v_mul_f32_e32 v19, s7, v19
	v_mul_f32_e32 v20, s7, v20
	v_mul_f32_e32 v21, s7, v21
	v_cvt_pk_f16_f32 v18, v18, v19
	v_cvt_pk_f16_f32 v19, v20, v21
	global_store_dwordx2 v193, v[18:19], s[22:23] offset:96
	v_add_u32_e32 v193, 0x2000, v193
	ds_bpermute_b32 v162, v190, v14
	ds_bpermute_b32 v163, v190, v15
	ds_bpermute_b32 v164, v190, v16
	ds_bpermute_b32 v165, v190, v17
	ds_bpermute_b32 v166, v190, v10
	ds_bpermute_b32 v167, v190, v11
	ds_bpermute_b32 v168, v190, v12
	ds_bpermute_b32 v169, v190, v13
	ds_bpermute_b32 v170, v190, v6
	ds_bpermute_b32 v171, v190, v7
	ds_bpermute_b32 v172, v190, v8
	ds_bpermute_b32 v173, v190, v9
	ds_bpermute_b32 v174, v190, v2
	ds_bpermute_b32 v175, v190, v3
	ds_bpermute_b32 v176, v190, v4
	ds_bpermute_b32 v177, v190, v5
	s_waitcnt vmcnt(8)
	v_xor_b32_e32 v150, v191, v150
	v_xor_b32_e32 v158, v191, v158
	v_xor_b32_e32 v151, v191, v151
	v_xor_b32_e32 v159, v191, v159
	v_xor_b32_e32 v152, v191, v152
	v_xor_b32_e32 v160, v191, v160
	v_xor_b32_e32 v153, v191, v153
	v_xor_b32_e32 v161, v191, v161
	s_waitcnt lgkmcnt(0)
	v_pk_mul_f32 v[162:163], v[150:151], v[162:163]
	v_pk_mul_f32 v[164:165], v[152:153], v[164:165]
	v_pk_fma_f32 v[14:15], v[14:15], v[146:147], v[162:163]
	v_pk_fma_f32 v[16:17], v[16:17], v[148:149], v[164:165]
	v_pk_mul_f32 v[166:167], v[158:159], v[166:167]
	v_pk_mul_f32 v[168:169], v[160:161], v[168:169]
	v_pk_fma_f32 v[10:11], v[10:11], v[154:155], v[166:167]
	v_pk_fma_f32 v[12:13], v[12:13], v[156:157], v[168:169]
	v_pk_mul_f32 v[170:171], v[150:151], v[170:171]
	v_pk_mul_f32 v[172:173], v[152:153], v[172:173]
	v_pk_fma_f32 v[6:7], v[6:7], v[146:147], v[170:171]
	v_pk_fma_f32 v[8:9], v[8:9], v[148:149], v[172:173]
	v_pk_mul_f32 v[174:175], v[158:159], v[174:175]
	v_pk_mul_f32 v[176:177], v[160:161], v[176:177]
	v_pk_fma_f32 v[2:3], v[2:3], v[154:155], v[174:175]
	v_pk_fma_f32 v[4:5], v[4:5], v[156:157], v[176:177]
	v_mul_f32_e32 v14, s7, v14
	v_mul_f32_e32 v15, s7, v15
	v_mul_f32_e32 v16, s7, v16
	v_mul_f32_e32 v17, s7, v17
	v_cvt_pk_f16_f32 v14, v14, v15
	v_cvt_pk_f16_f32 v15, v16, v17
	global_store_dwordx2 v193, v[14:15], s[22:23] offset:0
	v_mul_f32_e32 v10, s7, v10
	v_mul_f32_e32 v11, s7, v11
	v_mul_f32_e32 v12, s7, v12
	v_mul_f32_e32 v13, s7, v13
	v_cvt_pk_f16_f32 v10, v10, v11
	v_cvt_pk_f16_f32 v11, v12, v13
	global_store_dwordx2 v193, v[10:11], s[22:23] offset:32
	v_mul_f32_e32 v6, s7, v6
	v_mul_f32_e32 v7, s7, v7
	v_mul_f32_e32 v8, s7, v8
	v_mul_f32_e32 v9, s7, v9
	v_cvt_pk_f16_f32 v6, v6, v7
	v_cvt_pk_f16_f32 v7, v8, v9
	global_store_dwordx2 v193, v[6:7], s[22:23] offset:64
	v_mul_f32_e32 v2, s7, v2
	v_mul_f32_e32 v3, s7, v3
	v_mul_f32_e32 v4, s7, v4
	v_mul_f32_e32 v5, s7, v5
	v_cvt_pk_f16_f32 v2, v2, v3
	v_cvt_pk_f16_f32 v3, v4, v5
	global_store_dwordx2 v193, v[2:3], s[22:23] offset:96
	s_branch .Lp1_join
.Lp1_rope_ctx:
	s_add_i32 s2, s53, s95
	s_cmp_lt_i32 s2, s58
	s_cselect_b32 s21, 1, 0
	s_cselect_b32 s53, s2, s53
	s_lshr_b32 s2, s53, 5
	s_mul_hi_u32 s2, s2, 0xcccccccd
	s_lshr_b32 s2, s2, 2
	s_lshl_b32 s3, s2, 4
	s_mul_i32 s2, s2, 0xa0
	s_sub_i32 s2, s53, s2
	s_lshr_b32 s2, s2, 4
	s_and_b32 s6, s53, 15
	s_add_i32 s3, s3, s6
	s_sub_i32 s28, s53, s58
	s_lshr_b32 s28, s28, 4
	s_add_i32 s28, s28, 8
	s_or_b32 s6, s6, 0x80
	s_cmp_ge_i32 s53, s58
	s_cselect_b32 s6, s6, s3
	s_cselect_b32 s28, s28, s2
	s_lshl_b32 s2, s6, 19
	s_add_u32 s12, s64, s2
	s_addc_u32 s13, s65, 0
	s_lshl_b32 s2, s28, 19
	s_add_u32 s14, s34, s2
	s_addc_u32 s15, s35, 0
	s_mov_b32 m0, s18
	s_nop 0
	global_load_lds_dwordx4 v1, s[12:13]
	s_add_i32 m0, s18, 0x2000
	s_add_u32 s16, s12, 0x20000
	s_addc_u32 s17, s13, 0
	global_load_lds_dwordx4 v1, s[16:17]
	s_add_i32 m0, s18, 0x4000
	s_add_u32 s16, s12, 0x40000
	s_addc_u32 s17, s13, 0
	global_load_lds_dwordx4 v1, s[16:17]
	s_add_i32 m0, s18, 0x6000
	s_add_u32 s16, s12, 0x60000
	s_addc_u32 s17, s13, 0
	global_load_lds_dwordx4 v1, s[16:17]
	s_add_i32 m0, s18, 0x8000
	s_nop 0
	global_load_lds_dwordx4 v1, s[14:15]
	s_add_i32 m0, s18, 0xa000
	s_add_u32 s16, s14, 0x20000
	s_addc_u32 s17, s15, 0
	global_load_lds_dwordx4 v1, s[16:17]
	s_add_i32 m0, s18, 0xc000
	s_add_u32 s16, s14, 0x40000
	s_addc_u32 s17, s15, 0
	global_load_lds_dwordx4 v1, s[16:17]
	s_add_i32 m0, s18, 0xe000
	s_add_u32 s16, s14, 0x60000
	s_addc_u32 s17, s15, 0
	global_load_lds_dwordx4 v1, s[16:17]
	v_mul_f32_e32 v126, s7, v126
	v_mul_f32_e32 v127, s7, v127
	v_mul_f32_e32 v128, s7, v128
	v_mul_f32_e32 v129, s7, v129
	v_cvt_pk_f16_f32 v126, v126, v127
	v_cvt_pk_f16_f32 v127, v128, v129
	global_store_dwordx2 v193, v[126:127], s[22:23] offset:0
	v_mul_f32_e32 v122, s7, v122
	v_mul_f32_e32 v123, s7, v123
	v_mul_f32_e32 v124, s7, v124
	v_mul_f32_e32 v125, s7, v125
	v_cvt_pk_f16_f32 v122, v122, v123
	v_cvt_pk_f16_f32 v123, v124, v125
	global_store_dwordx2 v193, v[122:123], s[22:23] offset:32
	v_mul_f32_e32 v118, s7, v118
	v_mul_f32_e32 v119, s7, v119
	v_mul_f32_e32 v120, s7, v120
	v_mul_f32_e32 v121, s7, v121
	v_cvt_pk_f16_f32 v118, v118, v119
	v_cvt_pk_f16_f32 v119, v120, v121
	global_store_dwordx2 v193, v[118:119], s[22:23] offset:64
	v_mul_f32_e32 v114, s7, v114
	v_mul_f32_e32 v115, s7, v115
	v_mul_f32_e32 v116, s7, v116
	v_mul_f32_e32 v117, s7, v117
	v_cvt_pk_f16_f32 v114, v114, v115
	v_cvt_pk_f16_f32 v115, v116, v117
	global_store_dwordx2 v193, v[114:115], s[22:23] offset:96
	v_add_u32_e32 v193, 0x2000, v193
	v_mul_f32_e32 v110, s7, v110
	v_mul_f32_e32 v111, s7, v111
	v_mul_f32_e32 v112, s7, v112
	v_mul_f32_e32 v113, s7, v113
	v_cvt_pk_f16_f32 v110, v110, v111
	v_cvt_pk_f16_f32 v111, v112, v113
	global_store_dwordx2 v193, v[110:111], s[22:23] offset:0
	v_mul_f32_e32 v106, s7, v106
	v_mul_f32_e32 v107, s7, v107
	v_mul_f32_e32 v108, s7, v108
	v_mul_f32_e32 v109, s7, v109
	v_cvt_pk_f16_f32 v106, v106, v107
	v_cvt_pk_f16_f32 v107, v108, v109
	global_store_dwordx2 v193, v[106:107], s[22:23] offset:32
	v_mul_f32_e32 v102, s7, v102
	v_mul_f32_e32 v103, s7, v103
	v_mul_f32_e32 v104, s7, v104
	v_mul_f32_e32 v105, s7, v105
	v_cvt_pk_f16_f32 v102, v102, v103
	v_cvt_pk_f16_f32 v103, v104, v105
	global_store_dwordx2 v193, v[102:103], s[22:23] offset:64
	v_mul_f32_e32 v98, s7, v98
	v_mul_f32_e32 v99, s7, v99
	v_mul_f32_e32 v100, s7, v100
	v_mul_f32_e32 v101, s7, v101
	v_cvt_pk_f16_f32 v98, v98, v99
	v_cvt_pk_f16_f32 v99, v100, v101
	global_store_dwordx2 v193, v[98:99], s[22:23] offset:96
	v_add_u32_e32 v193, 0x2000, v193
	v_mul_f32_e32 v94, s7, v94
	v_mul_f32_e32 v95, s7, v95
	v_mul_f32_e32 v96, s7, v96
	v_mul_f32_e32 v97, s7, v97
	v_cvt_pk_f16_f32 v94, v94, v95
	v_cvt_pk_f16_f32 v95, v96, v97
	global_store_dwordx2 v193, v[94:95], s[22:23] offset:0
	v_mul_f32_e32 v90, s7, v90
	v_mul_f32_e32 v91, s7, v91
	v_mul_f32_e32 v92, s7, v92
	v_mul_f32_e32 v93, s7, v93
	v_cvt_pk_f16_f32 v90, v90, v91
	v_cvt_pk_f16_f32 v91, v92, v93
	global_store_dwordx2 v193, v[90:91], s[22:23] offset:32
	v_mul_f32_e32 v86, s7, v86
	v_mul_f32_e32 v87, s7, v87
	v_mul_f32_e32 v88, s7, v88
	v_mul_f32_e32 v89, s7, v89
	v_cvt_pk_f16_f32 v86, v86, v87
	v_cvt_pk_f16_f32 v87, v88, v89
	global_store_dwordx2 v193, v[86:87], s[22:23] offset:64
	v_mul_f32_e32 v82, s7, v82
	v_mul_f32_e32 v83, s7, v83
	v_mul_f32_e32 v84, s7, v84
	v_mul_f32_e32 v85, s7, v85
	v_cvt_pk_f16_f32 v82, v82, v83
	v_cvt_pk_f16_f32 v83, v84, v85
	global_store_dwordx2 v193, v[82:83], s[22:23] offset:96
	v_add_u32_e32 v193, 0x2000, v193
	v_mul_f32_e32 v78, s7, v78
	v_mul_f32_e32 v79, s7, v79
	v_mul_f32_e32 v80, s7, v80
	v_mul_f32_e32 v81, s7, v81
	v_cvt_pk_f16_f32 v78, v78, v79
	v_cvt_pk_f16_f32 v79, v80, v81
	global_store_dwordx2 v193, v[78:79], s[22:23] offset:0
	v_mul_f32_e32 v74, s7, v74
	v_mul_f32_e32 v75, s7, v75
	v_mul_f32_e32 v76, s7, v76
	v_mul_f32_e32 v77, s7, v77
	v_cvt_pk_f16_f32 v74, v74, v75
	v_cvt_pk_f16_f32 v75, v76, v77
	global_store_dwordx2 v193, v[74:75], s[22:23] offset:32
	v_mul_f32_e32 v70, s7, v70
	v_mul_f32_e32 v71, s7, v71
	v_mul_f32_e32 v72, s7, v72
	v_mul_f32_e32 v73, s7, v73
	v_cvt_pk_f16_f32 v70, v70, v71
	v_cvt_pk_f16_f32 v71, v72, v73
	global_store_dwordx2 v193, v[70:71], s[22:23] offset:64
	v_mul_f32_e32 v66, s7, v66
	v_mul_f32_e32 v67, s7, v67
	v_mul_f32_e32 v68, s7, v68
	v_mul_f32_e32 v69, s7, v69
	v_cvt_pk_f16_f32 v66, v66, v67
	v_cvt_pk_f16_f32 v67, v68, v69
	global_store_dwordx2 v193, v[66:67], s[22:23] offset:96
	v_add_u32_e32 v193, 0x2000, v193
	v_mul_f32_e32 v62, s7, v62
	v_mul_f32_e32 v63, s7, v63
	v_mul_f32_e32 v64, s7, v64
	v_mul_f32_e32 v65, s7, v65
	v_cvt_pk_f16_f32 v62, v62, v63
	v_cvt_pk_f16_f32 v63, v64, v65
	global_store_dwordx2 v193, v[62:63], s[22:23] offset:0
	v_mul_f32_e32 v58, s7, v58
	v_mul_f32_e32 v59, s7, v59
	v_mul_f32_e32 v60, s7, v60
	v_mul_f32_e32 v61, s7, v61
	v_cvt_pk_f16_f32 v58, v58, v59
	v_cvt_pk_f16_f32 v59, v60, v61
	global_store_dwordx2 v193, v[58:59], s[22:23] offset:32
	v_mul_f32_e32 v54, s7, v54
	v_mul_f32_e32 v55, s7, v55
	v_mul_f32_e32 v56, s7, v56
	v_mul_f32_e32 v57, s7, v57
	v_cvt_pk_f16_f32 v54, v54, v55
	v_cvt_pk_f16_f32 v55, v56, v57
	global_store_dwordx2 v193, v[54:55], s[22:23] offset:64
	v_mul_f32_e32 v50, s7, v50
	v_mul_f32_e32 v51, s7, v51
	v_mul_f32_e32 v52, s7, v52
	v_mul_f32_e32 v53, s7, v53
	v_cvt_pk_f16_f32 v50, v50, v51
	v_cvt_pk_f16_f32 v51, v52, v53
	global_store_dwordx2 v193, v[50:51], s[22:23] offset:96
	v_add_u32_e32 v193, 0x2000, v193
	v_mul_f32_e32 v46, s7, v46
	v_mul_f32_e32 v47, s7, v47
	v_mul_f32_e32 v48, s7, v48
	v_mul_f32_e32 v49, s7, v49
	v_cvt_pk_f16_f32 v46, v46, v47
	v_cvt_pk_f16_f32 v47, v48, v49
	global_store_dwordx2 v193, v[46:47], s[22:23] offset:0
	v_mul_f32_e32 v42, s7, v42
	v_mul_f32_e32 v43, s7, v43
	v_mul_f32_e32 v44, s7, v44
	v_mul_f32_e32 v45, s7, v45
	v_cvt_pk_f16_f32 v42, v42, v43
	v_cvt_pk_f16_f32 v43, v44, v45
	global_store_dwordx2 v193, v[42:43], s[22:23] offset:32
	v_mul_f32_e32 v38, s7, v38
	v_mul_f32_e32 v39, s7, v39
	v_mul_f32_e32 v40, s7, v40
	v_mul_f32_e32 v41, s7, v41
	v_cvt_pk_f16_f32 v38, v38, v39
	v_cvt_pk_f16_f32 v39, v40, v41
	global_store_dwordx2 v193, v[38:39], s[22:23] offset:64
	v_mul_f32_e32 v34, s7, v34
	v_mul_f32_e32 v35, s7, v35
	v_mul_f32_e32 v36, s7, v36
	v_mul_f32_e32 v37, s7, v37
	v_cvt_pk_f16_f32 v34, v34, v35
	v_cvt_pk_f16_f32 v35, v36, v37
	global_store_dwordx2 v193, v[34:35], s[22:23] offset:96
	v_add_u32_e32 v193, 0x2000, v193
	v_mul_f32_e32 v30, s7, v30
	v_mul_f32_e32 v31, s7, v31
	v_mul_f32_e32 v32, s7, v32
	v_mul_f32_e32 v33, s7, v33
	v_cvt_pk_f16_f32 v30, v30, v31
	v_cvt_pk_f16_f32 v31, v32, v33
	global_store_dwordx2 v193, v[30:31], s[22:23] offset:0
	v_mul_f32_e32 v26, s7, v26
	v_mul_f32_e32 v27, s7, v27
	v_mul_f32_e32 v28, s7, v28
	v_mul_f32_e32 v29, s7, v29
	v_cvt_pk_f16_f32 v26, v26, v27
	v_cvt_pk_f16_f32 v27, v28, v29
	global_store_dwordx2 v193, v[26:27], s[22:23] offset:32
	v_mul_f32_e32 v22, s7, v22
	v_mul_f32_e32 v23, s7, v23
	v_mul_f32_e32 v24, s7, v24
	v_mul_f32_e32 v25, s7, v25
	v_cvt_pk_f16_f32 v22, v22, v23
	v_cvt_pk_f16_f32 v23, v24, v25
	global_store_dwordx2 v193, v[22:23], s[22:23] offset:64
	v_mul_f32_e32 v18, s7, v18
	v_mul_f32_e32 v19, s7, v19
	v_mul_f32_e32 v20, s7, v20
	v_mul_f32_e32 v21, s7, v21
	v_cvt_pk_f16_f32 v18, v18, v19
	v_cvt_pk_f16_f32 v19, v20, v21
	global_store_dwordx2 v193, v[18:19], s[22:23] offset:96
	v_add_u32_e32 v193, 0x2000, v193
	v_mul_f32_e32 v14, s7, v14
	v_mul_f32_e32 v15, s7, v15
	v_mul_f32_e32 v16, s7, v16
	v_mul_f32_e32 v17, s7, v17
	v_cvt_pk_f16_f32 v14, v14, v15
	v_cvt_pk_f16_f32 v15, v16, v17
	global_store_dwordx2 v193, v[14:15], s[22:23] offset:0
	v_mul_f32_e32 v10, s7, v10
	v_mul_f32_e32 v11, s7, v11
	v_mul_f32_e32 v12, s7, v12
	v_mul_f32_e32 v13, s7, v13
	v_cvt_pk_f16_f32 v10, v10, v11
	v_cvt_pk_f16_f32 v11, v12, v13
	global_store_dwordx2 v193, v[10:11], s[22:23] offset:32
	v_mul_f32_e32 v6, s7, v6
	v_mul_f32_e32 v7, s7, v7
	v_mul_f32_e32 v8, s7, v8
	v_mul_f32_e32 v9, s7, v9
	v_cvt_pk_f16_f32 v6, v6, v7
	v_cvt_pk_f16_f32 v7, v8, v9
	global_store_dwordx2 v193, v[6:7], s[22:23] offset:64
	v_mul_f32_e32 v2, s7, v2
	v_mul_f32_e32 v3, s7, v3
	v_mul_f32_e32 v4, s7, v4
	v_mul_f32_e32 v5, s7, v5
	v_cvt_pk_f16_f32 v2, v2, v3
	v_cvt_pk_f16_f32 v3, v4, v5
	global_store_dwordx2 v193, v[2:3], s[22:23] offset:96
	s_waitcnt vmcnt(32)
.Lp1_join:
	s_cmp_lg_u32 s21, 0
	s_cbranch_scc1 .Lp1_cont
	s_cmp_le_i32 s9, s58
	s_cbranch_scc1 .Lp1t_none
	s_waitcnt vmcnt(0)
	v_readlane_b32 s2, v255, 22
	s_nop 0
	s_and_b32 s4, s2, 7
	s_lshr_b32 s2, s2, 3
	s_and_b32 s6, s2, 15
	s_or_b32 s6, s6, 0x80
	s_lshr_b32 s28, s2, 4
	s_add_i32 s28, s28, 8
	s_lshl_b32 s2, s6, 19
	s_lshl_b32 s3, s4, 16
	s_add_i32 s2, s2, s3
	s_add_u32 s12, s64, s2
	s_addc_u32 s13, s65, 0
	s_lshl_b32 s2, s28, 19
	s_add_u32 s14, s34, s2
	s_addc_u32 s15, s35, 0
	s_lshl_b32 s7, s4, 5
	v_and_b32_e32 v194, 15, v222
	v_bfe_u32 v195, v222, 4, 2
	v_bfe_u32 v196, v194, 1, 3
	v_xor_b32_e32 v195, v195, v196
	v_lshlrev_b32_e32 v195, 4, v195
	v_lshrrev_b32_e32 v196, 8, v222
	v_lshl_or_b32 v196, v196, 4, v194
	v_lshl_or_b32 v200, v196, 7, v195
	v_xor_b32_e32 v201, 64, v200
	v_bfe_u32 v196, v222, 6, 2
	v_lshl_or_b32 v196, v196, 6, v194
	v_lshl_or_b32 v202, v196, 7, v195
	v_xor_b32_e32 v203, 64, v202
	v_add_u32_e32 v204, 0x10000, v200
	v_add_u32_e32 v205, 0x10000, v201
	v_add_u32_e32 v206, 0x10000, v202
	v_add_u32_e32 v207, 0x10000, v203
	v_readfirstlane_b32 s18, v222
	s_nop 3
	s_lshr_b32 s19, s18, 8
	s_lshr_b32 s18, s18, 6
	s_lshl_b32 s18, s18, 10
	s_barrier
	s_mov_b32 m0, s18
	s_nop 0
	global_load_lds_dwordx4 v1, s[12:13]
	s_add_i32 m0, s18, 0x2000
	s_nop 0
	global_load_lds_dwordx4 v1, s[12:13]
	s_add_i32 m0, s18, 0x4000
	s_nop 0
	global_load_lds_dwordx4 v1, s[12:13]
	s_add_i32 m0, s18, 0x6000
	s_nop 0
	global_load_lds_dwordx4 v1, s[12:13]
	s_add_i32 m0, s18, 0x8000
	s_nop 0
	global_load_lds_dwordx4 v1, s[14:15]
	s_add_i32 m0, s18, 0xa000
	s_add_u32 s16, s14, 0x20000
	s_addc_u32 s17, s15, 0
	global_load_lds_dwordx4 v1, s[16:17]
	s_add_i32 m0, s18, 0xc000
	s_add_u32 s16, s14, 0x40000
	s_addc_u32 s17, s15, 0
	global_load_lds_dwordx4 v1, s[16:17]
	s_add_i32 m0, s18, 0xe000
	s_add_u32 s16, s14, 0x60000
	s_addc_u32 s17, s15, 0
	global_load_lds_dwordx4 v1, s[16:17]
	s_add_i32 m0, s18, 0x10000
	s_add_u32 s16, s12, 0x80
	s_addc_u32 s17, s13, 0
	global_load_lds_dwordx4 v1, s[16:17]
	s_add_i32 m0, s18, 0x18000
	s_add_u32 s16, s14, 0x80
	s_addc_u32 s17, s15, 0
	global_load_lds_dwordx4 v1, s[16:17]
	s_waitcnt vmcnt(2)
	s_barrier
	s_cmp_eq_u32 s19, 0
	s_cbranch_scc1 .Lp1t_skew0
	s_barrier
.Lp1t_skew0:
	ds_read_b128 v[130:133], v200 offset:0
	ds_read_b128 v[162:165], v202 offset:32768
	ds_read_b128 v[166:169], v202 offset:34816
	ds_read_b128 v[170:173], v202 offset:36864
	ds_read_b128 v[174:177], v202 offset:38912
	s_add_i32 m0, s18, 0x14000
	s_add_u32 s16, s12, 0x80
	s_addc_u32 s17, s13, 0
	global_load_lds_dwordx4 v1, s[16:17]
	s_add_i32 m0, s18, 0x1a000
	s_add_u32 s16, s14, 0x20080
	s_addc_u32 s17, s15, 0
	global_load_lds_dwordx4 v1, s[16:17]
	s_waitcnt lgkmcnt(0)
	s_barrier
	v_mfma_f32_16x16x32_f16 v[126:129], v[162:165], v[130:133], 0
	v_mfma_f32_16x16x32_f16 v[122:125], v[166:169], v[130:133], 0
	v_mfma_f32_16x16x32_f16 v[118:121], v[170:173], v[130:133], 0
	v_mfma_f32_16x16x32_f16 v[114:117], v[174:177], v[130:133], 0
	s_barrier
	s_add_i32 m0, s18, 0x1c000
	s_add_u32 s16, s14, 0x40080
	s_addc_u32 s17, s15, 0
	global_load_lds_dwordx4 v1, s[16:17]
	s_add_i32 m0, s18, 0x1e000
	s_add_u32 s16, s14, 0x60080
	s_addc_u32 s17, s15, 0
	global_load_lds_dwordx4 v1, s[16:17]
	s_waitcnt lgkmcnt(0)
	s_barrier
	s_barrier
	ds_read_b128 v[130:133], v201 offset:0
	ds_read_b128 v[162:165], v203 offset:32768
	ds_read_b128 v[166:169], v203 offset:34816
	ds_read_b128 v[170:173], v203 offset:36864
	ds_read_b128 v[174:177], v203 offset:38912
	s_add_i32 m0, s18, 0x12000
	s_add_u32 s16, s12, 0x80
	s_addc_u32 s17, s13, 0
	global_load_lds_dwordx4 v1, s[16:17]
	s_add_i32 m0, s18, 0x16000
	s_add_u32 s16, s12, 0x80
	s_addc_u32 s17, s13, 0
	global_load_lds_dwordx4 v1, s[16:17]
	s_waitcnt lgkmcnt(0)
	s_barrier
	v_mfma_f32_16x16x32_f16 v[126:129], v[162:165], v[130:133], v[126:129]
	v_mfma_f32_16x16x32_f16 v[122:125], v[166:169], v[130:133], v[122:125]
	v_mfma_f32_16x16x32_f16 v[118:121], v[170:173], v[130:133], v[118:121]
	v_mfma_f32_16x16x32_f16 v[114:117], v[174:177], v[130:133], v[114:117]
	s_barrier
	s_mov_b32 m0, s18
	s_add_u32 s16, s12, 0x100
	s_addc_u32 s17, s13, 0
	global_load_lds_dwordx4 v1, s[16:17]
	s_add_i32 m0, s18, 0x8000
	s_add_u32 s16, s14, 0x100
	s_addc_u32 s17, s15, 0
	global_load_lds_dwordx4 v1, s[16:17]
	s_waitcnt vmcnt(4) lgkmcnt(0)
	s_barrier
	s_barrier
	s_add_u32 s12, s12, 0x80
	s_addc_u32 s13, s13, 0
	s_add_u32 s14, s14, 0x80
	s_addc_u32 s15, s15, 0
	ds_read_b128 v[130:133], v204 offset:0
	ds_read_b128 v[162:165], v206 offset:32768
	ds_read_b128 v[166:169], v206 offset:34816
	ds_read_b128 v[170:173], v206 offset:36864
	ds_read_b128 v[174:177], v206 offset:38912
	s_add_i32 m0, s18, 0x4000
	s_add_u32 s16, s12, 0x80
	s_addc_u32 s17, s13, 0
	global_load_lds_dwordx4 v1, s[16:17]
	s_add_i32 m0, s18, 0xa000
	s_add_u32 s16, s14, 0x20080
	s_addc_u32 s17, s15, 0
	global_load_lds_dwordx4 v1, s[16:17]
	s_waitcnt vmcnt(4) lgkmcnt(0)
	s_barrier
	v_mfma_f32_16x16x32_f16 v[126:129], v[162:165], v[130:133], v[126:129]
	v_mfma_f32_16x16x32_f16 v[122:125], v[166:169], v[130:133], v[122:125]
	v_mfma_f32_16x16x32_f16 v[118:121], v[170:173], v[130:133], v[118:121]
	v_mfma_f32_16x16x32_f16 v[114:117], v[174:177], v[130:133], v[114:117]
	s_barrier
	s_add_i32 m0, s18, 0xc000
	s_add_u32 s16, s14, 0x40080
	s_addc_u32 s17, s15, 0
	global_load_lds_dwordx4 v1, s[16:17]
	s_add_i32 m0, s18, 0xe000
	s_add_u32 s16, s14, 0x60080
	s_addc_u32 s17, s15, 0
	global_load_lds_dwordx4 v1, s[16:17]
	s_waitcnt lgkmcnt(0)
	s_barrier
	s_barrier
	ds_read_b128 v[130:133], v205 offset:0
	ds_read_b128 v[162:165], v207 offset:32768
	ds_read_b128 v[166:169], v207 offset:34816
	ds_read_b128 v[170:173], v207 offset:36864
	ds_read_b128 v[174:177], v207 offset:38912
	s_add_i32 m0, s18, 0x2000
	s_add_u32 s16, s12, 0x80
	s_addc_u32 s17, s13, 0
	global_load_lds_dwordx4 v1, s[16:17]
	s_add_i32 m0, s18, 0x6000
	s_add_u32 s16, s12, 0x80
	s_addc_u32 s17, s13, 0
	global_load_lds_dwordx4 v1, s[16:17]
	s_waitcnt lgkmcnt(0)
	s_barrier
	v_mfma_f32_16x16x32_f16 v[126:129], v[162:165], v[130:133], v[126:129]
	v_mfma_f32_16x16x32_f16 v[122:125], v[166:169], v[130:133], v[122:125]
	v_mfma_f32_16x16x32_f16 v[118:121], v[170:173], v[130:133], v[118:121]
	v_mfma_f32_16x16x32_f16 v[114:117], v[174:177], v[130:133], v[114:117]
	s_barrier
	s_add_i32 m0, s18, 0x10000
	s_add_u32 s16, s12, 0x100
	s_addc_u32 s17, s13, 0
	global_load_lds_dwordx4 v1, s[16:17]
	s_add_i32 m0, s18, 0x18000
	s_add_u32 s16, s14, 0x100
	s_addc_u32 s17, s15, 0
	global_load_lds_dwordx4 v1, s[16:17]
	s_waitcnt vmcnt(4) lgkmcnt(0)
	s_barrier
	s_barrier
	s_add_u32 s12, s12, 0x80
	s_addc_u32 s13, s13, 0
	s_add_u32 s14, s14, 0x80
	s_addc_u32 s15, s15, 0
	s_movk_i32 s20, 6
.Lp1t_loop:
	ds_read_b128 v[130:133], v200 offset:0
	ds_read_b128 v[162:165], v202 offset:32768
	ds_read_b128 v[166:169], v202 offset:34816
	ds_read_b128 v[170:173], v202 offset:36864
	ds_read_b128 v[174:177], v202 offset:38912
	s_add_i32 m0, s18, 0x14000
	s_add_u32 s16, s12, 0x80
	s_addc_u32 s17, s13, 0
	global_load_lds_dwordx4 v1, s[16:17]
	s_add_i32 m0, s18, 0x1a000
	s_add_u32 s16, s14, 0x20080
	s_addc_u32 s17, s15, 0
	global_load_lds_dwordx4 v1, s[16:17]
	s_waitcnt vmcnt(4) lgkmcnt(0)
	s_barrier
	v_mfma_f32_16x16x32_f16 v[126:129], v[162:165], v[130:133], v[126:129]
	v_mfma_f32_16x16x32_f16 v[122:125], v[166:169], v[130:133], v[122:125]
	v_mfma_f32_16x16x32_f16 v[118:121], v[170:173], v[130:133], v[118:121]
	v_mfma_f32_16x16x32_f16 v[114:117], v[174:177], v[130:133], v[114:117]
	s_barrier
	s_add_i32 m0, s18, 0x1c000
	s_add_u32 s16, s14, 0x40080
	s_addc_u32 s17, s15, 0
	global_load_lds_dwordx4 v1, s[16:17]
	s_add_i32 m0, s18, 0x1e000
	s_add_u32 s16, s14, 0x60080
	s_addc_u32 s17, s15, 0
	global_load_lds_dwordx4 v1, s[16:17]
	s_waitcnt lgkmcnt(0)
	s_barrier
	s_barrier
	ds_read_b128 v[130:133], v201 offset:0
	ds_read_b128 v[162:165], v203 offset:32768
	ds_read_b128 v[166:169], v203 offset:34816
	ds_read_b128 v[170:173], v203 offset:36864
	ds_read_b128 v[174:177], v203 offset:38912
	s_add_i32 m0, s18, 0x12000
	s_add_u32 s16, s12, 0x80
	s_addc_u32 s17, s13, 0
	global_load_lds_dwordx4 v1, s[16:17]
	s_add_i32 m0, s18, 0x16000
	s_add_u32 s16, s12, 0x80
	s_addc_u32 s17, s13, 0
	global_load_lds_dwordx4 v1, s[16:17]
	s_waitcnt lgkmcnt(0)
	s_barrier
	v_mfma_f32_16x16x32_f16 v[126:129], v[162:165], v[130:133], v[126:129]
	v_mfma_f32_16x16x32_f16 v[122:125], v[166:169], v[130:133], v[122:125]
	v_mfma_f32_16x16x32_f16 v[118:121], v[170:173], v[130:133], v[118:121]
	v_mfma_f32_16x16x32_f16 v[114:117], v[174:177], v[130:133], v[114:117]
	s_barrier
	s_mov_b32 m0, s18
	s_add_u32 s16, s12, 0x100
	s_addc_u32 s17, s13, 0
	global_load_lds_dwordx4 v1, s[16:17]
	s_add_i32 m0, s18, 0x8000
	s_add_u32 s16, s14, 0x100
	s_addc_u32 s17, s15, 0
	global_load_lds_dwordx4 v1, s[16:17]
	s_waitcnt vmcnt(4) lgkmcnt(0)
	s_barrier
	s_barrier
	s_add_u32 s12, s12, 0x80
	s_addc_u32 s13, s13, 0
	s_add_u32 s14, s14, 0x80
	s_addc_u32 s15, s15, 0
	ds_read_b128 v[130:133], v204 offset:0
	ds_read_b128 v[162:165], v206 offset:32768
	ds_read_b128 v[166:169], v206 offset:34816
	ds_read_b128 v[170:173], v206 offset:36864
	ds_read_b128 v[174:177], v206 offset:38912
	s_add_i32 m0, s18, 0x4000
	s_add_u32 s16, s12, 0x80
	s_addc_u32 s17, s13, 0
	global_load_lds_dwordx4 v1, s[16:17]
	s_add_i32 m0, s18, 0xa000
	s_add_u32 s16, s14, 0x20080
	s_addc_u32 s17, s15, 0
	global_load_lds_dwordx4 v1, s[16:17]
	s_waitcnt vmcnt(4) lgkmcnt(0)
	s_barrier
	v_mfma_f32_16x16x32_f16 v[126:129], v[162:165], v[130:133], v[126:129]
	v_mfma_f32_16x16x32_f16 v[122:125], v[166:169], v[130:133], v[122:125]
	v_mfma_f32_16x16x32_f16 v[118:121], v[170:173], v[130:133], v[118:121]
	v_mfma_f32_16x16x32_f16 v[114:117], v[174:177], v[130:133], v[114:117]
	s_barrier
	s_add_i32 m0, s18, 0xc000
	s_add_u32 s16, s14, 0x40080
	s_addc_u32 s17, s15, 0
	global_load_lds_dwordx4 v1, s[16:17]
	s_add_i32 m0, s18, 0xe000
	s_add_u32 s16, s14, 0x60080
	s_addc_u32 s17, s15, 0
	global_load_lds_dwordx4 v1, s[16:17]
	s_waitcnt lgkmcnt(0)
	s_barrier
	s_barrier
	ds_read_b128 v[130:133], v205 offset:0
	ds_read_b128 v[162:165], v207 offset:32768
	ds_read_b128 v[166:169], v207 offset:34816
	ds_read_b128 v[170:173], v207 offset:36864
	ds_read_b128 v[174:177], v207 offset:38912
	s_add_i32 m0, s18, 0x2000
	s_add_u32 s16, s12, 0x80
	s_addc_u32 s17, s13, 0
	global_load_lds_dwordx4 v1, s[16:17]
	s_add_i32 m0, s18, 0x6000
	s_add_u32 s16, s12, 0x80
	s_addc_u32 s17, s13, 0
	global_load_lds_dwordx4 v1, s[16:17]
	s_waitcnt lgkmcnt(0)
	s_barrier
	v_mfma_f32_16x16x32_f16 v[126:129], v[162:165], v[130:133], v[126:129]
	v_mfma_f32_16x16x32_f16 v[122:125], v[166:169], v[130:133], v[122:125]
	v_mfma_f32_16x16x32_f16 v[118:121], v[170:173], v[130:133], v[118:121]
	v_mfma_f32_16x16x32_f16 v[114:117], v[174:177], v[130:133], v[114:117]
	s_barrier
	s_add_i32 m0, s18, 0x10000
	s_add_u32 s16, s12, 0x100
	s_addc_u32 s17, s13, 0
	global_load_lds_dwordx4 v1, s[16:17]
	s_add_i32 m0, s18, 0x18000
	s_add_u32 s16, s14, 0x100
	s_addc_u32 s17, s15, 0
	global_load_lds_dwordx4 v1, s[16:17]
	s_waitcnt vmcnt(4) lgkmcnt(0)
	s_barrier
	s_barrier
	s_add_u32 s12, s12, 0x80
	s_addc_u32 s13, s13, 0
	s_add_u32 s14, s14, 0x80
	s_addc_u32 s15, s15, 0
	s_add_i32 s20, s20, -1
	s_cmp_lg_u32 s20, 0
	s_cbranch_scc1 .Lp1t_loop
	ds_read_b128 v[130:133], v200 offset:0
	ds_read_b128 v[162:165], v202 offset:32768
	ds_read_b128 v[166:169], v202 offset:34816
	ds_read_b128 v[170:173], v202 offset:36864
	ds_read_b128 v[174:177], v202 offset:38912
	s_add_i32 m0, s18, 0x14000
	s_add_u32 s16, s12, 0x80
	s_addc_u32 s17, s13, 0
	global_load_lds_dwordx4 v1, s[16:17]
	s_add_i32 m0, s18, 0x1a000
	s_add_u32 s16, s14, 0x20080
	s_addc_u32 s17, s15, 0
	global_load_lds_dwordx4 v1, s[16:17]
	s_waitcnt vmcnt(4) lgkmcnt(0)
	s_barrier
	v_mfma_f32_16x16x32_f16 v[126:129], v[162:165], v[130:133], v[126:129]
	v_mfma_f32_16x16x32_f16 v[122:125], v[166:169], v[130:133], v[122:125]
	v_mfma_f32_16x16x32_f16 v[118:121], v[170:173], v[130:133], v[118:121]
	v_mfma_f32_16x16x32_f16 v[114:117], v[174:177], v[130:133], v[114:117]
	s_barrier
	s_add_i32 m0, s18, 0x1c000
	s_add_u32 s16, s14, 0x40080
	s_addc_u32 s17, s15, 0
	global_load_lds_dwordx4 v1, s[16:17]
	s_add_i32 m0, s18, 0x1e000
	s_add_u32 s16, s14, 0x60080
	s_addc_u32 s17, s15, 0
	global_load_lds_dwordx4 v1, s[16:17]
	s_waitcnt lgkmcnt(0)
	s_barrier
	s_barrier
	ds_read_b128 v[130:133], v201 offset:0
	ds_read_b128 v[162:165], v203 offset:32768
	ds_read_b128 v[166:169], v203 offset:34816
	ds_read_b128 v[170:173], v203 offset:36864
	ds_read_b128 v[174:177], v203 offset:38912
	s_add_i32 m0, s18, 0x12000
	s_add_u32 s16, s12, 0x80
	s_addc_u32 s17, s13, 0
	global_load_lds_dwordx4 v1, s[16:17]
	s_add_i32 m0, s18, 0x16000
	s_add_u32 s16, s12, 0x80
	s_addc_u32 s17, s13, 0
	global_load_lds_dwordx4 v1, s[16:17]
	s_waitcnt lgkmcnt(0)
	s_barrier
	v_mfma_f32_16x16x32_f16 v[126:129], v[162:165], v[130:133], v[126:129]
	v_mfma_f32_16x16x32_f16 v[122:125], v[166:169], v[130:133], v[122:125]
	v_mfma_f32_16x16x32_f16 v[118:121], v[170:173], v[130:133], v[118:121]
	v_mfma_f32_16x16x32_f16 v[114:117], v[174:177], v[130:133], v[114:117]
	s_barrier
	s_waitcnt vmcnt(2) lgkmcnt(0)
	s_barrier
	s_barrier
	s_add_u32 s12, s12, 0x80
	s_addc_u32 s13, s13, 0
	s_add_u32 s14, s14, 0x80
	s_addc_u32 s15, s15, 0
	ds_read_b128 v[130:133], v204 offset:0
	ds_read_b128 v[162:165], v206 offset:32768
	ds_read_b128 v[166:169], v206 offset:34816
	ds_read_b128 v[170:173], v206 offset:36864
	ds_read_b128 v[174:177], v206 offset:38912
	s_waitcnt vmcnt(0) lgkmcnt(0)
	s_barrier
	v_mfma_f32_16x16x32_f16 v[126:129], v[162:165], v[130:133], v[126:129]
	v_mfma_f32_16x16x32_f16 v[122:125], v[166:169], v[130:133], v[122:125]
	v_mfma_f32_16x16x32_f16 v[118:121], v[170:173], v[130:133], v[118:121]
	v_mfma_f32_16x16x32_f16 v[114:117], v[174:177], v[130:133], v[114:117]
	s_barrier
	s_waitcnt lgkmcnt(0)
	s_barrier
	s_barrier
	ds_read_b128 v[130:133], v205 offset:0
	ds_read_b128 v[162:165], v207 offset:32768
	ds_read_b128 v[166:169], v207 offset:34816
	ds_read_b128 v[170:173], v207 offset:36864
	ds_read_b128 v[174:177], v207 offset:38912
	s_waitcnt lgkmcnt(0)
	s_barrier
	v_mfma_f32_16x16x32_f16 v[126:129], v[162:165], v[130:133], v[126:129]
	v_mfma_f32_16x16x32_f16 v[122:125], v[166:169], v[130:133], v[122:125]
	v_mfma_f32_16x16x32_f16 v[118:121], v[170:173], v[130:133], v[118:121]
	v_mfma_f32_16x16x32_f16 v[114:117], v[174:177], v[130:133], v[114:117]
	s_barrier
	s_waitcnt lgkmcnt(0)
	s_barrier
	s_barrier
	s_cmp_eq_u32 s19, 1
	s_cbranch_scc1 .Lp1t_skew1
	s_barrier
.Lp1t_skew1:
	s_nop 7
	s_nop 1
	v_and_b32_e32 v194, 15, v222
	v_bfe_u32 v195, v222, 4, 2
	v_bfe_u32 v196, v222, 6, 2
	v_lshrrev_b32_e32 v197, 8, v222
	v_lshl_or_b32 v198, v197, 4, v194
	v_add_u32_e32 v198, s7, v198
	v_lshlrev_b32_e32 v199, 2, v195
	v_lshl_or_b32 v199, v196, 6, v199
	v_readlane_b32 s22, v254, 14
	v_readlane_b32 s23, v254, 15
	s_add_i32 s2, s6, 0xffffff80
	s_cmp_eq_u32 s28, 9
	s_cbranch_scc1 .Lp1t_v
	s_mul_i32 s2, s2, 0x900
	s_lshl_b32 s2, s2, 9
	s_add_u32 s22, s22, 0x128ae500
	s_addc_u32 s23, s23, 0
	s_add_u32 s22, s22, s2
	s_addc_u32 s23, s23, 0
	v_lshlrev_b32_e32 v193, 9, v198
	v_lshl_add_u32 v193, v199, 1, v193
	v_cvt_pk_f16_f32 v126, v126, v127
	v_cvt_pk_f16_f32 v127, v128, v129
	global_store_dwordx2 v193, v[126:127], s[22:23] offset:0
	v_cvt_pk_f16_f32 v122, v122, v123
	v_cvt_pk_f16_f32 v123, v124, v125
	global_store_dwordx2 v193, v[122:123], s[22:23] offset:32
	v_cvt_pk_f16_f32 v118, v118, v119
	v_cvt_pk_f16_f32 v119, v120, v121
	global_store_dwordx2 v193, v[118:119], s[22:23] offset:64
	v_cvt_pk_f16_f32 v114, v114, v115
	v_cvt_pk_f16_f32 v115, v116, v117
	global_store_dwordx2 v193, v[114:115], s[22:23] offset:96
	s_branch .Lp1t_done
.Lp1t_v:
	s_mul_i32 s2, s2, 0x120000
	s_add_u32 s22, s22, 0x13aae500
	s_addc_u32 s23, s23, 0
	s_add_u32 s22, s22, s2
	s_addc_u32 s23, s23, 0
	v_mul_u32_u24_e32 v193, 0x1200, v199
	v_lshl_add_u32 v193, v198, 1, v193
	v_cvt_pk_f16_f32 v126, v126, v127
	v_cvt_pk_f16_f32 v127, v128, v129
	v_add_u32_e32 v192, 0x0, v193
	global_store_short v192, v126, s[22:23]
	v_add_u32_e32 v192, 0x1200, v193
	global_store_short_d16_hi v192, v126, s[22:23]
	v_add_u32_e32 v192, 0x2400, v193
	global_store_short v192, v127, s[22:23]
	v_add_u32_e32 v192, 0x3600, v193
	global_store_short_d16_hi v192, v127, s[22:23]
	v_cvt_pk_f16_f32 v122, v122, v123
	v_cvt_pk_f16_f32 v123, v124, v125
	v_add_u32_e32 v192, 0x12000, v193
	global_store_short v192, v122, s[22:23]
	v_add_u32_e32 v192, 0x13200, v193
	global_store_short_d16_hi v192, v122, s[22:23]
	v_add_u32_e32 v192, 0x14400, v193
	global_store_short v192, v123, s[22:23]
	v_add_u32_e32 v192, 0x15600, v193
	global_store_short_d16_hi v192, v123, s[22:23]
	v_cvt_pk_f16_f32 v118, v118, v119
	v_cvt_pk_f16_f32 v119, v120, v121
	v_add_u32_e32 v192, 0x24000, v193
	global_store_short v192, v118, s[22:23]
	v_add_u32_e32 v192, 0x25200, v193
	global_store_short_d16_hi v192, v118, s[22:23]
	v_add_u32_e32 v192, 0x26400, v193
	global_store_short v192, v119, s[22:23]
	v_add_u32_e32 v192, 0x27600, v193
	global_store_short_d16_hi v192, v119, s[22:23]
	v_cvt_pk_f16_f32 v114, v114, v115
	v_cvt_pk_f16_f32 v115, v116, v117
	v_add_u32_e32 v192, 0x36000, v193
	global_store_short v192, v114, s[22:23]
	v_add_u32_e32 v192, 0x37200, v193
	global_store_short_d16_hi v192, v114, s[22:23]
	v_add_u32_e32 v192, 0x38400, v193
	global_store_short v192, v115, s[22:23]
	v_add_u32_e32 v192, 0x39600, v193
	global_store_short_d16_hi v192, v115, s[22:23]
.Lp1t_done:
	s_waitcnt vmcnt(0)
.Lp1t_none:
	s_branch .LBB0_689
.LBB0_689:
	s_movk_i32 s39, 0x1200
	s_mov_b32 s40, 0x5040100
	s_movk_i32 s41, 0x301
